# LayerNorm no longer rewrites x: it leaves (mean, rstd) per row in the h-row padding and the residual GEMM epilogue normalises x on the fly with the same three f32 operations; hand-written LayerNorm fo
# speedup vs baseline: 1.0172x; 1.0109x over previous
.LBB0_38:
	s_add_i32 s34, s60, -2
	s_mul_hi_i32 s35, s34, 0x2aaaaaab
	s_lshr_b32 s36, s35, 31
	s_ashr_i32 s35, s35, 1
	s_add_i32 s6, s35, s36
	s_mov_b32 s4, s6
	v_writelane_b32 v235, s4, 44
	s_mul_i32 s35, s6, 12
	s_sub_i32 s6, s34, s35
	v_writelane_b32 v235, s5, 45
	v_writelane_b32 v235, s60, 46
	s_lshl_b32 s34, s60, 6
	s_ashr_i32 s35, s34, 31
	s_lshl_b64 s[34:35], s[34:35], 2
	v_readlane_b32 s4, v236, 19
	s_add_u32 s8, s4, s34
	v_readlane_b32 s4, v236, 20
	v_writelane_b32 v235, s61, 47
	s_addc_u32 s9, s4, s35
	v_writelane_b32 v235, s8, 36
	s_mov_b64 s[34:35], -1
	s_mov_b64 s[40:41], 0
	v_writelane_b32 v235, s9, 37
	s_nop 0
	v_readlane_b32 s4, v235, 34
	v_readlane_b32 s5, v235, 35
	s_add_u32 s60, s4, 0xfae6000
	s_addc_u32 s61, s5, 0
	v_writelane_b32 v235, s6, 48
	s_mov_b64 s[4:5], 0
	v_writelane_b32 v235, s4, 49
	s_cmp_lt_i32 s6, 6
	s_nop 0
	v_writelane_b32 v235, s5, 50
	s_mov_b64 s[4:5], 0
	v_writelane_b32 v235, s4, 51
	s_nop 1
	v_writelane_b32 v235, s5, 52
	s_cbranch_scc1 .LBB0_134
	v_readlane_b32 s4, v235, 48
	s_cmp_gt_i32 s4, 8
	s_cbranch_scc0 .LBB0_85
	s_mov_b64 s[6:7], -1
	v_writelane_b32 v235, s6, 49
	s_mov_b64 s[44:45], 0
	s_cmp_gt_i32 s4, 9
	v_writelane_b32 v235, s7, 50
	s_mov_b64 s[6:7], 0
	s_cbranch_scc0 .LBB0_89
	v_readlane_b32 s2, v235, 48
	s_cmp_gt_i32 s2, 10
	s_mov_b64 s[6:7], -1
	s_cbranch_scc0 .LBB0_88
	v_readlane_b32 s2, v235, 48
	s_cmp_eq_u32 s2, 11
	s_cbranch_scc0 .LBB0_87
	v_mov_b32_e32 v33, v170
	v_mov_b32_e32 v0, v170
	v_readlane_b32 s4, v235, 17
	s_waitcnt lgkmcnt(0)
	v_ashrrev_i32_e32 v34, 6, v0
	s_mov_b64 s[88:89], s[74:75]
	v_add_u32_e32 v32, s4, v34
	s_movk_i32 s4, 0x3000
	v_cmp_gt_i32_e32 vcc, s4, v32
	s_and_saveexec_b64 s[46:47], vcc
	s_cbranch_execz .LBB0_86
	v_readlane_b32 s4, v235, 33
	s_cmp_lg_u32 s4, 0x200
	s_cbranch_scc1 .Llna_orig
	v_and_b32_e32 v232, 63, v170
	v_lshlrev_b32_e32 v233, 3, v232
	v_lshlrev_b32_e32 v232, 4, v232
	v_lshrrev_b32_e32 v231, 6, v170
	s_nop 0
	v_readfirstlane_b32 s6, v231
	v_readlane_b32 s7, v237, 0
	s_lshl_b32 s7, s7, 2
	s_add_u32 s6, s6, s7
	v_readlane_b32 s8, v235, 34
	v_readlane_b32 s9, v235, 35
	v_readlane_b32 s7, v235, 44
	s_mul_i32 s10, s7, 3
	s_add_u32 s10, s10, 2
	s_lshl_b32 s10, s10, 12
	v_readlane_b32 s4, v237, 25
	v_readlane_b32 s5, v237, 26
	s_add_u32 s4, s4, s10
	s_addc_u32 s5, s5, 0
	global_load_dwordx4 v[136:139], v232, s[4:5]
	global_load_dwordx4 v[140:143], v232, s[4:5] offset:1024
	global_load_dwordx4 v[144:147], v232, s[4:5] offset:2048
	global_load_dwordx4 v[148:151], v232, s[4:5] offset:3072
	v_readlane_b32 s4, v237, 27
	v_readlane_b32 s5, v237, 28
	s_add_u32 s4, s4, s10
	s_addc_u32 s5, s5, 0
	global_load_dwordx4 v[152:155], v232, s[4:5]
	global_load_dwordx4 v[156:159], v232, s[4:5] offset:1024
	global_load_dwordx4 v[160:163], v232, s[4:5] offset:2048
	global_load_dwordx4 v[164:167], v232, s[4:5] offset:3072
	s_cmp_lt_u32 s7, 3
	s_addc_u32 s11, s7, 0
	s_mul_i32 s11, s11, 0x1b000
	s_add_u32 s11, s11, 0xb0f8000
	s_add_u32 s10, s8, s11
	s_addc_u32 s11, s9, 0
	s_cmp_eq_u32 s7, 3
	s_cselect_b32 s57, 1, 0
	s_add_u32 s4, s10, 0x0
	s_addc_u32 s5, s11, 0
	global_load_dwordx4 v[64:67], v232, s[4:5]
	global_load_dwordx4 v[68:71], v232, s[4:5] offset:1024
	global_load_dwordx4 v[72:75], v232, s[4:5] offset:2048
	global_load_dwordx4 v[76:79], v232, s[4:5] offset:3072
	s_add_u32 s4, s4, 0x1000
	s_addc_u32 s5, s5, 0
	global_load_dwordx4 v[80:83], v232, s[4:5]
	global_load_dwordx4 v[84:87], v232, s[4:5] offset:1024
	global_load_dwordx4 v[88:91], v232, s[4:5] offset:2048
	global_load_dwordx4 v[92:95], v232, s[4:5] offset:3072
	s_lshl_b32 s4, s6, 12
	s_add_u32 s4, s4, 0xb166000
	s_add_u32 s4, s4, s8
	s_addc_u32 s5, s9, 0
	global_load_dwordx4 v[0:3], v232, s[4:5]
	global_load_dwordx4 v[4:7], v232, s[4:5] offset:1024
	global_load_dwordx4 v[8:11], v232, s[4:5] offset:2048
	global_load_dwordx4 v[12:15], v232, s[4:5] offset:3072
	s_lshl_b32 s4, s6, 12
	s_add_u32 s4, s4, 0xb966000
	s_add_u32 s4, s4, s8
	s_addc_u32 s5, s9, 0
	global_load_dwordx4 v[16:19], v232, s[4:5]
	global_load_dwordx4 v[20:23], v232, s[4:5] offset:1024
	global_load_dwordx4 v[24:27], v232, s[4:5] offset:2048
	global_load_dwordx4 v[28:31], v232, s[4:5] offset:3072
	s_lshl_b32 s4, s6, 12
	s_add_u32 s4, s4, 0xc166000
	s_add_u32 s4, s4, s8
	s_addc_u32 s5, s9, 0
	global_load_dwordx4 v[32:35], v232, s[4:5]
	global_load_dwordx4 v[36:39], v232, s[4:5] offset:1024
	global_load_dwordx4 v[40:43], v232, s[4:5] offset:2048
	global_load_dwordx4 v[44:47], v232, s[4:5] offset:3072
	s_lshl_b32 s4, s6, 12
	s_add_u32 s4, s4, 0xc966000
	s_add_u32 s4, s4, s8
	s_addc_u32 s5, s9, 0
	global_load_dwordx4 v[48:51], v232, s[4:5]
	global_load_dwordx4 v[52:55], v232, s[4:5] offset:1024
	global_load_dwordx4 v[56:59], v232, s[4:5] offset:2048
	global_load_dwordx4 v[60:63], v232, s[4:5] offset:3072
	s_add_u32 s4, s10, 0x9000
	s_addc_u32 s5, s11, 0
	global_load_dwordx4 v[96:99], v232, s[4:5]
	global_load_dwordx4 v[100:103], v232, s[4:5] offset:1024
	global_load_dwordx4 v[104:107], v232, s[4:5] offset:2048
	global_load_dwordx4 v[108:111], v232, s[4:5] offset:3072
	s_add_u32 s4, s4, 0x1000
	s_addc_u32 s5, s5, 0
	global_load_dwordx4 v[112:115], v232, s[4:5]
	global_load_dwordx4 v[116:119], v232, s[4:5] offset:1024
	global_load_dwordx4 v[120:123], v232, s[4:5] offset:2048
	global_load_dwordx4 v[124:127], v232, s[4:5] offset:3072
	s_waitcnt vmcnt(16)
	v_pk_add_f32 v[204:205], v[0:1], v[2:3]
	v_pk_add_f32 v[206:207], v[4:5], v[6:7]
	v_pk_add_f32 v[208:209], v[8:9], v[10:11]
	v_pk_add_f32 v[210:211], v[12:13], v[14:15]
	v_pk_add_f32 v[216:217], v[16:17], v[18:19]
	v_pk_add_f32 v[218:219], v[20:21], v[22:23]
	v_pk_add_f32 v[220:221], v[24:25], v[26:27]
	v_pk_add_f32 v[222:223], v[28:29], v[30:31]
	v_pk_add_f32 v[204:205], v[204:205], v[206:207]
	v_pk_add_f32 v[208:209], v[208:209], v[210:211]
	v_pk_add_f32 v[216:217], v[216:217], v[218:219]
	v_pk_add_f32 v[220:221], v[220:221], v[222:223]
	v_pk_add_f32 v[204:205], v[204:205], v[208:209]
	v_pk_add_f32 v[216:217], v[216:217], v[220:221]
	v_add_f32_e32 v204, v204, v205
	v_add_f32_e32 v216, v216, v217
	s_nop 1
	v_add_f32_dpp v204, v204, v204 row_ror:1 row_mask:0xf bank_mask:0xf bound_ctrl:1
	v_add_f32_dpp v216, v216, v216 row_ror:1 row_mask:0xf bank_mask:0xf bound_ctrl:1
	s_nop 0
	v_add_f32_dpp v204, v204, v204 row_ror:2 row_mask:0xf bank_mask:0xf bound_ctrl:1
	v_add_f32_dpp v216, v216, v216 row_ror:2 row_mask:0xf bank_mask:0xf bound_ctrl:1
	s_nop 0
	v_add_f32_dpp v204, v204, v204 row_ror:4 row_mask:0xf bank_mask:0xf bound_ctrl:1
	v_add_f32_dpp v216, v216, v216 row_ror:4 row_mask:0xf bank_mask:0xf bound_ctrl:1
	s_nop 0
	v_add_f32_dpp v204, v204, v204 row_ror:8 row_mask:0xf bank_mask:0xf bound_ctrl:1
	v_add_f32_dpp v216, v216, v216 row_ror:8 row_mask:0xf bank_mask:0xf bound_ctrl:1
	s_nop 0
	v_mov_b32_e32 v205, v204
	v_mov_b32_e32 v217, v216
	s_nop 1
	v_permlane16_swap_b32_e32 v204, v205
	v_permlane16_swap_b32_e32 v216, v217
	s_nop 0
	v_add_f32_e32 v204, v204, v205
	v_add_f32_e32 v216, v216, v217
	v_mov_b32_e32 v205, v204
	v_mov_b32_e32 v217, v216
	s_nop 1
	v_permlane32_swap_b32_e32 v204, v205
	v_permlane32_swap_b32_e32 v216, v217
	s_nop 0
	v_add_f32_e32 v204, v204, v205
	v_add_f32_e32 v216, v216, v217
	v_mul_f32_e32 v212, 0x3a800000, v204
	v_mul_f32_e32 v224, 0x3a800000, v216
	v_pk_add_f32 v[0:1], v[0:1], v[212:213] op_sel_hi:[1,0] neg_lo:[0,1] neg_hi:[0,1]
	v_pk_add_f32 v[2:3], v[2:3], v[212:213] op_sel_hi:[1,0] neg_lo:[0,1] neg_hi:[0,1]
	v_pk_add_f32 v[4:5], v[4:5], v[212:213] op_sel_hi:[1,0] neg_lo:[0,1] neg_hi:[0,1]
	v_pk_add_f32 v[6:7], v[6:7], v[212:213] op_sel_hi:[1,0] neg_lo:[0,1] neg_hi:[0,1]
	v_pk_add_f32 v[8:9], v[8:9], v[212:213] op_sel_hi:[1,0] neg_lo:[0,1] neg_hi:[0,1]
	v_pk_add_f32 v[10:11], v[10:11], v[212:213] op_sel_hi:[1,0] neg_lo:[0,1] neg_hi:[0,1]
	v_pk_add_f32 v[12:13], v[12:13], v[212:213] op_sel_hi:[1,0] neg_lo:[0,1] neg_hi:[0,1]
	v_pk_add_f32 v[14:15], v[14:15], v[212:213] op_sel_hi:[1,0] neg_lo:[0,1] neg_hi:[0,1]
	v_pk_add_f32 v[16:17], v[16:17], v[224:225] op_sel_hi:[1,0] neg_lo:[0,1] neg_hi:[0,1]
	v_pk_add_f32 v[18:19], v[18:19], v[224:225] op_sel_hi:[1,0] neg_lo:[0,1] neg_hi:[0,1]
	v_pk_add_f32 v[20:21], v[20:21], v[224:225] op_sel_hi:[1,0] neg_lo:[0,1] neg_hi:[0,1]
	v_pk_add_f32 v[22:23], v[22:23], v[224:225] op_sel_hi:[1,0] neg_lo:[0,1] neg_hi:[0,1]
	v_pk_add_f32 v[24:25], v[24:25], v[224:225] op_sel_hi:[1,0] neg_lo:[0,1] neg_hi:[0,1]
	v_pk_add_f32 v[26:27], v[26:27], v[224:225] op_sel_hi:[1,0] neg_lo:[0,1] neg_hi:[0,1]
	v_pk_add_f32 v[28:29], v[28:29], v[224:225] op_sel_hi:[1,0] neg_lo:[0,1] neg_hi:[0,1]
	v_pk_add_f32 v[30:31], v[30:31], v[224:225] op_sel_hi:[1,0] neg_lo:[0,1] neg_hi:[0,1]
	v_pk_mul_f32 v[204:205], v[0:1], v[0:1]
	v_pk_mul_f32 v[206:207], v[2:3], v[2:3]
	v_pk_mul_f32 v[216:217], v[16:17], v[16:17]
	v_pk_mul_f32 v[218:219], v[18:19], v[18:19]
	v_pk_fma_f32 v[204:205], v[4:5], v[4:5], v[204:205]
	v_pk_fma_f32 v[206:207], v[6:7], v[6:7], v[206:207]
	v_pk_fma_f32 v[216:217], v[20:21], v[20:21], v[216:217]
	v_pk_fma_f32 v[218:219], v[22:23], v[22:23], v[218:219]
	v_pk_fma_f32 v[204:205], v[8:9], v[8:9], v[204:205]
	v_pk_fma_f32 v[206:207], v[10:11], v[10:11], v[206:207]
	v_pk_fma_f32 v[216:217], v[24:25], v[24:25], v[216:217]
	v_pk_fma_f32 v[218:219], v[26:27], v[26:27], v[218:219]
	v_pk_fma_f32 v[204:205], v[12:13], v[12:13], v[204:205]
	v_pk_fma_f32 v[206:207], v[14:15], v[14:15], v[206:207]
	v_pk_fma_f32 v[216:217], v[28:29], v[28:29], v[216:217]
	v_pk_fma_f32 v[218:219], v[30:31], v[30:31], v[218:219]
	v_pk_add_f32 v[204:205], v[204:205], v[206:207]
	v_pk_add_f32 v[216:217], v[216:217], v[218:219]
	v_add_f32_e32 v204, v204, v205
	v_add_f32_e32 v216, v216, v217
	s_nop 1
	v_add_f32_dpp v204, v204, v204 row_ror:1 row_mask:0xf bank_mask:0xf bound_ctrl:1
	v_add_f32_dpp v216, v216, v216 row_ror:1 row_mask:0xf bank_mask:0xf bound_ctrl:1
	s_nop 0
	v_add_f32_dpp v204, v204, v204 row_ror:2 row_mask:0xf bank_mask:0xf bound_ctrl:1
	v_add_f32_dpp v216, v216, v216 row_ror:2 row_mask:0xf bank_mask:0xf bound_ctrl:1
	s_nop 0
	v_add_f32_dpp v204, v204, v204 row_ror:4 row_mask:0xf bank_mask:0xf bound_ctrl:1
	v_add_f32_dpp v216, v216, v216 row_ror:4 row_mask:0xf bank_mask:0xf bound_ctrl:1
	s_nop 0
	v_add_f32_dpp v204, v204, v204 row_ror:8 row_mask:0xf bank_mask:0xf bound_ctrl:1
	v_add_f32_dpp v216, v216, v216 row_ror:8 row_mask:0xf bank_mask:0xf bound_ctrl:1
	s_nop 0
	v_mov_b32_e32 v205, v204
	v_mov_b32_e32 v217, v216
	s_nop 1
	v_permlane16_swap_b32_e32 v204, v205
	v_permlane16_swap_b32_e32 v216, v217
	s_nop 0
	v_add_f32_e32 v204, v204, v205
	v_add_f32_e32 v216, v216, v217
	v_mov_b32_e32 v205, v204
	v_mov_b32_e32 v217, v216
	s_nop 1
	v_permlane32_swap_b32_e32 v204, v205
	v_permlane32_swap_b32_e32 v216, v217
	s_nop 0
	v_add_f32_e32 v204, v204, v205
	v_add_f32_e32 v216, v216, v217
	v_mov_b32_e32 v205, 0x3727c5ac
	v_fmac_f32_e32 v205, 0x3a800000, v204
	v_mov_b32_e32 v217, 0x3727c5ac
	v_fmac_f32_e32 v217, 0x3a800000, v216
	v_mul_f32_e32 v206, 0x4b800000, v205
	s_mov_b32 s4, 0x800000
	v_cmp_gt_f32_e32 vcc, s4, v205
	s_nop 1
	v_cndmask_b32_e32 v205, v205, v206, vcc
	v_rsq_f32_e32 v205, v205
	s_nop 0
	v_mul_f32_e32 v206, 0x45800000, v205
	v_cndmask_b32_e32 v214, v205, v206, vcc
	v_mul_f32_e32 v218, 0x4b800000, v217
	s_mov_b32 s4, 0x800000
	v_cmp_gt_f32_e32 vcc, s4, v217
	s_nop 1
	v_cndmask_b32_e32 v217, v217, v218, vcc
	v_rsq_f32_e32 v217, v217
	s_nop 0
	v_mul_f32_e32 v218, 0x45800000, v217
	v_cndmask_b32_e32 v226, v217, v218, vcc
	v_pk_mul_f32 v[0:1], v[0:1], v[214:215] op_sel_hi:[1,0]
	v_pk_mul_f32 v[2:3], v[2:3], v[214:215] op_sel_hi:[1,0]
	v_pk_mul_f32 v[4:5], v[4:5], v[214:215] op_sel_hi:[1,0]
	v_pk_mul_f32 v[6:7], v[6:7], v[214:215] op_sel_hi:[1,0]
	v_pk_mul_f32 v[8:9], v[8:9], v[214:215] op_sel_hi:[1,0]
	v_pk_mul_f32 v[10:11], v[10:11], v[214:215] op_sel_hi:[1,0]
	v_pk_mul_f32 v[12:13], v[12:13], v[214:215] op_sel_hi:[1,0]
	v_pk_mul_f32 v[14:15], v[14:15], v[214:215] op_sel_hi:[1,0]
	v_pk_mul_f32 v[16:17], v[16:17], v[226:227] op_sel_hi:[1,0]
	v_pk_mul_f32 v[18:19], v[18:19], v[226:227] op_sel_hi:[1,0]
	v_pk_mul_f32 v[20:21], v[20:21], v[226:227] op_sel_hi:[1,0]
	v_pk_mul_f32 v[22:23], v[22:23], v[226:227] op_sel_hi:[1,0]
	v_pk_mul_f32 v[24:25], v[24:25], v[226:227] op_sel_hi:[1,0]
	v_pk_mul_f32 v[26:27], v[26:27], v[226:227] op_sel_hi:[1,0]
	v_pk_mul_f32 v[28:29], v[28:29], v[226:227] op_sel_hi:[1,0]
	v_pk_mul_f32 v[30:31], v[30:31], v[226:227] op_sel_hi:[1,0]
	v_pk_fma_f32 v[0:1], v[136:137], v[0:1], v[152:153]
	v_pk_fma_f32 v[2:3], v[138:139], v[2:3], v[154:155]
	v_pk_fma_f32 v[4:5], v[140:141], v[4:5], v[156:157]
	v_pk_fma_f32 v[6:7], v[142:143], v[6:7], v[158:159]
	v_pk_fma_f32 v[8:9], v[144:145], v[8:9], v[160:161]
	v_pk_fma_f32 v[10:11], v[146:147], v[10:11], v[162:163]
	v_pk_fma_f32 v[12:13], v[148:149], v[12:13], v[164:165]
	v_pk_fma_f32 v[14:15], v[150:151], v[14:15], v[166:167]
	v_pk_fma_f32 v[16:17], v[136:137], v[16:17], v[152:153]
	v_pk_fma_f32 v[18:19], v[138:139], v[18:19], v[154:155]
	v_pk_fma_f32 v[20:21], v[140:141], v[20:21], v[156:157]
	v_pk_fma_f32 v[22:23], v[142:143], v[22:23], v[158:159]
	v_pk_fma_f32 v[24:25], v[144:145], v[24:25], v[160:161]
	v_pk_fma_f32 v[26:27], v[146:147], v[26:27], v[162:163]
	v_pk_fma_f32 v[28:29], v[148:149], v[28:29], v[164:165]
	v_pk_fma_f32 v[30:31], v[150:151], v[30:31], v[166:167]
	v_mov_b32_e32 v228, v212
	v_mov_b32_e32 v229, v214
	v_mov_b32_e32 v168, v224
	v_mov_b32_e32 v169, v226
	s_cmp_eq_u32 s57, 1
	s_cbranch_scc1 .Llna_last0
	v_add_f32_e32 v80, 1.0, v80
	v_add_f32_e32 v81, 1.0, v81
	v_add_f32_e32 v82, 1.0, v82
	v_add_f32_e32 v83, 1.0, v83
	v_add_f32_e32 v84, 1.0, v84
	v_add_f32_e32 v85, 1.0, v85
	v_add_f32_e32 v86, 1.0, v86
	v_add_f32_e32 v87, 1.0, v87
	v_add_f32_e32 v88, 1.0, v88
	v_add_f32_e32 v89, 1.0, v89
	v_add_f32_e32 v90, 1.0, v90
	v_add_f32_e32 v91, 1.0, v91
	v_add_f32_e32 v92, 1.0, v92
	v_add_f32_e32 v93, 1.0, v93
	v_add_f32_e32 v94, 1.0, v94
	v_add_f32_e32 v95, 1.0, v95
	v_pk_fma_f32 v[204:205], v[80:81], v[0:1], v[64:65]
	v_pk_fma_f32 v[206:207], v[82:83], v[2:3], v[66:67]
	v_pk_fma_f32 v[208:209], v[84:85], v[4:5], v[68:69]
	v_pk_fma_f32 v[210:211], v[86:87], v[6:7], v[70:71]
	v_pk_fma_f32 v[212:213], v[88:89], v[8:9], v[72:73]
	v_pk_fma_f32 v[214:215], v[90:91], v[10:11], v[74:75]
	v_pk_fma_f32 v[216:217], v[92:93], v[12:13], v[76:77]
	v_pk_fma_f32 v[218:219], v[94:95], v[14:15], v[78:79]
	v_cvt_pk_bf16_f32 v220, v204, v205
	v_cvt_pk_bf16_f32 v221, v206, v207
	v_cvt_pk_bf16_f32 v222, v208, v209
	v_cvt_pk_bf16_f32 v223, v210, v211
	v_cvt_pk_bf16_f32 v224, v212, v213
	v_cvt_pk_bf16_f32 v225, v214, v215
	v_cvt_pk_bf16_f32 v226, v216, v217
	v_cvt_pk_bf16_f32 v227, v218, v219
	s_mul_i32 s4, s6, 0x880
	s_add_u32 s4, s4, 0xe166000
	s_add_u32 s4, s4, s8
	s_addc_u32 s5, s9, 0
	global_store_dwordx2 v233, v[220:221], s[4:5]
	global_store_dwordx2 v233, v[222:223], s[4:5] offset:512
	global_store_dwordx2 v233, v[224:225], s[4:5] offset:1024
	global_store_dwordx2 v233, v[226:227], s[4:5] offset:1536
	s_mov_b64 s[12:13], exec
	s_mov_b64 exec, 1
	global_store_dwordx2 v129, v[228:229], s[4:5] offset:2048
	s_mov_b64 exec, s[12:13]
	v_pk_fma_f32 v[204:205], v[80:81], v[16:17], v[64:65]
	v_pk_fma_f32 v[206:207], v[82:83], v[18:19], v[66:67]
	v_pk_fma_f32 v[208:209], v[84:85], v[20:21], v[68:69]
	v_pk_fma_f32 v[210:211], v[86:87], v[22:23], v[70:71]
	v_pk_fma_f32 v[212:213], v[88:89], v[24:25], v[72:73]
	v_pk_fma_f32 v[214:215], v[90:91], v[26:27], v[74:75]
	v_pk_fma_f32 v[216:217], v[92:93], v[28:29], v[76:77]
	v_pk_fma_f32 v[218:219], v[94:95], v[30:31], v[78:79]
	v_cvt_pk_bf16_f32 v220, v204, v205
	v_cvt_pk_bf16_f32 v221, v206, v207
	v_cvt_pk_bf16_f32 v222, v208, v209
	v_cvt_pk_bf16_f32 v223, v210, v211
	v_cvt_pk_bf16_f32 v224, v212, v213
	v_cvt_pk_bf16_f32 v225, v214, v215
	v_cvt_pk_bf16_f32 v226, v216, v217
	v_cvt_pk_bf16_f32 v227, v218, v219
	s_mul_i32 s4, s6, 0x880
	s_add_u32 s4, s4, 0xe5a6000
	s_add_u32 s4, s4, s8
	s_addc_u32 s5, s9, 0
	global_store_dwordx2 v233, v[220:221], s[4:5]
	global_store_dwordx2 v233, v[222:223], s[4:5] offset:512
	global_store_dwordx2 v233, v[224:225], s[4:5] offset:1024
	global_store_dwordx2 v233, v[226:227], s[4:5] offset:1536
	s_mov_b64 s[12:13], exec
	s_mov_b64 exec, 1
	global_store_dwordx2 v129, v[168:169], s[4:5] offset:2048
	s_mov_b64 exec, s[12:13]
	s_branch .Llna_join0
.Llna_last0:
	s_lshl_b32 s4, s6, 12
	s_add_u32 s4, s4, 0x0
	s_add_u32 s4, s4, s88
	s_addc_u32 s5, s89, 0
	global_store_dwordx4 v232, v[0:3], s[4:5]
	global_store_dwordx4 v232, v[4:7], s[4:5] offset:1024
	global_store_dwordx4 v232, v[8:11], s[4:5] offset:2048
	global_store_dwordx4 v232, v[12:15], s[4:5] offset:3072
	s_lshl_b32 s4, s6, 12
	s_add_u32 s4, s4, 0x800000
	s_add_u32 s4, s4, s88
	s_addc_u32 s5, s89, 0
	global_store_dwordx4 v232, v[16:19], s[4:5]
	global_store_dwordx4 v232, v[20:23], s[4:5] offset:1024
	global_store_dwordx4 v232, v[24:27], s[4:5] offset:2048
	global_store_dwordx4 v232, v[28:31], s[4:5] offset:3072
.Llna_join0:
	s_lshl_b32 s4, s6, 12
	s_add_u32 s4, s4, 0xd166000
	s_add_u32 s4, s4, s8
	s_addc_u32 s5, s9, 0
	global_load_dwordx4 v[0:3], v232, s[4:5]
	global_load_dwordx4 v[4:7], v232, s[4:5] offset:1024
	global_load_dwordx4 v[8:11], v232, s[4:5] offset:2048
	global_load_dwordx4 v[12:15], v232, s[4:5] offset:3072
	s_lshl_b32 s4, s6, 12
	s_add_u32 s4, s4, 0xd966000
	s_add_u32 s4, s4, s8
	s_addc_u32 s5, s9, 0
	global_load_dwordx4 v[16:19], v232, s[4:5]
	global_load_dwordx4 v[20:23], v232, s[4:5] offset:1024
	global_load_dwordx4 v[24:27], v232, s[4:5] offset:2048
	global_load_dwordx4 v[28:31], v232, s[4:5] offset:3072
	s_add_u32 s4, s10, 0x12000
	s_addc_u32 s5, s11, 0
	global_load_dwordx4 v[64:67], v232, s[4:5]
	global_load_dwordx4 v[68:71], v232, s[4:5] offset:1024
	global_load_dwordx4 v[72:75], v232, s[4:5] offset:2048
	global_load_dwordx4 v[76:79], v232, s[4:5] offset:3072
	s_add_u32 s4, s4, 0x1000
	s_addc_u32 s5, s5, 0
	global_load_dwordx4 v[80:83], v232, s[4:5]
	global_load_dwordx4 v[84:87], v232, s[4:5] offset:1024
	global_load_dwordx4 v[88:91], v232, s[4:5] offset:2048
	global_load_dwordx4 v[92:95], v232, s[4:5] offset:3072
	s_waitcnt vmcnt(24)
	v_pk_add_f32 v[204:205], v[32:33], v[34:35]
	v_pk_add_f32 v[206:207], v[36:37], v[38:39]
	v_pk_add_f32 v[208:209], v[40:41], v[42:43]
	v_pk_add_f32 v[210:211], v[44:45], v[46:47]
	v_pk_add_f32 v[216:217], v[48:49], v[50:51]
	v_pk_add_f32 v[218:219], v[52:53], v[54:55]
	v_pk_add_f32 v[220:221], v[56:57], v[58:59]
	v_pk_add_f32 v[222:223], v[60:61], v[62:63]
	v_pk_add_f32 v[204:205], v[204:205], v[206:207]
	v_pk_add_f32 v[208:209], v[208:209], v[210:211]
	v_pk_add_f32 v[216:217], v[216:217], v[218:219]
	v_pk_add_f32 v[220:221], v[220:221], v[222:223]
	v_pk_add_f32 v[204:205], v[204:205], v[208:209]
	v_pk_add_f32 v[216:217], v[216:217], v[220:221]
	v_add_f32_e32 v204, v204, v205
	v_add_f32_e32 v216, v216, v217
	s_nop 1
	v_add_f32_dpp v204, v204, v204 row_ror:1 row_mask:0xf bank_mask:0xf bound_ctrl:1
	v_add_f32_dpp v216, v216, v216 row_ror:1 row_mask:0xf bank_mask:0xf bound_ctrl:1
	s_nop 0
	v_add_f32_dpp v204, v204, v204 row_ror:2 row_mask:0xf bank_mask:0xf bound_ctrl:1
	v_add_f32_dpp v216, v216, v216 row_ror:2 row_mask:0xf bank_mask:0xf bound_ctrl:1
	s_nop 0
	v_add_f32_dpp v204, v204, v204 row_ror:4 row_mask:0xf bank_mask:0xf bound_ctrl:1
	v_add_f32_dpp v216, v216, v216 row_ror:4 row_mask:0xf bank_mask:0xf bound_ctrl:1
	s_nop 0
	v_add_f32_dpp v204, v204, v204 row_ror:8 row_mask:0xf bank_mask:0xf bound_ctrl:1
	v_add_f32_dpp v216, v216, v216 row_ror:8 row_mask:0xf bank_mask:0xf bound_ctrl:1
	s_nop 0
	v_mov_b32_e32 v205, v204
	v_mov_b32_e32 v217, v216
	s_nop 1
	v_permlane16_swap_b32_e32 v204, v205
	v_permlane16_swap_b32_e32 v216, v217
	s_nop 0
	v_add_f32_e32 v204, v204, v205
	v_add_f32_e32 v216, v216, v217
	v_mov_b32_e32 v205, v204
	v_mov_b32_e32 v217, v216
	s_nop 1
	v_permlane32_swap_b32_e32 v204, v205
	v_permlane32_swap_b32_e32 v216, v217
	s_nop 0
	v_add_f32_e32 v204, v204, v205
	v_add_f32_e32 v216, v216, v217
	v_mul_f32_e32 v212, 0x3a800000, v204
	v_mul_f32_e32 v224, 0x3a800000, v216
	v_pk_add_f32 v[32:33], v[32:33], v[212:213] op_sel_hi:[1,0] neg_lo:[0,1] neg_hi:[0,1]
	v_pk_add_f32 v[34:35], v[34:35], v[212:213] op_sel_hi:[1,0] neg_lo:[0,1] neg_hi:[0,1]
	v_pk_add_f32 v[36:37], v[36:37], v[212:213] op_sel_hi:[1,0] neg_lo:[0,1] neg_hi:[0,1]
	v_pk_add_f32 v[38:39], v[38:39], v[212:213] op_sel_hi:[1,0] neg_lo:[0,1] neg_hi:[0,1]
	v_pk_add_f32 v[40:41], v[40:41], v[212:213] op_sel_hi:[1,0] neg_lo:[0,1] neg_hi:[0,1]
	v_pk_add_f32 v[42:43], v[42:43], v[212:213] op_sel_hi:[1,0] neg_lo:[0,1] neg_hi:[0,1]
	v_pk_add_f32 v[44:45], v[44:45], v[212:213] op_sel_hi:[1,0] neg_lo:[0,1] neg_hi:[0,1]
	v_pk_add_f32 v[46:47], v[46:47], v[212:213] op_sel_hi:[1,0] neg_lo:[0,1] neg_hi:[0,1]
	v_pk_add_f32 v[48:49], v[48:49], v[224:225] op_sel_hi:[1,0] neg_lo:[0,1] neg_hi:[0,1]
	v_pk_add_f32 v[50:51], v[50:51], v[224:225] op_sel_hi:[1,0] neg_lo:[0,1] neg_hi:[0,1]
	v_pk_add_f32 v[52:53], v[52:53], v[224:225] op_sel_hi:[1,0] neg_lo:[0,1] neg_hi:[0,1]
	v_pk_add_f32 v[54:55], v[54:55], v[224:225] op_sel_hi:[1,0] neg_lo:[0,1] neg_hi:[0,1]
	v_pk_add_f32 v[56:57], v[56:57], v[224:225] op_sel_hi:[1,0] neg_lo:[0,1] neg_hi:[0,1]
	v_pk_add_f32 v[58:59], v[58:59], v[224:225] op_sel_hi:[1,0] neg_lo:[0,1] neg_hi:[0,1]
	v_pk_add_f32 v[60:61], v[60:61], v[224:225] op_sel_hi:[1,0] neg_lo:[0,1] neg_hi:[0,1]
	v_pk_add_f32 v[62:63], v[62:63], v[224:225] op_sel_hi:[1,0] neg_lo:[0,1] neg_hi:[0,1]
	v_pk_mul_f32 v[204:205], v[32:33], v[32:33]
	v_pk_mul_f32 v[206:207], v[34:35], v[34:35]
	v_pk_mul_f32 v[216:217], v[48:49], v[48:49]
	v_pk_mul_f32 v[218:219], v[50:51], v[50:51]
	v_pk_fma_f32 v[204:205], v[36:37], v[36:37], v[204:205]
	v_pk_fma_f32 v[206:207], v[38:39], v[38:39], v[206:207]
	v_pk_fma_f32 v[216:217], v[52:53], v[52:53], v[216:217]
	v_pk_fma_f32 v[218:219], v[54:55], v[54:55], v[218:219]
	v_pk_fma_f32 v[204:205], v[40:41], v[40:41], v[204:205]
	v_pk_fma_f32 v[206:207], v[42:43], v[42:43], v[206:207]
	v_pk_fma_f32 v[216:217], v[56:57], v[56:57], v[216:217]
	v_pk_fma_f32 v[218:219], v[58:59], v[58:59], v[218:219]
	v_pk_fma_f32 v[204:205], v[44:45], v[44:45], v[204:205]
	v_pk_fma_f32 v[206:207], v[46:47], v[46:47], v[206:207]
	v_pk_fma_f32 v[216:217], v[60:61], v[60:61], v[216:217]
	v_pk_fma_f32 v[218:219], v[62:63], v[62:63], v[218:219]
	v_pk_add_f32 v[204:205], v[204:205], v[206:207]
	v_pk_add_f32 v[216:217], v[216:217], v[218:219]
	v_add_f32_e32 v204, v204, v205
	v_add_f32_e32 v216, v216, v217
	s_nop 1
	v_add_f32_dpp v204, v204, v204 row_ror:1 row_mask:0xf bank_mask:0xf bound_ctrl:1
	v_add_f32_dpp v216, v216, v216 row_ror:1 row_mask:0xf bank_mask:0xf bound_ctrl:1
	s_nop 0
	v_add_f32_dpp v204, v204, v204 row_ror:2 row_mask:0xf bank_mask:0xf bound_ctrl:1
	v_add_f32_dpp v216, v216, v216 row_ror:2 row_mask:0xf bank_mask:0xf bound_ctrl:1
	s_nop 0
	v_add_f32_dpp v204, v204, v204 row_ror:4 row_mask:0xf bank_mask:0xf bound_ctrl:1
	v_add_f32_dpp v216, v216, v216 row_ror:4 row_mask:0xf bank_mask:0xf bound_ctrl:1
	s_nop 0
	v_add_f32_dpp v204, v204, v204 row_ror:8 row_mask:0xf bank_mask:0xf bound_ctrl:1
	v_add_f32_dpp v216, v216, v216 row_ror:8 row_mask:0xf bank_mask:0xf bound_ctrl:1
	s_nop 0
	v_mov_b32_e32 v205, v204
	v_mov_b32_e32 v217, v216
	s_nop 1
	v_permlane16_swap_b32_e32 v204, v205
	v_permlane16_swap_b32_e32 v216, v217
	s_nop 0
	v_add_f32_e32 v204, v204, v205
	v_add_f32_e32 v216, v216, v217
	v_mov_b32_e32 v205, v204
	v_mov_b32_e32 v217, v216
	s_nop 1
	v_permlane32_swap_b32_e32 v204, v205
	v_permlane32_swap_b32_e32 v216, v217
	s_nop 0
	v_add_f32_e32 v204, v204, v205
	v_add_f32_e32 v216, v216, v217
	v_mov_b32_e32 v205, 0x3727c5ac
	v_fmac_f32_e32 v205, 0x3a800000, v204
	v_mov_b32_e32 v217, 0x3727c5ac
	v_fmac_f32_e32 v217, 0x3a800000, v216
	v_mul_f32_e32 v206, 0x4b800000, v205
	s_mov_b32 s4, 0x800000
	v_cmp_gt_f32_e32 vcc, s4, v205
	s_nop 1
	v_cndmask_b32_e32 v205, v205, v206, vcc
	v_rsq_f32_e32 v205, v205
	s_nop 0
	v_mul_f32_e32 v206, 0x45800000, v205
	v_cndmask_b32_e32 v214, v205, v206, vcc
	v_mul_f32_e32 v218, 0x4b800000, v217
	s_mov_b32 s4, 0x800000
	v_cmp_gt_f32_e32 vcc, s4, v217
	s_nop 1
	v_cndmask_b32_e32 v217, v217, v218, vcc
	v_rsq_f32_e32 v217, v217
	s_nop 0
	v_mul_f32_e32 v218, 0x45800000, v217
	v_cndmask_b32_e32 v226, v217, v218, vcc
	v_pk_mul_f32 v[32:33], v[32:33], v[214:215] op_sel_hi:[1,0]
	v_pk_mul_f32 v[34:35], v[34:35], v[214:215] op_sel_hi:[1,0]
	v_pk_mul_f32 v[36:37], v[36:37], v[214:215] op_sel_hi:[1,0]
	v_pk_mul_f32 v[38:39], v[38:39], v[214:215] op_sel_hi:[1,0]
	v_pk_mul_f32 v[40:41], v[40:41], v[214:215] op_sel_hi:[1,0]
	v_pk_mul_f32 v[42:43], v[42:43], v[214:215] op_sel_hi:[1,0]
	v_pk_mul_f32 v[44:45], v[44:45], v[214:215] op_sel_hi:[1,0]
	v_pk_mul_f32 v[46:47], v[46:47], v[214:215] op_sel_hi:[1,0]
	v_pk_mul_f32 v[48:49], v[48:49], v[226:227] op_sel_hi:[1,0]
	v_pk_mul_f32 v[50:51], v[50:51], v[226:227] op_sel_hi:[1,0]
	v_pk_mul_f32 v[52:53], v[52:53], v[226:227] op_sel_hi:[1,0]
	v_pk_mul_f32 v[54:55], v[54:55], v[226:227] op_sel_hi:[1,0]
	v_pk_mul_f32 v[56:57], v[56:57], v[226:227] op_sel_hi:[1,0]
	v_pk_mul_f32 v[58:59], v[58:59], v[226:227] op_sel_hi:[1,0]
	v_pk_mul_f32 v[60:61], v[60:61], v[226:227] op_sel_hi:[1,0]
	v_pk_mul_f32 v[62:63], v[62:63], v[226:227] op_sel_hi:[1,0]
	v_pk_fma_f32 v[32:33], v[136:137], v[32:33], v[152:153]
	v_pk_fma_f32 v[34:35], v[138:139], v[34:35], v[154:155]
	v_pk_fma_f32 v[36:37], v[140:141], v[36:37], v[156:157]
	v_pk_fma_f32 v[38:39], v[142:143], v[38:39], v[158:159]
	v_pk_fma_f32 v[40:41], v[144:145], v[40:41], v[160:161]
	v_pk_fma_f32 v[42:43], v[146:147], v[42:43], v[162:163]
	v_pk_fma_f32 v[44:45], v[148:149], v[44:45], v[164:165]
	v_pk_fma_f32 v[46:47], v[150:151], v[46:47], v[166:167]
	v_pk_fma_f32 v[48:49], v[136:137], v[48:49], v[152:153]
	v_pk_fma_f32 v[50:51], v[138:139], v[50:51], v[154:155]
	v_pk_fma_f32 v[52:53], v[140:141], v[52:53], v[156:157]
	v_pk_fma_f32 v[54:55], v[142:143], v[54:55], v[158:159]
	v_pk_fma_f32 v[56:57], v[144:145], v[56:57], v[160:161]
	v_pk_fma_f32 v[58:59], v[146:147], v[58:59], v[162:163]
	v_pk_fma_f32 v[60:61], v[148:149], v[60:61], v[164:165]
	v_pk_fma_f32 v[62:63], v[150:151], v[62:63], v[166:167]
	v_mov_b32_e32 v228, v212
	v_mov_b32_e32 v229, v214
	v_mov_b32_e32 v168, v224
	v_mov_b32_e32 v169, v226
	s_cmp_eq_u32 s57, 1
	s_cbranch_scc1 .Llna_last1
	v_add_f32_e32 v112, 1.0, v112
	v_add_f32_e32 v113, 1.0, v113
	v_add_f32_e32 v114, 1.0, v114
	v_add_f32_e32 v115, 1.0, v115
	v_add_f32_e32 v116, 1.0, v116
	v_add_f32_e32 v117, 1.0, v117
	v_add_f32_e32 v118, 1.0, v118
	v_add_f32_e32 v119, 1.0, v119
	v_add_f32_e32 v120, 1.0, v120
	v_add_f32_e32 v121, 1.0, v121
	v_add_f32_e32 v122, 1.0, v122
	v_add_f32_e32 v123, 1.0, v123
	v_add_f32_e32 v124, 1.0, v124
	v_add_f32_e32 v125, 1.0, v125
	v_add_f32_e32 v126, 1.0, v126
	v_add_f32_e32 v127, 1.0, v127
	v_pk_fma_f32 v[204:205], v[112:113], v[32:33], v[96:97]
	v_pk_fma_f32 v[206:207], v[114:115], v[34:35], v[98:99]
	v_pk_fma_f32 v[208:209], v[116:117], v[36:37], v[100:101]
	v_pk_fma_f32 v[210:211], v[118:119], v[38:39], v[102:103]
	v_pk_fma_f32 v[212:213], v[120:121], v[40:41], v[104:105]
	v_pk_fma_f32 v[214:215], v[122:123], v[42:43], v[106:107]
	v_pk_fma_f32 v[216:217], v[124:125], v[44:45], v[108:109]
	v_pk_fma_f32 v[218:219], v[126:127], v[46:47], v[110:111]
	v_cvt_pk_bf16_f32 v220, v204, v205
	v_cvt_pk_bf16_f32 v221, v206, v207
	v_cvt_pk_bf16_f32 v222, v208, v209
	v_cvt_pk_bf16_f32 v223, v210, v211
	v_cvt_pk_bf16_f32 v224, v212, v213
	v_cvt_pk_bf16_f32 v225, v214, v215
	v_cvt_pk_bf16_f32 v226, v216, v217
	v_cvt_pk_bf16_f32 v227, v218, v219
	s_mul_i32 s4, s6, 0x880
	s_add_u32 s4, s4, 0xe9e6000
	s_add_u32 s4, s4, s8
	s_addc_u32 s5, s9, 0
	global_store_dwordx2 v233, v[220:221], s[4:5]
	global_store_dwordx2 v233, v[222:223], s[4:5] offset:512
	global_store_dwordx2 v233, v[224:225], s[4:5] offset:1024
	global_store_dwordx2 v233, v[226:227], s[4:5] offset:1536
	s_mov_b64 s[12:13], exec
	s_mov_b64 exec, 1
	global_store_dwordx2 v129, v[228:229], s[4:5] offset:2048
	s_mov_b64 exec, s[12:13]
	v_pk_fma_f32 v[204:205], v[112:113], v[48:49], v[96:97]
	v_pk_fma_f32 v[206:207], v[114:115], v[50:51], v[98:99]
	v_pk_fma_f32 v[208:209], v[116:117], v[52:53], v[100:101]
	v_pk_fma_f32 v[210:211], v[118:119], v[54:55], v[102:103]
	v_pk_fma_f32 v[212:213], v[120:121], v[56:57], v[104:105]
	v_pk_fma_f32 v[214:215], v[122:123], v[58:59], v[106:107]
	v_pk_fma_f32 v[216:217], v[124:125], v[60:61], v[108:109]
	v_pk_fma_f32 v[218:219], v[126:127], v[62:63], v[110:111]
	v_cvt_pk_bf16_f32 v220, v204, v205
	v_cvt_pk_bf16_f32 v221, v206, v207
	v_cvt_pk_bf16_f32 v222, v208, v209
	v_cvt_pk_bf16_f32 v223, v210, v211
	v_cvt_pk_bf16_f32 v224, v212, v213
	v_cvt_pk_bf16_f32 v225, v214, v215
	v_cvt_pk_bf16_f32 v226, v216, v217
	v_cvt_pk_bf16_f32 v227, v218, v219
	s_mul_i32 s4, s6, 0x880
	s_add_u32 s4, s4, 0xee26000
	s_add_u32 s4, s4, s8
	s_addc_u32 s5, s9, 0
	global_store_dwordx2 v233, v[220:221], s[4:5]
	global_store_dwordx2 v233, v[222:223], s[4:5] offset:512
	global_store_dwordx2 v233, v[224:225], s[4:5] offset:1024
	global_store_dwordx2 v233, v[226:227], s[4:5] offset:1536
	s_mov_b64 s[12:13], exec
	s_mov_b64 exec, 1
	global_store_dwordx2 v129, v[168:169], s[4:5] offset:2048
	s_mov_b64 exec, s[12:13]
	s_branch .Llna_join1
.Llna_last1:
	s_lshl_b32 s4, s6, 12
	s_add_u32 s4, s4, 0x1000000
	s_add_u32 s4, s4, s88
	s_addc_u32 s5, s89, 0
	global_store_dwordx4 v232, v[32:35], s[4:5]
	global_store_dwordx4 v232, v[36:39], s[4:5] offset:1024
	global_store_dwordx4 v232, v[40:43], s[4:5] offset:2048
	global_store_dwordx4 v232, v[44:47], s[4:5] offset:3072
	s_lshl_b32 s4, s6, 12
	s_add_u32 s4, s4, 0x1800000
	s_add_u32 s4, s4, s88
	s_addc_u32 s5, s89, 0
	global_store_dwordx4 v232, v[48:51], s[4:5]
	global_store_dwordx4 v232, v[52:55], s[4:5] offset:1024
	global_store_dwordx4 v232, v[56:59], s[4:5] offset:2048
	global_store_dwordx4 v232, v[60:63], s[4:5] offset:3072
.Llna_join1:
	s_waitcnt vmcnt(8)
	v_pk_add_f32 v[204:205], v[0:1], v[2:3]
	v_pk_add_f32 v[206:207], v[4:5], v[6:7]
	v_pk_add_f32 v[208:209], v[8:9], v[10:11]
	v_pk_add_f32 v[210:211], v[12:13], v[14:15]
	v_pk_add_f32 v[216:217], v[16:17], v[18:19]
	v_pk_add_f32 v[218:219], v[20:21], v[22:23]
	v_pk_add_f32 v[220:221], v[24:25], v[26:27]
	v_pk_add_f32 v[222:223], v[28:29], v[30:31]
	v_pk_add_f32 v[204:205], v[204:205], v[206:207]
	v_pk_add_f32 v[208:209], v[208:209], v[210:211]
	v_pk_add_f32 v[216:217], v[216:217], v[218:219]
	v_pk_add_f32 v[220:221], v[220:221], v[222:223]
	v_pk_add_f32 v[204:205], v[204:205], v[208:209]
	v_pk_add_f32 v[216:217], v[216:217], v[220:221]
	v_add_f32_e32 v204, v204, v205
	v_add_f32_e32 v216, v216, v217
	s_nop 1
	v_add_f32_dpp v204, v204, v204 row_ror:1 row_mask:0xf bank_mask:0xf bound_ctrl:1
	v_add_f32_dpp v216, v216, v216 row_ror:1 row_mask:0xf bank_mask:0xf bound_ctrl:1
	s_nop 0
	v_add_f32_dpp v204, v204, v204 row_ror:2 row_mask:0xf bank_mask:0xf bound_ctrl:1
	v_add_f32_dpp v216, v216, v216 row_ror:2 row_mask:0xf bank_mask:0xf bound_ctrl:1
	s_nop 0
	v_add_f32_dpp v204, v204, v204 row_ror:4 row_mask:0xf bank_mask:0xf bound_ctrl:1
	v_add_f32_dpp v216, v216, v216 row_ror:4 row_mask:0xf bank_mask:0xf bound_ctrl:1
	s_nop 0
	v_add_f32_dpp v204, v204, v204 row_ror:8 row_mask:0xf bank_mask:0xf bound_ctrl:1
	v_add_f32_dpp v216, v216, v216 row_ror:8 row_mask:0xf bank_mask:0xf bound_ctrl:1
	s_nop 0
	v_mov_b32_e32 v205, v204
	v_mov_b32_e32 v217, v216
	s_nop 1
	v_permlane16_swap_b32_e32 v204, v205
	v_permlane16_swap_b32_e32 v216, v217
	s_nop 0
	v_add_f32_e32 v204, v204, v205
	v_add_f32_e32 v216, v216, v217
	v_mov_b32_e32 v205, v204
	v_mov_b32_e32 v217, v216
	s_nop 1
	v_permlane32_swap_b32_e32 v204, v205
	v_permlane32_swap_b32_e32 v216, v217
	s_nop 0
	v_add_f32_e32 v204, v204, v205
	v_add_f32_e32 v216, v216, v217
	v_mul_f32_e32 v212, 0x3a800000, v204
	v_mul_f32_e32 v224, 0x3a800000, v216
	v_pk_add_f32 v[0:1], v[0:1], v[212:213] op_sel_hi:[1,0] neg_lo:[0,1] neg_hi:[0,1]
	v_pk_add_f32 v[2:3], v[2:3], v[212:213] op_sel_hi:[1,0] neg_lo:[0,1] neg_hi:[0,1]
	v_pk_add_f32 v[4:5], v[4:5], v[212:213] op_sel_hi:[1,0] neg_lo:[0,1] neg_hi:[0,1]
	v_pk_add_f32 v[6:7], v[6:7], v[212:213] op_sel_hi:[1,0] neg_lo:[0,1] neg_hi:[0,1]
	v_pk_add_f32 v[8:9], v[8:9], v[212:213] op_sel_hi:[1,0] neg_lo:[0,1] neg_hi:[0,1]
	v_pk_add_f32 v[10:11], v[10:11], v[212:213] op_sel_hi:[1,0] neg_lo:[0,1] neg_hi:[0,1]
	v_pk_add_f32 v[12:13], v[12:13], v[212:213] op_sel_hi:[1,0] neg_lo:[0,1] neg_hi:[0,1]
	v_pk_add_f32 v[14:15], v[14:15], v[212:213] op_sel_hi:[1,0] neg_lo:[0,1] neg_hi:[0,1]
	v_pk_add_f32 v[16:17], v[16:17], v[224:225] op_sel_hi:[1,0] neg_lo:[0,1] neg_hi:[0,1]
	v_pk_add_f32 v[18:19], v[18:19], v[224:225] op_sel_hi:[1,0] neg_lo:[0,1] neg_hi:[0,1]
	v_pk_add_f32 v[20:21], v[20:21], v[224:225] op_sel_hi:[1,0] neg_lo:[0,1] neg_hi:[0,1]
	v_pk_add_f32 v[22:23], v[22:23], v[224:225] op_sel_hi:[1,0] neg_lo:[0,1] neg_hi:[0,1]
	v_pk_add_f32 v[24:25], v[24:25], v[224:225] op_sel_hi:[1,0] neg_lo:[0,1] neg_hi:[0,1]
	v_pk_add_f32 v[26:27], v[26:27], v[224:225] op_sel_hi:[1,0] neg_lo:[0,1] neg_hi:[0,1]
	v_pk_add_f32 v[28:29], v[28:29], v[224:225] op_sel_hi:[1,0] neg_lo:[0,1] neg_hi:[0,1]
	v_pk_add_f32 v[30:31], v[30:31], v[224:225] op_sel_hi:[1,0] neg_lo:[0,1] neg_hi:[0,1]
	v_pk_mul_f32 v[204:205], v[0:1], v[0:1]
	v_pk_mul_f32 v[206:207], v[2:3], v[2:3]
	v_pk_mul_f32 v[216:217], v[16:17], v[16:17]
	v_pk_mul_f32 v[218:219], v[18:19], v[18:19]
	v_pk_fma_f32 v[204:205], v[4:5], v[4:5], v[204:205]
	v_pk_fma_f32 v[206:207], v[6:7], v[6:7], v[206:207]
	v_pk_fma_f32 v[216:217], v[20:21], v[20:21], v[216:217]
	v_pk_fma_f32 v[218:219], v[22:23], v[22:23], v[218:219]
	v_pk_fma_f32 v[204:205], v[8:9], v[8:9], v[204:205]
	v_pk_fma_f32 v[206:207], v[10:11], v[10:11], v[206:207]
	v_pk_fma_f32 v[216:217], v[24:25], v[24:25], v[216:217]
	v_pk_fma_f32 v[218:219], v[26:27], v[26:27], v[218:219]
	v_pk_fma_f32 v[204:205], v[12:13], v[12:13], v[204:205]
	v_pk_fma_f32 v[206:207], v[14:15], v[14:15], v[206:207]
	v_pk_fma_f32 v[216:217], v[28:29], v[28:29], v[216:217]
	v_pk_fma_f32 v[218:219], v[30:31], v[30:31], v[218:219]
	v_pk_add_f32 v[204:205], v[204:205], v[206:207]
	v_pk_add_f32 v[216:217], v[216:217], v[218:219]
	v_add_f32_e32 v204, v204, v205
	v_add_f32_e32 v216, v216, v217
	s_nop 1
	v_add_f32_dpp v204, v204, v204 row_ror:1 row_mask:0xf bank_mask:0xf bound_ctrl:1
	v_add_f32_dpp v216, v216, v216 row_ror:1 row_mask:0xf bank_mask:0xf bound_ctrl:1
	s_nop 0
	v_add_f32_dpp v204, v204, v204 row_ror:2 row_mask:0xf bank_mask:0xf bound_ctrl:1
	v_add_f32_dpp v216, v216, v216 row_ror:2 row_mask:0xf bank_mask:0xf bound_ctrl:1
	s_nop 0
	v_add_f32_dpp v204, v204, v204 row_ror:4 row_mask:0xf bank_mask:0xf bound_ctrl:1
	v_add_f32_dpp v216, v216, v216 row_ror:4 row_mask:0xf bank_mask:0xf bound_ctrl:1
	s_nop 0
	v_add_f32_dpp v204, v204, v204 row_ror:8 row_mask:0xf bank_mask:0xf bound_ctrl:1
	v_add_f32_dpp v216, v216, v216 row_ror:8 row_mask:0xf bank_mask:0xf bound_ctrl:1
	s_nop 0
	v_mov_b32_e32 v205, v204
	v_mov_b32_e32 v217, v216
	s_nop 1
	v_permlane16_swap_b32_e32 v204, v205
	v_permlane16_swap_b32_e32 v216, v217
	s_nop 0
	v_add_f32_e32 v204, v204, v205
	v_add_f32_e32 v216, v216, v217
	v_mov_b32_e32 v205, v204
	v_mov_b32_e32 v217, v216
	s_nop 1
	v_permlane32_swap_b32_e32 v204, v205
	v_permlane32_swap_b32_e32 v216, v217
	s_nop 0
	v_add_f32_e32 v204, v204, v205
	v_add_f32_e32 v216, v216, v217
	v_mov_b32_e32 v205, 0x3727c5ac
	v_fmac_f32_e32 v205, 0x3a800000, v204
	v_mov_b32_e32 v217, 0x3727c5ac
	v_fmac_f32_e32 v217, 0x3a800000, v216
	v_mul_f32_e32 v206, 0x4b800000, v205
	s_mov_b32 s4, 0x800000
	v_cmp_gt_f32_e32 vcc, s4, v205
	s_nop 1
	v_cndmask_b32_e32 v205, v205, v206, vcc
	v_rsq_f32_e32 v205, v205
	s_nop 0
	v_mul_f32_e32 v206, 0x45800000, v205
	v_cndmask_b32_e32 v214, v205, v206, vcc
	v_mul_f32_e32 v218, 0x4b800000, v217
	s_mov_b32 s4, 0x800000
	v_cmp_gt_f32_e32 vcc, s4, v217
	s_nop 1
	v_cndmask_b32_e32 v217, v217, v218, vcc
	v_rsq_f32_e32 v217, v217
	s_nop 0
	v_mul_f32_e32 v218, 0x45800000, v217
	v_cndmask_b32_e32 v226, v217, v218, vcc
	v_pk_mul_f32 v[0:1], v[0:1], v[214:215] op_sel_hi:[1,0]
	v_pk_mul_f32 v[2:3], v[2:3], v[214:215] op_sel_hi:[1,0]
	v_pk_mul_f32 v[4:5], v[4:5], v[214:215] op_sel_hi:[1,0]
	v_pk_mul_f32 v[6:7], v[6:7], v[214:215] op_sel_hi:[1,0]
	v_pk_mul_f32 v[8:9], v[8:9], v[214:215] op_sel_hi:[1,0]
	v_pk_mul_f32 v[10:11], v[10:11], v[214:215] op_sel_hi:[1,0]
	v_pk_mul_f32 v[12:13], v[12:13], v[214:215] op_sel_hi:[1,0]
	v_pk_mul_f32 v[14:15], v[14:15], v[214:215] op_sel_hi:[1,0]
	v_pk_mul_f32 v[16:17], v[16:17], v[226:227] op_sel_hi:[1,0]
	v_pk_mul_f32 v[18:19], v[18:19], v[226:227] op_sel_hi:[1,0]
	v_pk_mul_f32 v[20:21], v[20:21], v[226:227] op_sel_hi:[1,0]
	v_pk_mul_f32 v[22:23], v[22:23], v[226:227] op_sel_hi:[1,0]
	v_pk_mul_f32 v[24:25], v[24:25], v[226:227] op_sel_hi:[1,0]
	v_pk_mul_f32 v[26:27], v[26:27], v[226:227] op_sel_hi:[1,0]
	v_pk_mul_f32 v[28:29], v[28:29], v[226:227] op_sel_hi:[1,0]
	v_pk_mul_f32 v[30:31], v[30:31], v[226:227] op_sel_hi:[1,0]
	v_pk_fma_f32 v[0:1], v[136:137], v[0:1], v[152:153]
	v_pk_fma_f32 v[2:3], v[138:139], v[2:3], v[154:155]
	v_pk_fma_f32 v[4:5], v[140:141], v[4:5], v[156:157]
	v_pk_fma_f32 v[6:7], v[142:143], v[6:7], v[158:159]
	v_pk_fma_f32 v[8:9], v[144:145], v[8:9], v[160:161]
	v_pk_fma_f32 v[10:11], v[146:147], v[10:11], v[162:163]
	v_pk_fma_f32 v[12:13], v[148:149], v[12:13], v[164:165]
	v_pk_fma_f32 v[14:15], v[150:151], v[14:15], v[166:167]
	v_pk_fma_f32 v[16:17], v[136:137], v[16:17], v[152:153]
	v_pk_fma_f32 v[18:19], v[138:139], v[18:19], v[154:155]
	v_pk_fma_f32 v[20:21], v[140:141], v[20:21], v[156:157]
	v_pk_fma_f32 v[22:23], v[142:143], v[22:23], v[158:159]
	v_pk_fma_f32 v[24:25], v[144:145], v[24:25], v[160:161]
	v_pk_fma_f32 v[26:27], v[146:147], v[26:27], v[162:163]
	v_pk_fma_f32 v[28:29], v[148:149], v[28:29], v[164:165]
	v_pk_fma_f32 v[30:31], v[150:151], v[30:31], v[166:167]
	v_mov_b32_e32 v228, v212
	v_mov_b32_e32 v229, v214
	v_mov_b32_e32 v168, v224
	v_mov_b32_e32 v169, v226
	s_cmp_eq_u32 s57, 1
	s_cbranch_scc1 .Llna_last2
	v_add_f32_e32 v80, 1.0, v80
	v_add_f32_e32 v81, 1.0, v81
	v_add_f32_e32 v82, 1.0, v82
	v_add_f32_e32 v83, 1.0, v83
	v_add_f32_e32 v84, 1.0, v84
	v_add_f32_e32 v85, 1.0, v85
	v_add_f32_e32 v86, 1.0, v86
	v_add_f32_e32 v87, 1.0, v87
	v_add_f32_e32 v88, 1.0, v88
	v_add_f32_e32 v89, 1.0, v89
	v_add_f32_e32 v90, 1.0, v90
	v_add_f32_e32 v91, 1.0, v91
	v_add_f32_e32 v92, 1.0, v92
	v_add_f32_e32 v93, 1.0, v93
	v_add_f32_e32 v94, 1.0, v94
	v_add_f32_e32 v95, 1.0, v95
	v_pk_fma_f32 v[204:205], v[80:81], v[0:1], v[64:65]
	v_pk_fma_f32 v[206:207], v[82:83], v[2:3], v[66:67]
	v_pk_fma_f32 v[208:209], v[84:85], v[4:5], v[68:69]
	v_pk_fma_f32 v[210:211], v[86:87], v[6:7], v[70:71]
	v_pk_fma_f32 v[212:213], v[88:89], v[8:9], v[72:73]
	v_pk_fma_f32 v[214:215], v[90:91], v[10:11], v[74:75]
	v_pk_fma_f32 v[216:217], v[92:93], v[12:13], v[76:77]
	v_pk_fma_f32 v[218:219], v[94:95], v[14:15], v[78:79]
	v_cvt_pk_bf16_f32 v220, v204, v205
	v_cvt_pk_bf16_f32 v221, v206, v207
	v_cvt_pk_bf16_f32 v222, v208, v209
	v_cvt_pk_bf16_f32 v223, v210, v211
	v_cvt_pk_bf16_f32 v224, v212, v213
	v_cvt_pk_bf16_f32 v225, v214, v215
	v_cvt_pk_bf16_f32 v226, v216, v217
	v_cvt_pk_bf16_f32 v227, v218, v219
	s_mul_i32 s4, s6, 0x880
	s_add_u32 s4, s4, 0xf266000
	s_add_u32 s4, s4, s8
	s_addc_u32 s5, s9, 0
	global_store_dwordx2 v233, v[220:221], s[4:5]
	global_store_dwordx2 v233, v[222:223], s[4:5] offset:512
	global_store_dwordx2 v233, v[224:225], s[4:5] offset:1024
	global_store_dwordx2 v233, v[226:227], s[4:5] offset:1536
	s_mov_b64 s[12:13], exec
	s_mov_b64 exec, 1
	global_store_dwordx2 v129, v[228:229], s[4:5] offset:2048
	s_mov_b64 exec, s[12:13]
	v_pk_fma_f32 v[204:205], v[80:81], v[16:17], v[64:65]
	v_pk_fma_f32 v[206:207], v[82:83], v[18:19], v[66:67]
	v_pk_fma_f32 v[208:209], v[84:85], v[20:21], v[68:69]
	v_pk_fma_f32 v[210:211], v[86:87], v[22:23], v[70:71]
	v_pk_fma_f32 v[212:213], v[88:89], v[24:25], v[72:73]
	v_pk_fma_f32 v[214:215], v[90:91], v[26:27], v[74:75]
	v_pk_fma_f32 v[216:217], v[92:93], v[28:29], v[76:77]
	v_pk_fma_f32 v[218:219], v[94:95], v[30:31], v[78:79]
	v_cvt_pk_bf16_f32 v220, v204, v205
	v_cvt_pk_bf16_f32 v221, v206, v207
	v_cvt_pk_bf16_f32 v222, v208, v209
	v_cvt_pk_bf16_f32 v223, v210, v211
	v_cvt_pk_bf16_f32 v224, v212, v213
	v_cvt_pk_bf16_f32 v225, v214, v215
	v_cvt_pk_bf16_f32 v226, v216, v217
	v_cvt_pk_bf16_f32 v227, v218, v219
	s_mul_i32 s4, s6, 0x880
	s_add_u32 s4, s4, 0xf6a6000
	s_add_u32 s4, s4, s8
	s_addc_u32 s5, s9, 0
	global_store_dwordx2 v233, v[220:221], s[4:5]
	global_store_dwordx2 v233, v[222:223], s[4:5] offset:512
	global_store_dwordx2 v233, v[224:225], s[4:5] offset:1024
	global_store_dwordx2 v233, v[226:227], s[4:5] offset:1536
	s_mov_b64 s[12:13], exec
	s_mov_b64 exec, 1
	global_store_dwordx2 v129, v[168:169], s[4:5] offset:2048
	s_mov_b64 exec, s[12:13]
	s_branch .Llna_join2
.Llna_last2:
	s_lshl_b32 s4, s6, 12
	s_add_u32 s4, s4, 0x2000000
	s_add_u32 s4, s4, s88
	s_addc_u32 s5, s89, 0
	global_store_dwordx4 v232, v[0:3], s[4:5]
	global_store_dwordx4 v232, v[4:7], s[4:5] offset:1024
	global_store_dwordx4 v232, v[8:11], s[4:5] offset:2048
	global_store_dwordx4 v232, v[12:15], s[4:5] offset:3072
	s_lshl_b32 s4, s6, 12
	s_add_u32 s4, s4, 0x2800000
	s_add_u32 s4, s4, s88
	s_addc_u32 s5, s89, 0
	global_store_dwordx4 v232, v[16:19], s[4:5]
	global_store_dwordx4 v232, v[20:23], s[4:5] offset:1024
	global_store_dwordx4 v232, v[24:27], s[4:5] offset:2048
	global_store_dwordx4 v232, v[28:31], s[4:5] offset:3072

.Llna_orig:
	v_readlane_b32 s54, v235, 46
	s_sub_i32 s34, s54, 38
	s_cmp_gt_u32 s34, 11
	v_readlane_b32 s58, v235, 34
	v_readlane_b32 s4, v235, 44
	s_cselect_b64 s[50:51], -1, 0
	v_readlane_b32 s59, v235, 35
	s_add_u32 s74, s58, 0xb166000
	s_mul_i32 s34, s4, 3
	s_addc_u32 s75, s59, 0
	s_ashr_i32 s35, s34, 31
	v_readlane_b32 s5, v235, 45
	s_lshl_b64 s[34:35], s[34:35], 12
	s_mov_b32 s56, s4
	s_add_u32 s36, s34, 0x2000
	v_readlane_b32 s4, v237, 19
	s_addc_u32 s37, s35, 0
	v_readlane_b32 s10, v237, 25
	v_readlane_b32 s11, v237, 26
	s_add_u32 s34, s10, s36
	v_lshlrev_b32_e32 v0, 2, v33
	v_readlane_b32 s12, v237, 27
	s_addc_u32 s35, s11, s37
	v_and_b32_e32 v136, 0xfc, v0
	v_readlane_b32 s13, v237, 28
	s_add_u32 s36, s12, s36
	v_lshlrev_b32_e32 v128, 2, v136
	s_addc_u32 s37, s13, s37
	global_load_dwordx4 v[0:3], v128, s[34:35]
	global_load_dwordx4 v[4:7], v128, s[34:35] offset:1024
	global_load_dwordx4 v[8:11], v128, s[36:37]
	global_load_dwordx4 v[12:15], v128, s[36:37] offset:1024
	global_load_dwordx4 v[16:19], v128, s[34:35] offset:2048
	global_load_dwordx4 v[20:23], v128, s[34:35] offset:3072
	global_load_dwordx4 v[24:27], v128, s[36:37] offset:2048
	global_load_dwordx4 v[28:31], v128, s[36:37] offset:3072
	v_readlane_b32 s5, v237, 20
	s_cmp_lt_i32 s54, 38
	v_readlane_b32 s6, v237, 21
	v_readlane_b32 s7, v237, 22
	s_cselect_b64 s[34:35], -1, 0
	v_lshl_add_u64 v[36:37], s[58:59], 0, v[128:129]
	s_mov_b64 s[4:5], 0x14ae6000
	s_cmp_lg_u64 s[34:35], 0
	v_lshl_add_u64 v[140:141], v[36:37], 0, s[4:5]
	s_mov_b64 s[6:7], s[88:89]
	v_and_b32_e32 v36, 63, v33
	s_addc_u32 s34, s56, 0
	v_lshl_add_u64 v[138:139], s[74:75], 0, v[128:129]
	v_lshl_add_u64 v[142:143], s[6:7], 0, v[128:129]
	v_readlane_b32 s4, v235, 18
	v_ashrrev_i32_e32 v33, 31, v32
	v_lshlrev_b32_e32 v128, 3, v36
	v_readlane_b32 s55, v235, 47
	s_add_u32 s54, s58, 0xb0f8000
	s_mul_i32 s56, s34, 3
	v_add_u32_e32 v144, s4, v34
	v_lshlrev_b64 v[34:35], 12, v[32:33]
	v_mad_i64_i32 v[32:33], s[34:35], v32, s3, v[128:129]
	s_addc_u32 s55, s59, 0
	v_lshl_add_u64 v[32:33], s[90:91], 0, v[32:33]
	v_lshlrev_b32_e32 v156, 2, v136
	s_ashr_i32 s57, s56, 31
	v_lshlrev_b32_e32 v146, 4, v36
	v_mov_b32_e32 v147, v129
	v_lshl_add_u64 v[148:149], s[74:75], 0, v[34:35]
	v_lshl_add_u64 v[150:151], v[32:33], 0, s[52:53]
	v_lshl_add_u64 v[152:153], s[6:7], 0, v[34:35]
	s_mov_b64 s[58:59], 0
	v_mov_b64_e32 v[154:155], s[54:55]
	v_mov_b32_e32 v158, v156
	v_mov_b32_e32 v159, v129
	v_readlane_b32 s8, v237, 23
	v_readlane_b32 s9, v237, 24
	v_readlane_b32 s14, v237, 29
	v_readlane_b32 s15, v237, 30
	v_readlane_b32 s16, v237, 31
	v_readlane_b32 s17, v237, 32
	v_readlane_b32 s18, v237, 33
	v_readlane_b32 s19, v237, 34
	s_branch .LBB0_46

.LBB0_90:
	v_readlane_b32 s2, v235, 48
	s_cmp_lt_i32 s2, 7
	s_mov_b64 s[34:35], -1
	s_cbranch_scc1 .LBB0_121
	v_readlane_b32 s2, v235, 48
	s_cmp_gt_i32 s2, 7
	s_cbranch_scc0 .LBB0_104
	s_waitcnt lgkmcnt(0)
	v_mov_b32_e32 v34, v170
	v_mov_b32_e32 v0, v170
	v_readlane_b32 s4, v235, 17
	v_ashrrev_i32_e32 v33, 6, v0
	s_nop 0
	v_add_u32_e32 v32, s4, v33
	s_movk_i32 s4, 0x3000
	v_cmp_gt_i32_e32 vcc, s4, v32
	s_and_saveexec_b64 s[36:37], vcc
	s_cbranch_execz .LBB0_103
	v_readlane_b32 s4, v235, 33
	s_cmp_lg_u32 s4, 0x200
	s_cbranch_scc1 .Llnb_orig
	v_and_b32_e32 v232, 63, v170
	v_lshlrev_b32_e32 v233, 3, v232
	v_lshlrev_b32_e32 v232, 4, v232
	v_lshrrev_b32_e32 v231, 6, v170
	s_nop 0
	v_readfirstlane_b32 s6, v231
	v_readlane_b32 s7, v237, 0
	s_lshl_b32 s7, s7, 2
	s_add_u32 s6, s6, s7
	v_readlane_b32 s8, v235, 34
	v_readlane_b32 s9, v235, 35
	v_readlane_b32 s7, v235, 44
	s_mul_i32 s10, s7, 3
	s_add_u32 s10, s10, 1
	s_lshl_b32 s10, s10, 12
	v_readlane_b32 s4, v237, 25
	v_readlane_b32 s5, v237, 26
	s_add_u32 s4, s4, s10
	s_addc_u32 s5, s5, 0
	global_load_dwordx4 v[136:139], v232, s[4:5]
	global_load_dwordx4 v[140:143], v232, s[4:5] offset:1024
	global_load_dwordx4 v[144:147], v232, s[4:5] offset:2048
	global_load_dwordx4 v[148:151], v232, s[4:5] offset:3072
	v_readlane_b32 s4, v237, 27
	v_readlane_b32 s5, v237, 28
	s_add_u32 s4, s4, s10
	s_addc_u32 s5, s5, 0
	global_load_dwordx4 v[152:155], v232, s[4:5]
	global_load_dwordx4 v[156:159], v232, s[4:5] offset:1024
	global_load_dwordx4 v[160:163], v232, s[4:5] offset:2048
	global_load_dwordx4 v[164:167], v232, s[4:5] offset:3072
	s_mov_b32 s11, s7
	s_mul_i32 s11, s11, 0x1b000
	s_add_u32 s11, s11, 0xb0fe000
	s_add_u32 s10, s8, s11
	s_addc_u32 s11, s9, 0
	s_add_u32 s4, s10, 0x0
	s_addc_u32 s5, s11, 0
	global_load_dwordx4 v[64:67], v232, s[4:5]
	global_load_dwordx4 v[68:71], v232, s[4:5] offset:1024
	global_load_dwordx4 v[72:75], v232, s[4:5] offset:2048
	global_load_dwordx4 v[76:79], v232, s[4:5] offset:3072
	s_add_u32 s4, s4, 0x1000
	s_addc_u32 s5, s5, 0
	global_load_dwordx4 v[80:83], v232, s[4:5]
	global_load_dwordx4 v[84:87], v232, s[4:5] offset:1024
	global_load_dwordx4 v[88:91], v232, s[4:5] offset:2048
	global_load_dwordx4 v[92:95], v232, s[4:5] offset:3072
	s_lshl_b32 s4, s6, 12
	s_add_u32 s4, s4, 0xb166000
	s_add_u32 s4, s4, s8
	s_addc_u32 s5, s9, 0
	global_load_dwordx4 v[0:3], v232, s[4:5]
	global_load_dwordx4 v[4:7], v232, s[4:5] offset:1024
	global_load_dwordx4 v[8:11], v232, s[4:5] offset:2048
	global_load_dwordx4 v[12:15], v232, s[4:5] offset:3072
	s_lshl_b32 s4, s6, 12
	s_add_u32 s4, s4, 0xb966000
	s_add_u32 s4, s4, s8
	s_addc_u32 s5, s9, 0
	global_load_dwordx4 v[16:19], v232, s[4:5]
	global_load_dwordx4 v[20:23], v232, s[4:5] offset:1024
	global_load_dwordx4 v[24:27], v232, s[4:5] offset:2048
	global_load_dwordx4 v[28:31], v232, s[4:5] offset:3072
	s_lshl_b32 s4, s6, 12
	s_add_u32 s4, s4, 0xc166000
	s_add_u32 s4, s4, s8
	s_addc_u32 s5, s9, 0
	global_load_dwordx4 v[32:35], v232, s[4:5]
	global_load_dwordx4 v[36:39], v232, s[4:5] offset:1024
	global_load_dwordx4 v[40:43], v232, s[4:5] offset:2048
	global_load_dwordx4 v[44:47], v232, s[4:5] offset:3072
	s_lshl_b32 s4, s6, 12
	s_add_u32 s4, s4, 0xc966000
	s_add_u32 s4, s4, s8
	s_addc_u32 s5, s9, 0
	global_load_dwordx4 v[48:51], v232, s[4:5]
	global_load_dwordx4 v[52:55], v232, s[4:5] offset:1024
	global_load_dwordx4 v[56:59], v232, s[4:5] offset:2048
	global_load_dwordx4 v[60:63], v232, s[4:5] offset:3072
	s_add_u32 s4, s10, 0x9000
	s_addc_u32 s5, s11, 0
	global_load_dwordx4 v[96:99], v232, s[4:5]
	global_load_dwordx4 v[100:103], v232, s[4:5] offset:1024
	global_load_dwordx4 v[104:107], v232, s[4:5] offset:2048
	global_load_dwordx4 v[108:111], v232, s[4:5] offset:3072
	s_add_u32 s4, s4, 0x1000
	s_addc_u32 s5, s5, 0
	global_load_dwordx4 v[112:115], v232, s[4:5]
	global_load_dwordx4 v[116:119], v232, s[4:5] offset:1024
	global_load_dwordx4 v[120:123], v232, s[4:5] offset:2048
	global_load_dwordx4 v[124:127], v232, s[4:5] offset:3072
	s_waitcnt vmcnt(16)
	v_pk_add_f32 v[204:205], v[0:1], v[2:3]
	v_pk_add_f32 v[206:207], v[4:5], v[6:7]
	v_pk_add_f32 v[208:209], v[8:9], v[10:11]
	v_pk_add_f32 v[210:211], v[12:13], v[14:15]
	v_pk_add_f32 v[216:217], v[16:17], v[18:19]
	v_pk_add_f32 v[218:219], v[20:21], v[22:23]
	v_pk_add_f32 v[220:221], v[24:25], v[26:27]
	v_pk_add_f32 v[222:223], v[28:29], v[30:31]
	v_pk_add_f32 v[204:205], v[204:205], v[206:207]
	v_pk_add_f32 v[208:209], v[208:209], v[210:211]
	v_pk_add_f32 v[216:217], v[216:217], v[218:219]
	v_pk_add_f32 v[220:221], v[220:221], v[222:223]
	v_pk_add_f32 v[204:205], v[204:205], v[208:209]
	v_pk_add_f32 v[216:217], v[216:217], v[220:221]
	v_add_f32_e32 v204, v204, v205
	v_add_f32_e32 v216, v216, v217
	s_nop 1
	v_add_f32_dpp v204, v204, v204 row_ror:1 row_mask:0xf bank_mask:0xf bound_ctrl:1
	v_add_f32_dpp v216, v216, v216 row_ror:1 row_mask:0xf bank_mask:0xf bound_ctrl:1
	s_nop 0
	v_add_f32_dpp v204, v204, v204 row_ror:2 row_mask:0xf bank_mask:0xf bound_ctrl:1
	v_add_f32_dpp v216, v216, v216 row_ror:2 row_mask:0xf bank_mask:0xf bound_ctrl:1
	s_nop 0
	v_add_f32_dpp v204, v204, v204 row_ror:4 row_mask:0xf bank_mask:0xf bound_ctrl:1
	v_add_f32_dpp v216, v216, v216 row_ror:4 row_mask:0xf bank_mask:0xf bound_ctrl:1
	s_nop 0
	v_add_f32_dpp v204, v204, v204 row_ror:8 row_mask:0xf bank_mask:0xf bound_ctrl:1
	v_add_f32_dpp v216, v216, v216 row_ror:8 row_mask:0xf bank_mask:0xf bound_ctrl:1
	s_nop 0
	v_mov_b32_e32 v205, v204
	v_mov_b32_e32 v217, v216
	s_nop 1
	v_permlane16_swap_b32_e32 v204, v205
	v_permlane16_swap_b32_e32 v216, v217
	s_nop 0
	v_add_f32_e32 v204, v204, v205
	v_add_f32_e32 v216, v216, v217
	v_mov_b32_e32 v205, v204
	v_mov_b32_e32 v217, v216
	s_nop 1
	v_permlane32_swap_b32_e32 v204, v205
	v_permlane32_swap_b32_e32 v216, v217
	s_nop 0
	v_add_f32_e32 v204, v204, v205
	v_add_f32_e32 v216, v216, v217
	v_mul_f32_e32 v212, 0x3a800000, v204
	v_mul_f32_e32 v224, 0x3a800000, v216
	v_pk_add_f32 v[0:1], v[0:1], v[212:213] op_sel_hi:[1,0] neg_lo:[0,1] neg_hi:[0,1]
	v_pk_add_f32 v[2:3], v[2:3], v[212:213] op_sel_hi:[1,0] neg_lo:[0,1] neg_hi:[0,1]
	v_pk_add_f32 v[4:5], v[4:5], v[212:213] op_sel_hi:[1,0] neg_lo:[0,1] neg_hi:[0,1]
	v_pk_add_f32 v[6:7], v[6:7], v[212:213] op_sel_hi:[1,0] neg_lo:[0,1] neg_hi:[0,1]
	v_pk_add_f32 v[8:9], v[8:9], v[212:213] op_sel_hi:[1,0] neg_lo:[0,1] neg_hi:[0,1]
	v_pk_add_f32 v[10:11], v[10:11], v[212:213] op_sel_hi:[1,0] neg_lo:[0,1] neg_hi:[0,1]
	v_pk_add_f32 v[12:13], v[12:13], v[212:213] op_sel_hi:[1,0] neg_lo:[0,1] neg_hi:[0,1]
	v_pk_add_f32 v[14:15], v[14:15], v[212:213] op_sel_hi:[1,0] neg_lo:[0,1] neg_hi:[0,1]
	v_pk_add_f32 v[16:17], v[16:17], v[224:225] op_sel_hi:[1,0] neg_lo:[0,1] neg_hi:[0,1]
	v_pk_add_f32 v[18:19], v[18:19], v[224:225] op_sel_hi:[1,0] neg_lo:[0,1] neg_hi:[0,1]
	v_pk_add_f32 v[20:21], v[20:21], v[224:225] op_sel_hi:[1,0] neg_lo:[0,1] neg_hi:[0,1]
	v_pk_add_f32 v[22:23], v[22:23], v[224:225] op_sel_hi:[1,0] neg_lo:[0,1] neg_hi:[0,1]
	v_pk_add_f32 v[24:25], v[24:25], v[224:225] op_sel_hi:[1,0] neg_lo:[0,1] neg_hi:[0,1]
	v_pk_add_f32 v[26:27], v[26:27], v[224:225] op_sel_hi:[1,0] neg_lo:[0,1] neg_hi:[0,1]
	v_pk_add_f32 v[28:29], v[28:29], v[224:225] op_sel_hi:[1,0] neg_lo:[0,1] neg_hi:[0,1]
	v_pk_add_f32 v[30:31], v[30:31], v[224:225] op_sel_hi:[1,0] neg_lo:[0,1] neg_hi:[0,1]
	v_pk_mul_f32 v[204:205], v[0:1], v[0:1]
	v_pk_mul_f32 v[206:207], v[2:3], v[2:3]
	v_pk_mul_f32 v[216:217], v[16:17], v[16:17]
	v_pk_mul_f32 v[218:219], v[18:19], v[18:19]
	v_pk_fma_f32 v[204:205], v[4:5], v[4:5], v[204:205]
	v_pk_fma_f32 v[206:207], v[6:7], v[6:7], v[206:207]
	v_pk_fma_f32 v[216:217], v[20:21], v[20:21], v[216:217]
	v_pk_fma_f32 v[218:219], v[22:23], v[22:23], v[218:219]
	v_pk_fma_f32 v[204:205], v[8:9], v[8:9], v[204:205]
	v_pk_fma_f32 v[206:207], v[10:11], v[10:11], v[206:207]
	v_pk_fma_f32 v[216:217], v[24:25], v[24:25], v[216:217]
	v_pk_fma_f32 v[218:219], v[26:27], v[26:27], v[218:219]
	v_pk_fma_f32 v[204:205], v[12:13], v[12:13], v[204:205]
	v_pk_fma_f32 v[206:207], v[14:15], v[14:15], v[206:207]
	v_pk_fma_f32 v[216:217], v[28:29], v[28:29], v[216:217]
	v_pk_fma_f32 v[218:219], v[30:31], v[30:31], v[218:219]
	v_pk_add_f32 v[204:205], v[204:205], v[206:207]
	v_pk_add_f32 v[216:217], v[216:217], v[218:219]
	v_add_f32_e32 v204, v204, v205
	v_add_f32_e32 v216, v216, v217
	s_nop 1
	v_add_f32_dpp v204, v204, v204 row_ror:1 row_mask:0xf bank_mask:0xf bound_ctrl:1
	v_add_f32_dpp v216, v216, v216 row_ror:1 row_mask:0xf bank_mask:0xf bound_ctrl:1
	s_nop 0
	v_add_f32_dpp v204, v204, v204 row_ror:2 row_mask:0xf bank_mask:0xf bound_ctrl:1
	v_add_f32_dpp v216, v216, v216 row_ror:2 row_mask:0xf bank_mask:0xf bound_ctrl:1
	s_nop 0
	v_add_f32_dpp v204, v204, v204 row_ror:4 row_mask:0xf bank_mask:0xf bound_ctrl:1
	v_add_f32_dpp v216, v216, v216 row_ror:4 row_mask:0xf bank_mask:0xf bound_ctrl:1
	s_nop 0
	v_add_f32_dpp v204, v204, v204 row_ror:8 row_mask:0xf bank_mask:0xf bound_ctrl:1
	v_add_f32_dpp v216, v216, v216 row_ror:8 row_mask:0xf bank_mask:0xf bound_ctrl:1
	s_nop 0
	v_mov_b32_e32 v205, v204
	v_mov_b32_e32 v217, v216
	s_nop 1
	v_permlane16_swap_b32_e32 v204, v205
	v_permlane16_swap_b32_e32 v216, v217
	s_nop 0
	v_add_f32_e32 v204, v204, v205
	v_add_f32_e32 v216, v216, v217
	v_mov_b32_e32 v205, v204
	v_mov_b32_e32 v217, v216
	s_nop 1
	v_permlane32_swap_b32_e32 v204, v205
	v_permlane32_swap_b32_e32 v216, v217
	s_nop 0
	v_add_f32_e32 v204, v204, v205
	v_add_f32_e32 v216, v216, v217
	v_mov_b32_e32 v205, 0x3727c5ac
	v_fmac_f32_e32 v205, 0x3a800000, v204
	v_mov_b32_e32 v217, 0x3727c5ac
	v_fmac_f32_e32 v217, 0x3a800000, v216
	v_mul_f32_e32 v206, 0x4b800000, v205
	s_mov_b32 s4, 0x800000
	v_cmp_gt_f32_e32 vcc, s4, v205
	s_nop 1
	v_cndmask_b32_e32 v205, v205, v206, vcc
	v_rsq_f32_e32 v205, v205
	s_nop 0
	v_mul_f32_e32 v206, 0x45800000, v205
	v_cndmask_b32_e32 v214, v205, v206, vcc
	v_mul_f32_e32 v218, 0x4b800000, v217
	s_mov_b32 s4, 0x800000
	v_cmp_gt_f32_e32 vcc, s4, v217
	s_nop 1
	v_cndmask_b32_e32 v217, v217, v218, vcc
	v_rsq_f32_e32 v217, v217
	s_nop 0
	v_mul_f32_e32 v218, 0x45800000, v217
	v_cndmask_b32_e32 v226, v217, v218, vcc
	v_pk_mul_f32 v[0:1], v[0:1], v[214:215] op_sel_hi:[1,0]
	v_pk_mul_f32 v[2:3], v[2:3], v[214:215] op_sel_hi:[1,0]
	v_pk_mul_f32 v[4:5], v[4:5], v[214:215] op_sel_hi:[1,0]
	v_pk_mul_f32 v[6:7], v[6:7], v[214:215] op_sel_hi:[1,0]
	v_pk_mul_f32 v[8:9], v[8:9], v[214:215] op_sel_hi:[1,0]
	v_pk_mul_f32 v[10:11], v[10:11], v[214:215] op_sel_hi:[1,0]
	v_pk_mul_f32 v[12:13], v[12:13], v[214:215] op_sel_hi:[1,0]
	v_pk_mul_f32 v[14:15], v[14:15], v[214:215] op_sel_hi:[1,0]
	v_pk_mul_f32 v[16:17], v[16:17], v[226:227] op_sel_hi:[1,0]
	v_pk_mul_f32 v[18:19], v[18:19], v[226:227] op_sel_hi:[1,0]
	v_pk_mul_f32 v[20:21], v[20:21], v[226:227] op_sel_hi:[1,0]
	v_pk_mul_f32 v[22:23], v[22:23], v[226:227] op_sel_hi:[1,0]
	v_pk_mul_f32 v[24:25], v[24:25], v[226:227] op_sel_hi:[1,0]
	v_pk_mul_f32 v[26:27], v[26:27], v[226:227] op_sel_hi:[1,0]
	v_pk_mul_f32 v[28:29], v[28:29], v[226:227] op_sel_hi:[1,0]
	v_pk_mul_f32 v[30:31], v[30:31], v[226:227] op_sel_hi:[1,0]
	v_pk_fma_f32 v[0:1], v[136:137], v[0:1], v[152:153]
	v_pk_fma_f32 v[2:3], v[138:139], v[2:3], v[154:155]
	v_pk_fma_f32 v[4:5], v[140:141], v[4:5], v[156:157]
	v_pk_fma_f32 v[6:7], v[142:143], v[6:7], v[158:159]
	v_pk_fma_f32 v[8:9], v[144:145], v[8:9], v[160:161]
	v_pk_fma_f32 v[10:11], v[146:147], v[10:11], v[162:163]
	v_pk_fma_f32 v[12:13], v[148:149], v[12:13], v[164:165]
	v_pk_fma_f32 v[14:15], v[150:151], v[14:15], v[166:167]
	v_pk_fma_f32 v[16:17], v[136:137], v[16:17], v[152:153]
	v_pk_fma_f32 v[18:19], v[138:139], v[18:19], v[154:155]
	v_pk_fma_f32 v[20:21], v[140:141], v[20:21], v[156:157]
	v_pk_fma_f32 v[22:23], v[142:143], v[22:23], v[158:159]
	v_pk_fma_f32 v[24:25], v[144:145], v[24:25], v[160:161]
	v_pk_fma_f32 v[26:27], v[146:147], v[26:27], v[162:163]
	v_pk_fma_f32 v[28:29], v[148:149], v[28:29], v[164:165]
	v_pk_fma_f32 v[30:31], v[150:151], v[30:31], v[166:167]
	v_mov_b32_e32 v228, v212
	v_mov_b32_e32 v229, v214
	v_mov_b32_e32 v168, v224
	v_mov_b32_e32 v169, v226
	v_add_f32_e32 v80, 1.0, v80
	v_add_f32_e32 v81, 1.0, v81
	v_add_f32_e32 v82, 1.0, v82
	v_add_f32_e32 v83, 1.0, v83
	v_add_f32_e32 v84, 1.0, v84
	v_add_f32_e32 v85, 1.0, v85
	v_add_f32_e32 v86, 1.0, v86
	v_add_f32_e32 v87, 1.0, v87
	v_add_f32_e32 v88, 1.0, v88
	v_add_f32_e32 v89, 1.0, v89
	v_add_f32_e32 v90, 1.0, v90
	v_add_f32_e32 v91, 1.0, v91
	v_add_f32_e32 v92, 1.0, v92
	v_add_f32_e32 v93, 1.0, v93
	v_add_f32_e32 v94, 1.0, v94
	v_add_f32_e32 v95, 1.0, v95
	v_pk_fma_f32 v[204:205], v[80:81], v[0:1], v[64:65]
	v_pk_fma_f32 v[206:207], v[82:83], v[2:3], v[66:67]
	v_pk_fma_f32 v[208:209], v[84:85], v[4:5], v[68:69]
	v_pk_fma_f32 v[210:211], v[86:87], v[6:7], v[70:71]
	v_pk_fma_f32 v[212:213], v[88:89], v[8:9], v[72:73]
	v_pk_fma_f32 v[214:215], v[90:91], v[10:11], v[74:75]
	v_pk_fma_f32 v[216:217], v[92:93], v[12:13], v[76:77]
	v_pk_fma_f32 v[218:219], v[94:95], v[14:15], v[78:79]
	v_cvt_pk_bf16_f32 v220, v204, v205
	v_cvt_pk_bf16_f32 v221, v206, v207
	v_cvt_pk_bf16_f32 v222, v208, v209
	v_cvt_pk_bf16_f32 v223, v210, v211
	v_cvt_pk_bf16_f32 v224, v212, v213
	v_cvt_pk_bf16_f32 v225, v214, v215
	v_cvt_pk_bf16_f32 v226, v216, v217
	v_cvt_pk_bf16_f32 v227, v218, v219
	s_mul_i32 s4, s6, 0x880
	s_add_u32 s4, s4, 0xe166000
	s_add_u32 s4, s4, s8
	s_addc_u32 s5, s9, 0
	global_store_dwordx2 v233, v[220:221], s[4:5]
	global_store_dwordx2 v233, v[222:223], s[4:5] offset:512
	global_store_dwordx2 v233, v[224:225], s[4:5] offset:1024
	global_store_dwordx2 v233, v[226:227], s[4:5] offset:1536
	s_mov_b64 s[12:13], exec
	s_mov_b64 exec, 1
	global_store_dwordx2 v129, v[228:229], s[4:5] offset:2048
	s_mov_b64 exec, s[12:13]
	v_pk_fma_f32 v[204:205], v[80:81], v[16:17], v[64:65]
	v_pk_fma_f32 v[206:207], v[82:83], v[18:19], v[66:67]
	v_pk_fma_f32 v[208:209], v[84:85], v[20:21], v[68:69]
	v_pk_fma_f32 v[210:211], v[86:87], v[22:23], v[70:71]
	v_pk_fma_f32 v[212:213], v[88:89], v[24:25], v[72:73]
	v_pk_fma_f32 v[214:215], v[90:91], v[26:27], v[74:75]
	v_pk_fma_f32 v[216:217], v[92:93], v[28:29], v[76:77]
	v_pk_fma_f32 v[218:219], v[94:95], v[30:31], v[78:79]
	v_cvt_pk_bf16_f32 v220, v204, v205
	v_cvt_pk_bf16_f32 v221, v206, v207
	v_cvt_pk_bf16_f32 v222, v208, v209
	v_cvt_pk_bf16_f32 v223, v210, v211
	v_cvt_pk_bf16_f32 v224, v212, v213
	v_cvt_pk_bf16_f32 v225, v214, v215
	v_cvt_pk_bf16_f32 v226, v216, v217
	v_cvt_pk_bf16_f32 v227, v218, v219
	s_mul_i32 s4, s6, 0x880
	s_add_u32 s4, s4, 0xe5a6000
	s_add_u32 s4, s4, s8
	s_addc_u32 s5, s9, 0
	global_store_dwordx2 v233, v[220:221], s[4:5]
	global_store_dwordx2 v233, v[222:223], s[4:5] offset:512
	global_store_dwordx2 v233, v[224:225], s[4:5] offset:1024
	global_store_dwordx2 v233, v[226:227], s[4:5] offset:1536
	s_mov_b64 s[12:13], exec
	s_mov_b64 exec, 1
	global_store_dwordx2 v129, v[168:169], s[4:5] offset:2048
	s_mov_b64 exec, s[12:13]
	s_lshl_b32 s4, s6, 12
	s_add_u32 s4, s4, 0xd166000
	s_add_u32 s4, s4, s8
	s_addc_u32 s5, s9, 0
	global_load_dwordx4 v[0:3], v232, s[4:5]
	global_load_dwordx4 v[4:7], v232, s[4:5] offset:1024
	global_load_dwordx4 v[8:11], v232, s[4:5] offset:2048
	global_load_dwordx4 v[12:15], v232, s[4:5] offset:3072
	s_lshl_b32 s4, s6, 12
	s_add_u32 s4, s4, 0xd966000
	s_add_u32 s4, s4, s8
	s_addc_u32 s5, s9, 0
	global_load_dwordx4 v[16:19], v232, s[4:5]
	global_load_dwordx4 v[20:23], v232, s[4:5] offset:1024
	global_load_dwordx4 v[24:27], v232, s[4:5] offset:2048
	global_load_dwordx4 v[28:31], v232, s[4:5] offset:3072
	s_add_u32 s4, s10, 0x12000
	s_addc_u32 s5, s11, 0
	global_load_dwordx4 v[64:67], v232, s[4:5]
	global_load_dwordx4 v[68:71], v232, s[4:5] offset:1024
	global_load_dwordx4 v[72:75], v232, s[4:5] offset:2048
	global_load_dwordx4 v[76:79], v232, s[4:5] offset:3072
	s_add_u32 s4, s4, 0x1000
	s_addc_u32 s5, s5, 0
	global_load_dwordx4 v[80:83], v232, s[4:5]
	global_load_dwordx4 v[84:87], v232, s[4:5] offset:1024
	global_load_dwordx4 v[88:91], v232, s[4:5] offset:2048
	global_load_dwordx4 v[92:95], v232, s[4:5] offset:3072
	s_waitcnt vmcnt(26)
	v_pk_add_f32 v[204:205], v[32:33], v[34:35]
	v_pk_add_f32 v[206:207], v[36:37], v[38:39]
	v_pk_add_f32 v[208:209], v[40:41], v[42:43]
	v_pk_add_f32 v[210:211], v[44:45], v[46:47]
	v_pk_add_f32 v[216:217], v[48:49], v[50:51]
	v_pk_add_f32 v[218:219], v[52:53], v[54:55]
	v_pk_add_f32 v[220:221], v[56:57], v[58:59]
	v_pk_add_f32 v[222:223], v[60:61], v[62:63]
	v_pk_add_f32 v[204:205], v[204:205], v[206:207]
	v_pk_add_f32 v[208:209], v[208:209], v[210:211]
	v_pk_add_f32 v[216:217], v[216:217], v[218:219]
	v_pk_add_f32 v[220:221], v[220:221], v[222:223]
	v_pk_add_f32 v[204:205], v[204:205], v[208:209]
	v_pk_add_f32 v[216:217], v[216:217], v[220:221]
	v_add_f32_e32 v204, v204, v205
	v_add_f32_e32 v216, v216, v217
	s_nop 1
	v_add_f32_dpp v204, v204, v204 row_ror:1 row_mask:0xf bank_mask:0xf bound_ctrl:1
	v_add_f32_dpp v216, v216, v216 row_ror:1 row_mask:0xf bank_mask:0xf bound_ctrl:1
	s_nop 0
	v_add_f32_dpp v204, v204, v204 row_ror:2 row_mask:0xf bank_mask:0xf bound_ctrl:1
	v_add_f32_dpp v216, v216, v216 row_ror:2 row_mask:0xf bank_mask:0xf bound_ctrl:1
	s_nop 0
	v_add_f32_dpp v204, v204, v204 row_ror:4 row_mask:0xf bank_mask:0xf bound_ctrl:1
	v_add_f32_dpp v216, v216, v216 row_ror:4 row_mask:0xf bank_mask:0xf bound_ctrl:1
	s_nop 0
	v_add_f32_dpp v204, v204, v204 row_ror:8 row_mask:0xf bank_mask:0xf bound_ctrl:1
	v_add_f32_dpp v216, v216, v216 row_ror:8 row_mask:0xf bank_mask:0xf bound_ctrl:1
	s_nop 0
	v_mov_b32_e32 v205, v204
	v_mov_b32_e32 v217, v216
	s_nop 1
	v_permlane16_swap_b32_e32 v204, v205
	v_permlane16_swap_b32_e32 v216, v217
	s_nop 0
	v_add_f32_e32 v204, v204, v205
	v_add_f32_e32 v216, v216, v217
	v_mov_b32_e32 v205, v204
	v_mov_b32_e32 v217, v216
	s_nop 1
	v_permlane32_swap_b32_e32 v204, v205
	v_permlane32_swap_b32_e32 v216, v217
	s_nop 0
	v_add_f32_e32 v204, v204, v205
	v_add_f32_e32 v216, v216, v217
	v_mul_f32_e32 v212, 0x3a800000, v204
	v_mul_f32_e32 v224, 0x3a800000, v216
	v_pk_add_f32 v[32:33], v[32:33], v[212:213] op_sel_hi:[1,0] neg_lo:[0,1] neg_hi:[0,1]
	v_pk_add_f32 v[34:35], v[34:35], v[212:213] op_sel_hi:[1,0] neg_lo:[0,1] neg_hi:[0,1]
	v_pk_add_f32 v[36:37], v[36:37], v[212:213] op_sel_hi:[1,0] neg_lo:[0,1] neg_hi:[0,1]
	v_pk_add_f32 v[38:39], v[38:39], v[212:213] op_sel_hi:[1,0] neg_lo:[0,1] neg_hi:[0,1]
	v_pk_add_f32 v[40:41], v[40:41], v[212:213] op_sel_hi:[1,0] neg_lo:[0,1] neg_hi:[0,1]
	v_pk_add_f32 v[42:43], v[42:43], v[212:213] op_sel_hi:[1,0] neg_lo:[0,1] neg_hi:[0,1]
	v_pk_add_f32 v[44:45], v[44:45], v[212:213] op_sel_hi:[1,0] neg_lo:[0,1] neg_hi:[0,1]
	v_pk_add_f32 v[46:47], v[46:47], v[212:213] op_sel_hi:[1,0] neg_lo:[0,1] neg_hi:[0,1]
	v_pk_add_f32 v[48:49], v[48:49], v[224:225] op_sel_hi:[1,0] neg_lo:[0,1] neg_hi:[0,1]
	v_pk_add_f32 v[50:51], v[50:51], v[224:225] op_sel_hi:[1,0] neg_lo:[0,1] neg_hi:[0,1]
	v_pk_add_f32 v[52:53], v[52:53], v[224:225] op_sel_hi:[1,0] neg_lo:[0,1] neg_hi:[0,1]
	v_pk_add_f32 v[54:55], v[54:55], v[224:225] op_sel_hi:[1,0] neg_lo:[0,1] neg_hi:[0,1]
	v_pk_add_f32 v[56:57], v[56:57], v[224:225] op_sel_hi:[1,0] neg_lo:[0,1] neg_hi:[0,1]
	v_pk_add_f32 v[58:59], v[58:59], v[224:225] op_sel_hi:[1,0] neg_lo:[0,1] neg_hi:[0,1]
	v_pk_add_f32 v[60:61], v[60:61], v[224:225] op_sel_hi:[1,0] neg_lo:[0,1] neg_hi:[0,1]
	v_pk_add_f32 v[62:63], v[62:63], v[224:225] op_sel_hi:[1,0] neg_lo:[0,1] neg_hi:[0,1]
	v_pk_mul_f32 v[204:205], v[32:33], v[32:33]
	v_pk_mul_f32 v[206:207], v[34:35], v[34:35]
	v_pk_mul_f32 v[216:217], v[48:49], v[48:49]
	v_pk_mul_f32 v[218:219], v[50:51], v[50:51]
	v_pk_fma_f32 v[204:205], v[36:37], v[36:37], v[204:205]
	v_pk_fma_f32 v[206:207], v[38:39], v[38:39], v[206:207]
	v_pk_fma_f32 v[216:217], v[52:53], v[52:53], v[216:217]
	v_pk_fma_f32 v[218:219], v[54:55], v[54:55], v[218:219]
	v_pk_fma_f32 v[204:205], v[40:41], v[40:41], v[204:205]
	v_pk_fma_f32 v[206:207], v[42:43], v[42:43], v[206:207]
	v_pk_fma_f32 v[216:217], v[56:57], v[56:57], v[216:217]
	v_pk_fma_f32 v[218:219], v[58:59], v[58:59], v[218:219]
	v_pk_fma_f32 v[204:205], v[44:45], v[44:45], v[204:205]
	v_pk_fma_f32 v[206:207], v[46:47], v[46:47], v[206:207]
	v_pk_fma_f32 v[216:217], v[60:61], v[60:61], v[216:217]
	v_pk_fma_f32 v[218:219], v[62:63], v[62:63], v[218:219]
	v_pk_add_f32 v[204:205], v[204:205], v[206:207]
	v_pk_add_f32 v[216:217], v[216:217], v[218:219]
	v_add_f32_e32 v204, v204, v205
	v_add_f32_e32 v216, v216, v217
	s_nop 1
	v_add_f32_dpp v204, v204, v204 row_ror:1 row_mask:0xf bank_mask:0xf bound_ctrl:1
	v_add_f32_dpp v216, v216, v216 row_ror:1 row_mask:0xf bank_mask:0xf bound_ctrl:1
	s_nop 0
	v_add_f32_dpp v204, v204, v204 row_ror:2 row_mask:0xf bank_mask:0xf bound_ctrl:1
	v_add_f32_dpp v216, v216, v216 row_ror:2 row_mask:0xf bank_mask:0xf bound_ctrl:1
	s_nop 0
	v_add_f32_dpp v204, v204, v204 row_ror:4 row_mask:0xf bank_mask:0xf bound_ctrl:1
	v_add_f32_dpp v216, v216, v216 row_ror:4 row_mask:0xf bank_mask:0xf bound_ctrl:1
	s_nop 0
	v_add_f32_dpp v204, v204, v204 row_ror:8 row_mask:0xf bank_mask:0xf bound_ctrl:1
	v_add_f32_dpp v216, v216, v216 row_ror:8 row_mask:0xf bank_mask:0xf bound_ctrl:1
	s_nop 0
	v_mov_b32_e32 v205, v204
	v_mov_b32_e32 v217, v216
	s_nop 1
	v_permlane16_swap_b32_e32 v204, v205
	v_permlane16_swap_b32_e32 v216, v217
	s_nop 0
	v_add_f32_e32 v204, v204, v205
	v_add_f32_e32 v216, v216, v217
	v_mov_b32_e32 v205, v204
	v_mov_b32_e32 v217, v216
	s_nop 1
	v_permlane32_swap_b32_e32 v204, v205
	v_permlane32_swap_b32_e32 v216, v217
	s_nop 0
	v_add_f32_e32 v204, v204, v205
	v_add_f32_e32 v216, v216, v217
	v_mov_b32_e32 v205, 0x3727c5ac
	v_fmac_f32_e32 v205, 0x3a800000, v204
	v_mov_b32_e32 v217, 0x3727c5ac
	v_fmac_f32_e32 v217, 0x3a800000, v216
	v_mul_f32_e32 v206, 0x4b800000, v205
	s_mov_b32 s4, 0x800000
	v_cmp_gt_f32_e32 vcc, s4, v205
	s_nop 1
	v_cndmask_b32_e32 v205, v205, v206, vcc
	v_rsq_f32_e32 v205, v205
	s_nop 0
	v_mul_f32_e32 v206, 0x45800000, v205
	v_cndmask_b32_e32 v214, v205, v206, vcc
	v_mul_f32_e32 v218, 0x4b800000, v217
	s_mov_b32 s4, 0x800000
	v_cmp_gt_f32_e32 vcc, s4, v217
	s_nop 1
	v_cndmask_b32_e32 v217, v217, v218, vcc
	v_rsq_f32_e32 v217, v217
	s_nop 0
	v_mul_f32_e32 v218, 0x45800000, v217
	v_cndmask_b32_e32 v226, v217, v218, vcc
	v_pk_mul_f32 v[32:33], v[32:33], v[214:215] op_sel_hi:[1,0]
	v_pk_mul_f32 v[34:35], v[34:35], v[214:215] op_sel_hi:[1,0]
	v_pk_mul_f32 v[36:37], v[36:37], v[214:215] op_sel_hi:[1,0]
	v_pk_mul_f32 v[38:39], v[38:39], v[214:215] op_sel_hi:[1,0]
	v_pk_mul_f32 v[40:41], v[40:41], v[214:215] op_sel_hi:[1,0]
	v_pk_mul_f32 v[42:43], v[42:43], v[214:215] op_sel_hi:[1,0]
	v_pk_mul_f32 v[44:45], v[44:45], v[214:215] op_sel_hi:[1,0]
	v_pk_mul_f32 v[46:47], v[46:47], v[214:215] op_sel_hi:[1,0]
	v_pk_mul_f32 v[48:49], v[48:49], v[226:227] op_sel_hi:[1,0]
	v_pk_mul_f32 v[50:51], v[50:51], v[226:227] op_sel_hi:[1,0]
	v_pk_mul_f32 v[52:53], v[52:53], v[226:227] op_sel_hi:[1,0]
	v_pk_mul_f32 v[54:55], v[54:55], v[226:227] op_sel_hi:[1,0]
	v_pk_mul_f32 v[56:57], v[56:57], v[226:227] op_sel_hi:[1,0]
	v_pk_mul_f32 v[58:59], v[58:59], v[226:227] op_sel_hi:[1,0]
	v_pk_mul_f32 v[60:61], v[60:61], v[226:227] op_sel_hi:[1,0]
	v_pk_mul_f32 v[62:63], v[62:63], v[226:227] op_sel_hi:[1,0]
	v_pk_fma_f32 v[32:33], v[136:137], v[32:33], v[152:153]
	v_pk_fma_f32 v[34:35], v[138:139], v[34:35], v[154:155]
	v_pk_fma_f32 v[36:37], v[140:141], v[36:37], v[156:157]
	v_pk_fma_f32 v[38:39], v[142:143], v[38:39], v[158:159]
	v_pk_fma_f32 v[40:41], v[144:145], v[40:41], v[160:161]
	v_pk_fma_f32 v[42:43], v[146:147], v[42:43], v[162:163]
	v_pk_fma_f32 v[44:45], v[148:149], v[44:45], v[164:165]
	v_pk_fma_f32 v[46:47], v[150:151], v[46:47], v[166:167]
	v_pk_fma_f32 v[48:49], v[136:137], v[48:49], v[152:153]
	v_pk_fma_f32 v[50:51], v[138:139], v[50:51], v[154:155]
	v_pk_fma_f32 v[52:53], v[140:141], v[52:53], v[156:157]
	v_pk_fma_f32 v[54:55], v[142:143], v[54:55], v[158:159]
	v_pk_fma_f32 v[56:57], v[144:145], v[56:57], v[160:161]
	v_pk_fma_f32 v[58:59], v[146:147], v[58:59], v[162:163]
	v_pk_fma_f32 v[60:61], v[148:149], v[60:61], v[164:165]
	v_pk_fma_f32 v[62:63], v[150:151], v[62:63], v[166:167]
	v_mov_b32_e32 v228, v212
	v_mov_b32_e32 v229, v214
	v_mov_b32_e32 v168, v224
	v_mov_b32_e32 v169, v226
	v_add_f32_e32 v112, 1.0, v112
	v_add_f32_e32 v113, 1.0, v113
	v_add_f32_e32 v114, 1.0, v114
	v_add_f32_e32 v115, 1.0, v115
	v_add_f32_e32 v116, 1.0, v116
	v_add_f32_e32 v117, 1.0, v117
	v_add_f32_e32 v118, 1.0, v118
	v_add_f32_e32 v119, 1.0, v119
	v_add_f32_e32 v120, 1.0, v120
	v_add_f32_e32 v121, 1.0, v121
	v_add_f32_e32 v122, 1.0, v122
	v_add_f32_e32 v123, 1.0, v123
	v_add_f32_e32 v124, 1.0, v124
	v_add_f32_e32 v125, 1.0, v125
	v_add_f32_e32 v126, 1.0, v126
	v_add_f32_e32 v127, 1.0, v127
	v_pk_fma_f32 v[204:205], v[112:113], v[32:33], v[96:97]
	v_pk_fma_f32 v[206:207], v[114:115], v[34:35], v[98:99]
	v_pk_fma_f32 v[208:209], v[116:117], v[36:37], v[100:101]
	v_pk_fma_f32 v[210:211], v[118:119], v[38:39], v[102:103]
	v_pk_fma_f32 v[212:213], v[120:121], v[40:41], v[104:105]
	v_pk_fma_f32 v[214:215], v[122:123], v[42:43], v[106:107]
	v_pk_fma_f32 v[216:217], v[124:125], v[44:45], v[108:109]
	v_pk_fma_f32 v[218:219], v[126:127], v[46:47], v[110:111]
	v_cvt_pk_bf16_f32 v220, v204, v205
	v_cvt_pk_bf16_f32 v221, v206, v207
	v_cvt_pk_bf16_f32 v222, v208, v209
	v_cvt_pk_bf16_f32 v223, v210, v211
	v_cvt_pk_bf16_f32 v224, v212, v213
	v_cvt_pk_bf16_f32 v225, v214, v215
	v_cvt_pk_bf16_f32 v226, v216, v217
	v_cvt_pk_bf16_f32 v227, v218, v219
	s_mul_i32 s4, s6, 0x880
	s_add_u32 s4, s4, 0xe9e6000
	s_add_u32 s4, s4, s8
	s_addc_u32 s5, s9, 0
	global_store_dwordx2 v233, v[220:221], s[4:5]
	global_store_dwordx2 v233, v[222:223], s[4:5] offset:512
	global_store_dwordx2 v233, v[224:225], s[4:5] offset:1024
	global_store_dwordx2 v233, v[226:227], s[4:5] offset:1536
	s_mov_b64 s[12:13], exec
	s_mov_b64 exec, 1
	global_store_dwordx2 v129, v[228:229], s[4:5] offset:2048
	s_mov_b64 exec, s[12:13]
	v_pk_fma_f32 v[204:205], v[112:113], v[48:49], v[96:97]
	v_pk_fma_f32 v[206:207], v[114:115], v[50:51], v[98:99]
	v_pk_fma_f32 v[208:209], v[116:117], v[52:53], v[100:101]
	v_pk_fma_f32 v[210:211], v[118:119], v[54:55], v[102:103]
	v_pk_fma_f32 v[212:213], v[120:121], v[56:57], v[104:105]
	v_pk_fma_f32 v[214:215], v[122:123], v[58:59], v[106:107]
	v_pk_fma_f32 v[216:217], v[124:125], v[60:61], v[108:109]
	v_pk_fma_f32 v[218:219], v[126:127], v[62:63], v[110:111]
	v_cvt_pk_bf16_f32 v220, v204, v205
	v_cvt_pk_bf16_f32 v221, v206, v207
	v_cvt_pk_bf16_f32 v222, v208, v209
	v_cvt_pk_bf16_f32 v223, v210, v211
	v_cvt_pk_bf16_f32 v224, v212, v213
	v_cvt_pk_bf16_f32 v225, v214, v215
	v_cvt_pk_bf16_f32 v226, v216, v217
	v_cvt_pk_bf16_f32 v227, v218, v219
	s_mul_i32 s4, s6, 0x880
	s_add_u32 s4, s4, 0xee26000
	s_add_u32 s4, s4, s8
	s_addc_u32 s5, s9, 0
	global_store_dwordx2 v233, v[220:221], s[4:5]
	global_store_dwordx2 v233, v[222:223], s[4:5] offset:512
	global_store_dwordx2 v233, v[224:225], s[4:5] offset:1024
	global_store_dwordx2 v233, v[226:227], s[4:5] offset:1536
	s_mov_b64 s[12:13], exec
	s_mov_b64 exec, 1
	global_store_dwordx2 v129, v[168:169], s[4:5] offset:2048
	s_mov_b64 exec, s[12:13]
	s_waitcnt vmcnt(10)
	v_pk_add_f32 v[204:205], v[0:1], v[2:3]
	v_pk_add_f32 v[206:207], v[4:5], v[6:7]
	v_pk_add_f32 v[208:209], v[8:9], v[10:11]
	v_pk_add_f32 v[210:211], v[12:13], v[14:15]
	v_pk_add_f32 v[216:217], v[16:17], v[18:19]
	v_pk_add_f32 v[218:219], v[20:21], v[22:23]
	v_pk_add_f32 v[220:221], v[24:25], v[26:27]
	v_pk_add_f32 v[222:223], v[28:29], v[30:31]
	v_pk_add_f32 v[204:205], v[204:205], v[206:207]
	v_pk_add_f32 v[208:209], v[208:209], v[210:211]
	v_pk_add_f32 v[216:217], v[216:217], v[218:219]
	v_pk_add_f32 v[220:221], v[220:221], v[222:223]
	v_pk_add_f32 v[204:205], v[204:205], v[208:209]
	v_pk_add_f32 v[216:217], v[216:217], v[220:221]
	v_add_f32_e32 v204, v204, v205
	v_add_f32_e32 v216, v216, v217
	s_nop 1
	v_add_f32_dpp v204, v204, v204 row_ror:1 row_mask:0xf bank_mask:0xf bound_ctrl:1
	v_add_f32_dpp v216, v216, v216 row_ror:1 row_mask:0xf bank_mask:0xf bound_ctrl:1
	s_nop 0
	v_add_f32_dpp v204, v204, v204 row_ror:2 row_mask:0xf bank_mask:0xf bound_ctrl:1
	v_add_f32_dpp v216, v216, v216 row_ror:2 row_mask:0xf bank_mask:0xf bound_ctrl:1
	s_nop 0
	v_add_f32_dpp v204, v204, v204 row_ror:4 row_mask:0xf bank_mask:0xf bound_ctrl:1
	v_add_f32_dpp v216, v216, v216 row_ror:4 row_mask:0xf bank_mask:0xf bound_ctrl:1
	s_nop 0
	v_add_f32_dpp v204, v204, v204 row_ror:8 row_mask:0xf bank_mask:0xf bound_ctrl:1
	v_add_f32_dpp v216, v216, v216 row_ror:8 row_mask:0xf bank_mask:0xf bound_ctrl:1
	s_nop 0
	v_mov_b32_e32 v205, v204
	v_mov_b32_e32 v217, v216
	s_nop 1
	v_permlane16_swap_b32_e32 v204, v205
	v_permlane16_swap_b32_e32 v216, v217
	s_nop 0
	v_add_f32_e32 v204, v204, v205
	v_add_f32_e32 v216, v216, v217
	v_mov_b32_e32 v205, v204
	v_mov_b32_e32 v217, v216
	s_nop 1
	v_permlane32_swap_b32_e32 v204, v205
	v_permlane32_swap_b32_e32 v216, v217
	s_nop 0
	v_add_f32_e32 v204, v204, v205
	v_add_f32_e32 v216, v216, v217
	v_mul_f32_e32 v212, 0x3a800000, v204
	v_mul_f32_e32 v224, 0x3a800000, v216
	v_pk_add_f32 v[0:1], v[0:1], v[212:213] op_sel_hi:[1,0] neg_lo:[0,1] neg_hi:[0,1]
	v_pk_add_f32 v[2:3], v[2:3], v[212:213] op_sel_hi:[1,0] neg_lo:[0,1] neg_hi:[0,1]
	v_pk_add_f32 v[4:5], v[4:5], v[212:213] op_sel_hi:[1,0] neg_lo:[0,1] neg_hi:[0,1]
	v_pk_add_f32 v[6:7], v[6:7], v[212:213] op_sel_hi:[1,0] neg_lo:[0,1] neg_hi:[0,1]
	v_pk_add_f32 v[8:9], v[8:9], v[212:213] op_sel_hi:[1,0] neg_lo:[0,1] neg_hi:[0,1]
	v_pk_add_f32 v[10:11], v[10:11], v[212:213] op_sel_hi:[1,0] neg_lo:[0,1] neg_hi:[0,1]
	v_pk_add_f32 v[12:13], v[12:13], v[212:213] op_sel_hi:[1,0] neg_lo:[0,1] neg_hi:[0,1]
	v_pk_add_f32 v[14:15], v[14:15], v[212:213] op_sel_hi:[1,0] neg_lo:[0,1] neg_hi:[0,1]
	v_pk_add_f32 v[16:17], v[16:17], v[224:225] op_sel_hi:[1,0] neg_lo:[0,1] neg_hi:[0,1]
	v_pk_add_f32 v[18:19], v[18:19], v[224:225] op_sel_hi:[1,0] neg_lo:[0,1] neg_hi:[0,1]
	v_pk_add_f32 v[20:21], v[20:21], v[224:225] op_sel_hi:[1,0] neg_lo:[0,1] neg_hi:[0,1]
	v_pk_add_f32 v[22:23], v[22:23], v[224:225] op_sel_hi:[1,0] neg_lo:[0,1] neg_hi:[0,1]
	v_pk_add_f32 v[24:25], v[24:25], v[224:225] op_sel_hi:[1,0] neg_lo:[0,1] neg_hi:[0,1]
	v_pk_add_f32 v[26:27], v[26:27], v[224:225] op_sel_hi:[1,0] neg_lo:[0,1] neg_hi:[0,1]
	v_pk_add_f32 v[28:29], v[28:29], v[224:225] op_sel_hi:[1,0] neg_lo:[0,1] neg_hi:[0,1]
	v_pk_add_f32 v[30:31], v[30:31], v[224:225] op_sel_hi:[1,0] neg_lo:[0,1] neg_hi:[0,1]
	v_pk_mul_f32 v[204:205], v[0:1], v[0:1]
	v_pk_mul_f32 v[206:207], v[2:3], v[2:3]
	v_pk_mul_f32 v[216:217], v[16:17], v[16:17]
	v_pk_mul_f32 v[218:219], v[18:19], v[18:19]
	v_pk_fma_f32 v[204:205], v[4:5], v[4:5], v[204:205]
	v_pk_fma_f32 v[206:207], v[6:7], v[6:7], v[206:207]
	v_pk_fma_f32 v[216:217], v[20:21], v[20:21], v[216:217]
	v_pk_fma_f32 v[218:219], v[22:23], v[22:23], v[218:219]
	v_pk_fma_f32 v[204:205], v[8:9], v[8:9], v[204:205]
	v_pk_fma_f32 v[206:207], v[10:11], v[10:11], v[206:207]
	v_pk_fma_f32 v[216:217], v[24:25], v[24:25], v[216:217]
	v_pk_fma_f32 v[218:219], v[26:27], v[26:27], v[218:219]
	v_pk_fma_f32 v[204:205], v[12:13], v[12:13], v[204:205]
	v_pk_fma_f32 v[206:207], v[14:15], v[14:15], v[206:207]
	v_pk_fma_f32 v[216:217], v[28:29], v[28:29], v[216:217]
	v_pk_fma_f32 v[218:219], v[30:31], v[30:31], v[218:219]
	v_pk_add_f32 v[204:205], v[204:205], v[206:207]
	v_pk_add_f32 v[216:217], v[216:217], v[218:219]
	v_add_f32_e32 v204, v204, v205
	v_add_f32_e32 v216, v216, v217
	s_nop 1
	v_add_f32_dpp v204, v204, v204 row_ror:1 row_mask:0xf bank_mask:0xf bound_ctrl:1
	v_add_f32_dpp v216, v216, v216 row_ror:1 row_mask:0xf bank_mask:0xf bound_ctrl:1
	s_nop 0
	v_add_f32_dpp v204, v204, v204 row_ror:2 row_mask:0xf bank_mask:0xf bound_ctrl:1
	v_add_f32_dpp v216, v216, v216 row_ror:2 row_mask:0xf bank_mask:0xf bound_ctrl:1
	s_nop 0
	v_add_f32_dpp v204, v204, v204 row_ror:4 row_mask:0xf bank_mask:0xf bound_ctrl:1
	v_add_f32_dpp v216, v216, v216 row_ror:4 row_mask:0xf bank_mask:0xf bound_ctrl:1
	s_nop 0
	v_add_f32_dpp v204, v204, v204 row_ror:8 row_mask:0xf bank_mask:0xf bound_ctrl:1
	v_add_f32_dpp v216, v216, v216 row_ror:8 row_mask:0xf bank_mask:0xf bound_ctrl:1
	s_nop 0
	v_mov_b32_e32 v205, v204
	v_mov_b32_e32 v217, v216
	s_nop 1
	v_permlane16_swap_b32_e32 v204, v205
	v_permlane16_swap_b32_e32 v216, v217
	s_nop 0
	v_add_f32_e32 v204, v204, v205
	v_add_f32_e32 v216, v216, v217
	v_mov_b32_e32 v205, v204
	v_mov_b32_e32 v217, v216
	s_nop 1
	v_permlane32_swap_b32_e32 v204, v205
	v_permlane32_swap_b32_e32 v216, v217
	s_nop 0
	v_add_f32_e32 v204, v204, v205
	v_add_f32_e32 v216, v216, v217
	v_mov_b32_e32 v205, 0x3727c5ac
	v_fmac_f32_e32 v205, 0x3a800000, v204
	v_mov_b32_e32 v217, 0x3727c5ac
	v_fmac_f32_e32 v217, 0x3a800000, v216
	v_mul_f32_e32 v206, 0x4b800000, v205
	s_mov_b32 s4, 0x800000
	v_cmp_gt_f32_e32 vcc, s4, v205
	s_nop 1
	v_cndmask_b32_e32 v205, v205, v206, vcc
	v_rsq_f32_e32 v205, v205
	s_nop 0
	v_mul_f32_e32 v206, 0x45800000, v205
	v_cndmask_b32_e32 v214, v205, v206, vcc
	v_mul_f32_e32 v218, 0x4b800000, v217
	s_mov_b32 s4, 0x800000
	v_cmp_gt_f32_e32 vcc, s4, v217
	s_nop 1
	v_cndmask_b32_e32 v217, v217, v218, vcc
	v_rsq_f32_e32 v217, v217
	s_nop 0
	v_mul_f32_e32 v218, 0x45800000, v217
	v_cndmask_b32_e32 v226, v217, v218, vcc
	v_pk_mul_f32 v[0:1], v[0:1], v[214:215] op_sel_hi:[1,0]
	v_pk_mul_f32 v[2:3], v[2:3], v[214:215] op_sel_hi:[1,0]
	v_pk_mul_f32 v[4:5], v[4:5], v[214:215] op_sel_hi:[1,0]
	v_pk_mul_f32 v[6:7], v[6:7], v[214:215] op_sel_hi:[1,0]
	v_pk_mul_f32 v[8:9], v[8:9], v[214:215] op_sel_hi:[1,0]
	v_pk_mul_f32 v[10:11], v[10:11], v[214:215] op_sel_hi:[1,0]
	v_pk_mul_f32 v[12:13], v[12:13], v[214:215] op_sel_hi:[1,0]
	v_pk_mul_f32 v[14:15], v[14:15], v[214:215] op_sel_hi:[1,0]
	v_pk_mul_f32 v[16:17], v[16:17], v[226:227] op_sel_hi:[1,0]
	v_pk_mul_f32 v[18:19], v[18:19], v[226:227] op_sel_hi:[1,0]
	v_pk_mul_f32 v[20:21], v[20:21], v[226:227] op_sel_hi:[1,0]
	v_pk_mul_f32 v[22:23], v[22:23], v[226:227] op_sel_hi:[1,0]
	v_pk_mul_f32 v[24:25], v[24:25], v[226:227] op_sel_hi:[1,0]
	v_pk_mul_f32 v[26:27], v[26:27], v[226:227] op_sel_hi:[1,0]
	v_pk_mul_f32 v[28:29], v[28:29], v[226:227] op_sel_hi:[1,0]
	v_pk_mul_f32 v[30:31], v[30:31], v[226:227] op_sel_hi:[1,0]
	v_pk_fma_f32 v[0:1], v[136:137], v[0:1], v[152:153]
	v_pk_fma_f32 v[2:3], v[138:139], v[2:3], v[154:155]
	v_pk_fma_f32 v[4:5], v[140:141], v[4:5], v[156:157]
	v_pk_fma_f32 v[6:7], v[142:143], v[6:7], v[158:159]
	v_pk_fma_f32 v[8:9], v[144:145], v[8:9], v[160:161]
	v_pk_fma_f32 v[10:11], v[146:147], v[10:11], v[162:163]
	v_pk_fma_f32 v[12:13], v[148:149], v[12:13], v[164:165]
	v_pk_fma_f32 v[14:15], v[150:151], v[14:15], v[166:167]
	v_pk_fma_f32 v[16:17], v[136:137], v[16:17], v[152:153]
	v_pk_fma_f32 v[18:19], v[138:139], v[18:19], v[154:155]
	v_pk_fma_f32 v[20:21], v[140:141], v[20:21], v[156:157]
	v_pk_fma_f32 v[22:23], v[142:143], v[22:23], v[158:159]
	v_pk_fma_f32 v[24:25], v[144:145], v[24:25], v[160:161]
	v_pk_fma_f32 v[26:27], v[146:147], v[26:27], v[162:163]
	v_pk_fma_f32 v[28:29], v[148:149], v[28:29], v[164:165]
	v_pk_fma_f32 v[30:31], v[150:151], v[30:31], v[166:167]
	v_mov_b32_e32 v228, v212
	v_mov_b32_e32 v229, v214
	v_mov_b32_e32 v168, v224
	v_mov_b32_e32 v169, v226
	v_add_f32_e32 v80, 1.0, v80
	v_add_f32_e32 v81, 1.0, v81
	v_add_f32_e32 v82, 1.0, v82
	v_add_f32_e32 v83, 1.0, v83
	v_add_f32_e32 v84, 1.0, v84
	v_add_f32_e32 v85, 1.0, v85
	v_add_f32_e32 v86, 1.0, v86
	v_add_f32_e32 v87, 1.0, v87
	v_add_f32_e32 v88, 1.0, v88
	v_add_f32_e32 v89, 1.0, v89
	v_add_f32_e32 v90, 1.0, v90
	v_add_f32_e32 v91, 1.0, v91
	v_add_f32_e32 v92, 1.0, v92
	v_add_f32_e32 v93, 1.0, v93
	v_add_f32_e32 v94, 1.0, v94
	v_add_f32_e32 v95, 1.0, v95
	v_pk_fma_f32 v[204:205], v[80:81], v[0:1], v[64:65]
	v_pk_fma_f32 v[206:207], v[82:83], v[2:3], v[66:67]
	v_pk_fma_f32 v[208:209], v[84:85], v[4:5], v[68:69]
	v_pk_fma_f32 v[210:211], v[86:87], v[6:7], v[70:71]
	v_pk_fma_f32 v[212:213], v[88:89], v[8:9], v[72:73]
	v_pk_fma_f32 v[214:215], v[90:91], v[10:11], v[74:75]
	v_pk_fma_f32 v[216:217], v[92:93], v[12:13], v[76:77]
	v_pk_fma_f32 v[218:219], v[94:95], v[14:15], v[78:79]
	v_cvt_pk_bf16_f32 v220, v204, v205
	v_cvt_pk_bf16_f32 v221, v206, v207
	v_cvt_pk_bf16_f32 v222, v208, v209
	v_cvt_pk_bf16_f32 v223, v210, v211
	v_cvt_pk_bf16_f32 v224, v212, v213
	v_cvt_pk_bf16_f32 v225, v214, v215
	v_cvt_pk_bf16_f32 v226, v216, v217
	v_cvt_pk_bf16_f32 v227, v218, v219
	s_mul_i32 s4, s6, 0x880
	s_add_u32 s4, s4, 0xf266000
	s_add_u32 s4, s4, s8
	s_addc_u32 s5, s9, 0
	global_store_dwordx2 v233, v[220:221], s[4:5]
	global_store_dwordx2 v233, v[222:223], s[4:5] offset:512
	global_store_dwordx2 v233, v[224:225], s[4:5] offset:1024
	global_store_dwordx2 v233, v[226:227], s[4:5] offset:1536
	s_mov_b64 s[12:13], exec
	s_mov_b64 exec, 1
	global_store_dwordx2 v129, v[228:229], s[4:5] offset:2048
	s_mov_b64 exec, s[12:13]
	v_pk_fma_f32 v[204:205], v[80:81], v[16:17], v[64:65]
	v_pk_fma_f32 v[206:207], v[82:83], v[18:19], v[66:67]
	v_pk_fma_f32 v[208:209], v[84:85], v[20:21], v[68:69]
	v_pk_fma_f32 v[210:211], v[86:87], v[22:23], v[70:71]
	v_pk_fma_f32 v[212:213], v[88:89], v[24:25], v[72:73]
	v_pk_fma_f32 v[214:215], v[90:91], v[26:27], v[74:75]
	v_pk_fma_f32 v[216:217], v[92:93], v[28:29], v[76:77]
	v_pk_fma_f32 v[218:219], v[94:95], v[30:31], v[78:79]
	v_cvt_pk_bf16_f32 v220, v204, v205
	v_cvt_pk_bf16_f32 v221, v206, v207
	v_cvt_pk_bf16_f32 v222, v208, v209
	v_cvt_pk_bf16_f32 v223, v210, v211
	v_cvt_pk_bf16_f32 v224, v212, v213
	v_cvt_pk_bf16_f32 v225, v214, v215
	v_cvt_pk_bf16_f32 v226, v216, v217
	v_cvt_pk_bf16_f32 v227, v218, v219
	s_mul_i32 s4, s6, 0x880
	s_add_u32 s4, s4, 0xf6a6000
	s_add_u32 s4, s4, s8
	s_addc_u32 s5, s9, 0
	global_store_dwordx2 v233, v[220:221], s[4:5]
	global_store_dwordx2 v233, v[222:223], s[4:5] offset:512
	global_store_dwordx2 v233, v[224:225], s[4:5] offset:1024
	global_store_dwordx2 v233, v[226:227], s[4:5] offset:1536
	s_mov_b64 s[12:13], exec
	s_mov_b64 exec, 1
	global_store_dwordx2 v129, v[168:169], s[4:5] offset:2048
	s_mov_b64 exec, s[12:13]
	s_waitcnt vmcnt(0)
	s_branch .LBB0_103
.Llnb_orig:
	v_readlane_b32 s52, v235, 34
	v_readlane_b32 s4, v235, 44
	v_readlane_b32 s53, v235, 35
	s_add_u32 s34, s52, 0xb166000
	s_mul_i32 s44, s4, 3
	s_addc_u32 s35, s53, 0
	s_ashr_i32 s45, s44, 31
	v_readlane_b32 s5, v235, 45
	s_lshl_b64 s[46:47], s[44:45], 12
	s_add_u32 s50, s46, 0x1000
	v_readlane_b32 s4, v237, 19
	s_addc_u32 s51, s47, 0
	v_readlane_b32 s10, v237, 25
	v_readlane_b32 s11, v237, 26
	s_add_u32 s46, s10, s50
	v_lshlrev_b32_e32 v0, 2, v34
	v_readlane_b32 s12, v237, 27
	s_addc_u32 s47, s11, s51
	v_and_b32_e32 v136, 0xfc, v0
	v_readlane_b32 s13, v237, 28
	s_add_u32 s50, s12, s50
	v_lshlrev_b32_e32 v128, 2, v136
	s_addc_u32 s51, s13, s51
	global_load_dwordx4 v[0:3], v128, s[46:47]
	global_load_dwordx4 v[4:7], v128, s[46:47] offset:1024
	global_load_dwordx4 v[8:11], v128, s[50:51]
	global_load_dwordx4 v[12:15], v128, s[50:51] offset:1024
	global_load_dwordx4 v[16:19], v128, s[46:47] offset:2048
	global_load_dwordx4 v[20:23], v128, s[46:47] offset:3072
	global_load_dwordx4 v[24:27], v128, s[50:51] offset:2048
	global_load_dwordx4 v[28:31], v128, s[50:51] offset:3072
	v_readlane_b32 s5, v237, 20
	v_lshl_add_u64 v[36:37], s[52:53], 0, v[128:129]
	s_mov_b64 s[4:5], 0x14ae6000
	v_lshl_add_u64 v[138:139], s[34:35], 0, v[128:129]
	v_lshl_add_u64 v[140:141], v[36:37], 0, s[4:5]
	v_lshlrev_b32_e32 v128, 1, v136
	v_readlane_b32 s4, v235, 18
	v_and_b32_e32 v36, 63, v34
	v_lshl_add_u64 v[142:143], s[90:91], 0, v[128:129]
	v_add_u32_e32 v144, s4, v33
	v_ashrrev_i32_e32 v33, 31, v32
	v_lshlrev_b32_e32 v128, 3, v36
	v_mad_i64_i32 v[34:35], s[50:51], v32, s3, v[128:129]
	v_lshlrev_b64 v[32:33], 12, v[32:33]
	v_lshl_or_b32 v32, v36, 4, v32
	s_add_u32 s46, s52, 0xb0fe000
	v_lshl_add_u64 v[32:33], s[34:35], 0, v[32:33]
	s_mov_b64 s[4:5], 0x800
	s_addc_u32 s47, s53, 0
	v_lshl_add_u64 v[146:147], s[90:91], 0, v[34:35]
	v_lshl_add_u64 v[148:149], v[32:33], 0, s[4:5]
	s_mov_b64 s[50:51], 0
	v_readlane_b32 s6, v237, 21
	v_readlane_b32 s7, v237, 22
	v_readlane_b32 s8, v237, 23
	v_readlane_b32 s9, v237, 24
	v_readlane_b32 s14, v237, 29
	v_readlane_b32 s15, v237, 30
	v_readlane_b32 s16, v237, 31
	v_readlane_b32 s17, v237, 32
	v_readlane_b32 s18, v237, 33
	v_readlane_b32 s19, v237, 34
	s_branch .LBB0_95

.Lop_entry:
	v_readlane_b32 s4, v235, 34
	v_readlane_b32 s5, v235, 35
	v_readlane_b32 s55, v235, 44
	s_mul_i32 s53, s55, 0x220000
	s_add_u32 s53, s53, 0xa738000
	s_add_u32 s44, s4, s53
	s_addc_u32 s45, s5, 0
	s_mul_i32 s53, s55, 0x1b000
	s_add_u32 s53, s53, 0xb0fd000
	s_add_u32 s46, s4, s53
	s_addc_u32 s47, s5, 0
	s_mul_i32 s40, s55, 3
	v_readlane_b32 s41, v235, 33
	s_cmp_lg_u32 s41, 0x200
	s_cselect_b32 s41, 0x100, 0
	s_or_b32 s40, s40, s41
	v_and_b32_e32 v225, 63, v170
	v_lshrrev_b32_e32 v226, 6, v170
	v_lshrrev_b32_e32 v227, 1, v226
	v_and_b32_e32 v228, 1, v226
	v_and_b32_e32 v229, 15, v225
	v_lshrrev_b32_e32 v230, 4, v225
	v_lshlrev_b32_e32 v231, 10, v226
	v_lshrrev_b32_e32 v232, 3, v170
	v_readfirstlane_b32 s52, v231
	v_and_b32_e32 v233, 7, v170
	v_bfe_u32 v224, v232, 1, 3
	v_xor_b32_e32 v233, v233, v224
	v_lshlrev_b32_e32 v233, 4, v233
	s_movk_i32 s4, 0x880
	v_mad_u32_u24 v224, v232, s4, v233
	v_and_b32_e32 v233, 15, v232
	v_lshlrev_b32_e32 v233, 1, v233
	v_lshrrev_b32_e32 v168, 4, v232
	v_add_u32_e32 v233, v233, v168
	v_and_b32_e32 v168, 7, v170
	v_bfe_u32 v169, v232, 1, 3
	v_xor_b32_e32 v168, v168, v169
	v_lshlrev_b32_e32 v168, 4, v168
	v_mad_u32_u24 v168, v233, s4, v168
	v_bfe_u32 v233, v229, 1, 3
	v_xor_b32_e32 v231, v230, v233
	v_or_b32_e32 v232, 4, v230
	v_xor_b32_e32 v232, v232, v233
	v_lshlrev_b32_e32 v231, 4, v231
	v_lshlrev_b32_e32 v232, 4, v232
	s_movk_i32 s4, 96
	v_mad_u32_u24 v233, v227, s4, v229
	v_lshlrev_b32_e32 v233, 7, v233
	v_add_u32_e32 v220, v233, v231
	v_add_u32_e32 v221, v233, v232
	v_lshl_add_u32 v233, v228, 6, v229
	v_lshlrev_b32_e32 v233, 7, v233
	v_add_u32_e32 v233, 0x8000, v233
	v_add_u32_e32 v222, v233, v231
	v_add_u32_e32 v223, v233, v232
	v_lshlrev_b32_e32 v231, 2, v230
	v_mad_u32_u24 v231, v227, s4, v231
	v_lshlrev_b32_e32 v232, 5, v228
	v_add_u32_e32 v232, v232, v229
	v_lshlrev_b32_e32 v232, 1, v232
	v_lshlrev_b32_e32 v169, 2, v232
	v_lshl_add_u32 v225, v231, 12, v169
	v_readlane_b32 s54, v237, 0
	s_cmp_ge_u32 s54, 0x200
	s_cbranch_scc1 .Lop_done
	s_add_u32 s57, s52, 0x8000
	s_and_b32 s55, s54, 7
	s_lshl_b32 s55, s55, 3
	s_lshr_b32 s62, s54, 6
	s_add_u32 s55, s55, s62
	s_bfe_u32 s36, s54, 0x30003
	s_lshl_b32 s62, s55, 8
	s_lshl_b32 s63, s36, 4
	s_or_b32 s62, s62, s63
	v_readlane_b32 s4, v235, 34
	v_readlane_b32 s5, v235, 35
	s_mul_i32 s34, s55, 0x66000
	s_add_u32 s34, s34, 0x19ce6000
	s_add_u32 s34, s34, s4
	s_addc_u32 s35, s5, 0
	s_mul_i32 s36, s36, 0x44000
	s_add_u32 s36, s36, s44
	s_addc_u32 s37, s45, 0
	s_add_u32 m0, s52, 0x0
	s_add_u32 s4, s34, 0x0
	s_addc_u32 s5, s35, 0
	global_load_lds_dwordx4 v224, s[4:5]
	s_add_u32 m0, s52, 0x1000
	s_add_u32 s4, s34, 0x11000
	s_addc_u32 s5, s35, 0
	global_load_lds_dwordx4 v224, s[4:5]
	s_add_u32 m0, s52, 0x2000
	s_add_u32 s4, s34, 0x22000
	s_addc_u32 s5, s35, 0
	global_load_lds_dwordx4 v224, s[4:5]
	s_add_u32 m0, s52, 0x3000
	s_add_u32 s4, s34, 0x33000
	s_addc_u32 s5, s35, 0
	global_load_lds_dwordx4 v224, s[4:5]
	s_add_u32 m0, s52, 0x4000
	s_add_u32 s4, s34, 0x44000
	s_addc_u32 s5, s35, 0
	global_load_lds_dwordx4 v224, s[4:5]
	s_add_u32 m0, s52, 0x5000
	s_add_u32 s4, s34, 0x55000
	s_addc_u32 s5, s35, 0
	global_load_lds_dwordx4 v224, s[4:5]
	s_add_u32 m0, s57, 0x0
	s_add_u32 s4, s36, 0x0
	s_addc_u32 s5, s37, 0
	global_load_lds_dwordx4 v168, s[4:5]
	s_add_u32 m0, s57, 0x1000
	s_add_u32 s4, s36, 0x11000
	s_addc_u32 s5, s37, 0
	global_load_lds_dwordx4 v168, s[4:5]
	s_add_u32 m0, s57, 0x2000
	s_add_u32 s4, s36, 0x22000
	s_addc_u32 s5, s37, 0
	global_load_lds_dwordx4 v168, s[4:5]
	s_add_u32 m0, s57, 0x3000
	s_add_u32 s4, s36, 0x33000
	s_addc_u32 s5, s37, 0
	global_load_lds_dwordx4 v168, s[4:5]
	s_add_u32 s36, s36, 0x80
	s_addc_u32 s37, s37, 0
	s_add_u32 s34, s34, 0x80
	s_addc_u32 s35, s35, 0
.Lop_tile:
	s_mov_b32 s56, s62
	v_mov_b32_e32 v0, 0
	v_mov_b32_e32 v1, 0
	v_mov_b32_e32 v2, 0
	v_mov_b32_e32 v3, 0
	v_mov_b32_e32 v4, 0
	v_mov_b32_e32 v5, 0
	v_mov_b32_e32 v6, 0
	v_mov_b32_e32 v7, 0
	v_mov_b32_e32 v8, 0
	v_mov_b32_e32 v9, 0
	v_mov_b32_e32 v10, 0
	v_mov_b32_e32 v11, 0
	v_mov_b32_e32 v12, 0
	v_mov_b32_e32 v13, 0
	v_mov_b32_e32 v14, 0
	v_mov_b32_e32 v15, 0
	v_mov_b32_e32 v16, 0
	v_mov_b32_e32 v17, 0
	v_mov_b32_e32 v18, 0
	v_mov_b32_e32 v19, 0
	v_mov_b32_e32 v20, 0
	v_mov_b32_e32 v21, 0
	v_mov_b32_e32 v22, 0
	v_mov_b32_e32 v23, 0
	v_mov_b32_e32 v24, 0
	v_mov_b32_e32 v25, 0
	v_mov_b32_e32 v26, 0
	v_mov_b32_e32 v27, 0
	v_mov_b32_e32 v28, 0
	v_mov_b32_e32 v29, 0
	v_mov_b32_e32 v30, 0
	v_mov_b32_e32 v31, 0
	v_mov_b32_e32 v32, 0
	v_mov_b32_e32 v33, 0
	v_mov_b32_e32 v34, 0
	v_mov_b32_e32 v35, 0
	v_mov_b32_e32 v36, 0
	v_mov_b32_e32 v37, 0
	v_mov_b32_e32 v38, 0
	v_mov_b32_e32 v39, 0
	v_mov_b32_e32 v40, 0
	v_mov_b32_e32 v41, 0
	v_mov_b32_e32 v42, 0
	v_mov_b32_e32 v43, 0
	v_mov_b32_e32 v44, 0
	v_mov_b32_e32 v45, 0
	v_mov_b32_e32 v46, 0
	v_mov_b32_e32 v47, 0
	v_mov_b32_e32 v48, 0
	v_mov_b32_e32 v49, 0
	v_mov_b32_e32 v50, 0
	v_mov_b32_e32 v51, 0
	v_mov_b32_e32 v52, 0
	v_mov_b32_e32 v53, 0
	v_mov_b32_e32 v54, 0
	v_mov_b32_e32 v55, 0
	v_mov_b32_e32 v56, 0
	v_mov_b32_e32 v57, 0
	v_mov_b32_e32 v58, 0
	v_mov_b32_e32 v59, 0
	v_mov_b32_e32 v60, 0
	v_mov_b32_e32 v61, 0
	v_mov_b32_e32 v62, 0
	v_mov_b32_e32 v63, 0
	v_mov_b32_e32 v64, 0
	v_mov_b32_e32 v65, 0
	v_mov_b32_e32 v66, 0
	v_mov_b32_e32 v67, 0
	v_mov_b32_e32 v68, 0
	v_mov_b32_e32 v69, 0
	v_mov_b32_e32 v70, 0
	v_mov_b32_e32 v71, 0
	v_mov_b32_e32 v72, 0
	v_mov_b32_e32 v73, 0
	v_mov_b32_e32 v74, 0
	v_mov_b32_e32 v75, 0
	v_mov_b32_e32 v76, 0
	v_mov_b32_e32 v77, 0
	v_mov_b32_e32 v78, 0
	v_mov_b32_e32 v79, 0
	v_mov_b32_e32 v80, 0
	v_mov_b32_e32 v81, 0
	v_mov_b32_e32 v82, 0
	v_mov_b32_e32 v83, 0
	v_mov_b32_e32 v84, 0
	v_mov_b32_e32 v85, 0
	v_mov_b32_e32 v86, 0
	v_mov_b32_e32 v87, 0
	v_mov_b32_e32 v88, 0
	v_mov_b32_e32 v89, 0
	v_mov_b32_e32 v90, 0
	v_mov_b32_e32 v91, 0
	v_mov_b32_e32 v92, 0
	v_mov_b32_e32 v93, 0
	v_mov_b32_e32 v94, 0
	v_mov_b32_e32 v95, 0
	s_mov_b32 s53, 0
	v_readlane_b32 s4, v235, 34
	v_readlane_b32 s5, v235, 35
	s_lshr_b32 s55, s56, 8
	s_mul_i32 s50, s55, 0xc0000
	s_bfe_u32 s63, s56, 0x30004
	s_lshl_b32 s63, s63, 9
	s_add_u32 s50, s50, s63
	s_add_u32 s50, s50, 0xb166000
	s_add_u32 s50, s50, s4
	s_addc_u32 s51, s5, 0
	s_mul_i32 s55, s55, 192
	s_lshr_b32 s4, s52, 11
	s_mul_i32 s4, s4, 96
	s_add_u32 s58, s55, s4
	s_lshr_b32 s4, s58, 12
	s_mov_b32 s59, s4
	s_mul_i32 s4, s4, 0x9000
	s_add_u32 s4, s4, s63
	s_add_u32 s4, s4, s46
	s_addc_u32 s5, s47, 0
	global_load_dwordx2 v[226:227], v169, s[4:5]
	global_load_dwordx2 v[228:229], v169, s[4:5] offset:128
	s_add_u32 s4, s58, 95
	s_lshr_b32 s4, s4, 12
	s_mul_i32 s4, s4, 0x9000
	s_add_u32 s4, s4, s63
	s_add_u32 s4, s4, s46
	s_addc_u32 s5, s47, 0
	global_load_dwordx2 v[230:231], v169, s[4:5]
	global_load_dwordx2 v[232:233], v169, s[4:5] offset:128
	s_bitcmp1_b32 s40, 8
	s_cbranch_scc1 .Lop_idgb
	s_and_b32 s4, s40, 0xff
	s_lshl_b32 s4, s4, 12
	s_add_u32 s41, s4, s63
	v_readlane_b32 s4, v237, 25
	v_readlane_b32 s5, v237, 26
	s_add_u32 s4, s4, s41
	s_addc_u32 s5, s5, 0
	global_load_dwordx2 v[96:97], v169, s[4:5]
	global_load_dwordx2 v[98:99], v169, s[4:5] offset:128
	v_readlane_b32 s4, v237, 27
	v_readlane_b32 s5, v237, 28
	s_add_u32 s4, s4, s41
	s_addc_u32 s5, s5, 0
	global_load_dwordx2 v[100:101], v169, s[4:5]
	global_load_dwordx2 v[102:103], v169, s[4:5] offset:128
	s_branch .Lop_gbdone
.Lop_idgb:
	v_mov_b32_e32 v96, 1.0
	v_mov_b32_e32 v97, 1.0
	v_mov_b32_e32 v98, 1.0
	v_mov_b32_e32 v99, 1.0
	v_mov_b32_e32 v100, 0
	v_mov_b32_e32 v101, 0
	v_mov_b32_e32 v102, 0
	v_mov_b32_e32 v103, 0
.Lop_gbdone:
.Lop_k:
	s_waitcnt vmcnt(0)
	s_barrier
	s_xor_b32 s57, s57, 0x4000
	s_cmp_eq_u32 s53, 15
	s_cbranch_scc1 .Lop_nob
	s_add_u32 m0, s57, 0x0
	s_add_u32 s4, s36, 0x0
	s_addc_u32 s5, s37, 0
	global_load_lds_dwordx4 v168, s[4:5]
	s_add_u32 m0, s57, 0x1000
	s_add_u32 s4, s36, 0x11000
	s_addc_u32 s5, s37, 0
	global_load_lds_dwordx4 v168, s[4:5]
	s_add_u32 m0, s57, 0x2000
	s_add_u32 s4, s36, 0x22000
	s_addc_u32 s5, s37, 0
	global_load_lds_dwordx4 v168, s[4:5]
	s_add_u32 m0, s57, 0x3000
	s_add_u32 s4, s36, 0x33000
	s_addc_u32 s5, s37, 0
	global_load_lds_dwordx4 v168, s[4:5]
	s_add_u32 s36, s36, 0x80
	s_addc_u32 s37, s37, 0

.Lop_nopf:
	s_setprio 1
	v_mfma_f32_16x16x32_bf16 v[0:3], v[136:139], a[0:3], v[0:3]
	v_mfma_f32_16x16x32_bf16 v[4:7], v[136:139], a[4:7], v[4:7]
	v_mfma_f32_16x16x32_bf16 v[8:11], v[136:139], a[8:11], v[8:11]
	v_mfma_f32_16x16x32_bf16 v[12:15], v[136:139], a[12:15], v[12:15]
	v_mfma_f32_16x16x32_bf16 v[16:19], v[140:143], a[0:3], v[16:19]
	v_mfma_f32_16x16x32_bf16 v[20:23], v[140:143], a[4:7], v[20:23]
	v_mfma_f32_16x16x32_bf16 v[24:27], v[140:143], a[8:11], v[24:27]
	v_mfma_f32_16x16x32_bf16 v[28:31], v[140:143], a[12:15], v[28:31]
	v_mfma_f32_16x16x32_bf16 v[32:35], v[144:147], a[0:3], v[32:35]
	v_mfma_f32_16x16x32_bf16 v[36:39], v[144:147], a[4:7], v[36:39]
	v_mfma_f32_16x16x32_bf16 v[40:43], v[144:147], a[8:11], v[40:43]
	v_mfma_f32_16x16x32_bf16 v[44:47], v[144:147], a[12:15], v[44:47]
	v_mfma_f32_16x16x32_bf16 v[48:51], v[148:151], a[0:3], v[48:51]
	v_mfma_f32_16x16x32_bf16 v[52:55], v[148:151], a[4:7], v[52:55]
	v_mfma_f32_16x16x32_bf16 v[56:59], v[148:151], a[8:11], v[56:59]
	v_mfma_f32_16x16x32_bf16 v[60:63], v[148:151], a[12:15], v[60:63]
	v_mfma_f32_16x16x32_bf16 v[64:67], v[152:155], a[0:3], v[64:67]
	v_mfma_f32_16x16x32_bf16 v[68:71], v[152:155], a[4:7], v[68:71]
	v_mfma_f32_16x16x32_bf16 v[72:75], v[152:155], a[8:11], v[72:75]
	v_mfma_f32_16x16x32_bf16 v[76:79], v[152:155], a[12:15], v[76:79]
	v_mfma_f32_16x16x32_bf16 v[80:83], v[156:159], a[0:3], v[80:83]
	v_mfma_f32_16x16x32_bf16 v[84:87], v[156:159], a[4:7], v[84:87]
	v_mfma_f32_16x16x32_bf16 v[88:91], v[156:159], a[8:11], v[88:91]
	v_mfma_f32_16x16x32_bf16 v[92:95], v[156:159], a[12:15], v[92:95]
	s_setprio 0
	s_mov_b32 s55, 0x3fd744fd
	v_readlane_b32 s4, v235, 34
	v_readlane_b32 s5, v235, 35
	s_lshr_b32 s42, s56, 8
	s_mul_i32 s42, s42, 0x66000
	s_add_u32 s42, s42, 0xe166000
	s_add_u32 s42, s42, s4
	s_addc_u32 s43, s5, 0
	v_lshrrev_b32_e32 v131, 12, v225
	s_movk_i32 s4, 0x880
	v_mul_u32_u24_e32 v131, s4, v131
	s_add_u32 s4, s50, 0x0
	s_addc_u32 s5, s51, 0
	global_load_dwordx2 v[104:105], v225, s[4:5]
	global_load_dwordx2 v[106:107], v225, s[4:5] offset:128
	s_add_u32 s4, s50, 0x1000
	s_addc_u32 s5, s51, 0
	global_load_dwordx2 v[108:109], v225, s[4:5]
	global_load_dwordx2 v[110:111], v225, s[4:5] offset:128
	s_add_u32 s4, s50, 0x2000
	s_addc_u32 s5, s51, 0
	global_load_dwordx2 v[112:113], v225, s[4:5]
	global_load_dwordx2 v[114:115], v225, s[4:5] offset:128
	s_add_u32 s4, s50, 0x3000
	s_addc_u32 s5, s51, 0
	global_load_dwordx2 v[116:117], v225, s[4:5]
	global_load_dwordx2 v[118:119], v225, s[4:5] offset:128
	s_add_u32 s4, s42, 0x0
	s_addc_u32 s5, s43, 0
	global_load_dwordx2 v[120:121], v131, s[4:5] offset:2048
	s_add_u32 s4, s42, 0x880
	s_addc_u32 s5, s43, 0
	global_load_dwordx2 v[122:123], v131, s[4:5] offset:2048
	s_add_u32 s4, s42, 0x1100
	s_addc_u32 s5, s43, 0
	global_load_dwordx2 v[124:125], v131, s[4:5] offset:2048
	s_add_u32 s4, s42, 0x1980
	s_addc_u32 s5, s43, 0
	global_load_dwordx2 v[126:127], v131, s[4:5] offset:2048
	s_add_u32 s4, s50, 0x10000
	s_addc_u32 s5, s51, 0
	global_load_dwordx2 v[136:137], v225, s[4:5]
	global_load_dwordx2 v[138:139], v225, s[4:5] offset:128
	s_add_u32 s4, s50, 0x11000
	s_addc_u32 s5, s51, 0
	global_load_dwordx2 v[140:141], v225, s[4:5]
	global_load_dwordx2 v[142:143], v225, s[4:5] offset:128
	s_add_u32 s4, s50, 0x12000
	s_addc_u32 s5, s51, 0
	global_load_dwordx2 v[144:145], v225, s[4:5]
	global_load_dwordx2 v[146:147], v225, s[4:5] offset:128
	s_add_u32 s4, s50, 0x13000
	s_addc_u32 s5, s51, 0
	global_load_dwordx2 v[148:149], v225, s[4:5]
	global_load_dwordx2 v[150:151], v225, s[4:5] offset:128
	s_add_u32 s4, s42, 0x8800
	s_addc_u32 s5, s43, 0
	global_load_dwordx2 v[152:153], v131, s[4:5] offset:2048
	s_add_u32 s4, s42, 0x9080
	s_addc_u32 s5, s43, 0
	global_load_dwordx2 v[154:155], v131, s[4:5] offset:2048
	s_add_u32 s4, s42, 0x9900
	s_addc_u32 s5, s43, 0
	global_load_dwordx2 v[156:157], v131, s[4:5] offset:2048
	s_add_u32 s4, s42, 0xa180
	s_addc_u32 s5, s43, 0
	global_load_dwordx2 v[158:159], v131, s[4:5] offset:2048
	s_add_u32 s4, s50, 0x20000
	s_addc_u32 s5, s51, 0
	global_load_dwordx2 v[204:205], v225, s[4:5]
	global_load_dwordx2 v[206:207], v225, s[4:5] offset:128
	s_add_u32 s4, s50, 0x21000
	s_addc_u32 s5, s51, 0
	global_load_dwordx2 v[208:209], v225, s[4:5]
	global_load_dwordx2 v[210:211], v225, s[4:5] offset:128
	s_add_u32 s4, s50, 0x22000
	s_addc_u32 s5, s51, 0
	global_load_dwordx2 v[212:213], v225, s[4:5]
	global_load_dwordx2 v[214:215], v225, s[4:5] offset:128
	s_add_u32 s4, s50, 0x23000
	s_addc_u32 s5, s51, 0
	global_load_dwordx2 v[216:217], v225, s[4:5]
	global_load_dwordx2 v[218:219], v225, s[4:5] offset:128
	s_add_u32 s4, s42, 0x11000
	s_addc_u32 s5, s43, 0
	global_load_dwordx2 v[160:161], v131, s[4:5] offset:2048
	s_add_u32 s4, s42, 0x11880
	s_addc_u32 s5, s43, 0
	global_load_dwordx2 v[162:163], v131, s[4:5] offset:2048
	s_add_u32 s4, s42, 0x12100
	s_addc_u32 s5, s43, 0
	global_load_dwordx2 v[164:165], v131, s[4:5] offset:2048
	s_add_u32 s4, s42, 0x12980
	s_addc_u32 s5, s43, 0
	global_load_dwordx2 v[166:167], v131, s[4:5] offset:2048
	s_nop 7
	s_nop 7
	s_waitcnt vmcnt(24)
	s_bitcmp1_b32 s40, 8
	s_cbranch_scc0 .Lop_st0
	v_mov_b32_e32 v120, 0
	v_mov_b32_e32 v121, 1.0
	v_mov_b32_e32 v122, 0
	v_mov_b32_e32 v123, 1.0
	v_mov_b32_e32 v124, 0
	v_mov_b32_e32 v125, 1.0
	v_mov_b32_e32 v126, 0
	v_mov_b32_e32 v127, 1.0
.Lop_st0:
	v_sub_f32_e32 v104, v104, v120
	v_sub_f32_e32 v105, v105, v120
	v_sub_f32_e32 v106, v106, v120
	v_sub_f32_e32 v107, v107, v120
	v_mul_f32_e32 v104, v104, v121
	v_mul_f32_e32 v105, v105, v121
	v_mul_f32_e32 v106, v106, v121
	v_mul_f32_e32 v107, v107, v121
	v_fma_f32 v104, v96, v104, v100
	v_fma_f32 v105, v97, v105, v101
	v_fma_f32 v106, v98, v106, v102
	v_fma_f32 v107, v99, v107, v103
	v_mul_f32_e32 v104, s55, v104
	v_mul_f32_e32 v105, s55, v105
	v_mul_f32_e32 v106, s55, v106
	v_mul_f32_e32 v107, s55, v107
	v_fmac_f32_e32 v104, v226, v0
	v_fmac_f32_e32 v105, v227, v4
	v_fmac_f32_e32 v106, v228, v8
	v_fmac_f32_e32 v107, v229, v12
	v_sub_f32_e32 v108, v108, v122
	v_sub_f32_e32 v109, v109, v122
	v_sub_f32_e32 v110, v110, v122
	v_sub_f32_e32 v111, v111, v122
	v_mul_f32_e32 v108, v108, v123
	v_mul_f32_e32 v109, v109, v123
	v_mul_f32_e32 v110, v110, v123
	v_mul_f32_e32 v111, v111, v123
	v_fma_f32 v108, v96, v108, v100
	v_fma_f32 v109, v97, v109, v101
	v_fma_f32 v110, v98, v110, v102
	v_fma_f32 v111, v99, v111, v103
	v_mul_f32_e32 v108, s55, v108
	v_mul_f32_e32 v109, s55, v109
	v_mul_f32_e32 v110, s55, v110
	v_mul_f32_e32 v111, s55, v111
	v_fmac_f32_e32 v108, v226, v1
	v_fmac_f32_e32 v109, v227, v5
	v_fmac_f32_e32 v110, v228, v9
	v_fmac_f32_e32 v111, v229, v13
	v_sub_f32_e32 v112, v112, v124
	v_sub_f32_e32 v113, v113, v124
	v_sub_f32_e32 v114, v114, v124
	v_sub_f32_e32 v115, v115, v124
	v_mul_f32_e32 v112, v112, v125
	v_mul_f32_e32 v113, v113, v125
	v_mul_f32_e32 v114, v114, v125
	v_mul_f32_e32 v115, v115, v125
	v_fma_f32 v112, v96, v112, v100
	v_fma_f32 v113, v97, v113, v101
	v_fma_f32 v114, v98, v114, v102
	v_fma_f32 v115, v99, v115, v103
	v_mul_f32_e32 v112, s55, v112
	v_mul_f32_e32 v113, s55, v113
	v_mul_f32_e32 v114, s55, v114
	v_mul_f32_e32 v115, s55, v115
	v_fmac_f32_e32 v112, v226, v2
	v_fmac_f32_e32 v113, v227, v6
	v_fmac_f32_e32 v114, v228, v10
	v_fmac_f32_e32 v115, v229, v14
	v_sub_f32_e32 v116, v116, v126
	v_sub_f32_e32 v117, v117, v126
	v_sub_f32_e32 v118, v118, v126
	v_sub_f32_e32 v119, v119, v126
	v_mul_f32_e32 v116, v116, v127
	v_mul_f32_e32 v117, v117, v127
	v_mul_f32_e32 v118, v118, v127
	v_mul_f32_e32 v119, v119, v127
	v_fma_f32 v116, v96, v116, v100
	v_fma_f32 v117, v97, v117, v101
	v_fma_f32 v118, v98, v118, v102
	v_fma_f32 v119, v99, v119, v103
	v_mul_f32_e32 v116, s55, v116
	v_mul_f32_e32 v117, s55, v117
	v_mul_f32_e32 v118, s55, v118
	v_mul_f32_e32 v119, s55, v119
	v_fmac_f32_e32 v116, v226, v3
	v_fmac_f32_e32 v117, v227, v7
	v_fmac_f32_e32 v118, v228, v11
	v_fmac_f32_e32 v119, v229, v15
	s_add_u32 s4, s50, 0x0
	s_addc_u32 s5, s51, 0
	global_store_dwordx2 v225, v[104:105], s[4:5]
	global_store_dwordx2 v225, v[106:107], s[4:5] offset:128
	s_add_u32 s4, s50, 0x1000
	s_addc_u32 s5, s51, 0
	global_store_dwordx2 v225, v[108:109], s[4:5]
	global_store_dwordx2 v225, v[110:111], s[4:5] offset:128
	s_add_u32 s4, s50, 0x2000
	s_addc_u32 s5, s51, 0
	global_store_dwordx2 v225, v[112:113], s[4:5]
	global_store_dwordx2 v225, v[114:115], s[4:5] offset:128
	s_add_u32 s4, s50, 0x3000
	s_addc_u32 s5, s51, 0
	global_store_dwordx2 v225, v[116:117], s[4:5]
	global_store_dwordx2 v225, v[118:119], s[4:5] offset:128
	s_add_u32 s4, s50, 0x30000
	s_addc_u32 s5, s51, 0
	global_load_dwordx2 v[104:105], v225, s[4:5]
	global_load_dwordx2 v[106:107], v225, s[4:5] offset:128
	s_add_u32 s4, s50, 0x31000
	s_addc_u32 s5, s51, 0
	global_load_dwordx2 v[108:109], v225, s[4:5]
	global_load_dwordx2 v[110:111], v225, s[4:5] offset:128
	s_add_u32 s4, s50, 0x32000
	s_addc_u32 s5, s51, 0
	global_load_dwordx2 v[112:113], v225, s[4:5]
	global_load_dwordx2 v[114:115], v225, s[4:5] offset:128
	s_add_u32 s4, s50, 0x33000
	s_addc_u32 s5, s51, 0
	global_load_dwordx2 v[116:117], v225, s[4:5]
	global_load_dwordx2 v[118:119], v225, s[4:5] offset:128
	s_add_u32 s4, s42, 0x19800
	s_addc_u32 s5, s43, 0
	global_load_dwordx2 v[120:121], v131, s[4:5] offset:2048
	s_add_u32 s4, s42, 0x1a080
	s_addc_u32 s5, s43, 0
	global_load_dwordx2 v[122:123], v131, s[4:5] offset:2048
	s_add_u32 s4, s42, 0x1a900
	s_addc_u32 s5, s43, 0
	global_load_dwordx2 v[124:125], v131, s[4:5] offset:2048
	s_add_u32 s4, s42, 0x1b180
	s_addc_u32 s5, s43, 0
	global_load_dwordx2 v[126:127], v131, s[4:5] offset:2048
	s_add_u32 s4, s58, 16
	s_lshr_b32 s4, s4, 12
	s_cmp_eq_u32 s4, s59
	s_cbranch_scc1 .Lop_g1
	s_mov_b32 s59, s4
	v_mov_b32_e32 v226, v230
	v_mov_b32_e32 v227, v231
	v_mov_b32_e32 v228, v232
	v_mov_b32_e32 v229, v233
.Lop_g1:
	s_waitcnt vmcnt(32)
	s_bitcmp1_b32 s40, 8
	s_cbranch_scc0 .Lop_st1
	v_mov_b32_e32 v152, 0
	v_mov_b32_e32 v153, 1.0
	v_mov_b32_e32 v154, 0
	v_mov_b32_e32 v155, 1.0
	v_mov_b32_e32 v156, 0
	v_mov_b32_e32 v157, 1.0
	v_mov_b32_e32 v158, 0
	v_mov_b32_e32 v159, 1.0
.Lop_st1:
	v_sub_f32_e32 v136, v136, v152
	v_sub_f32_e32 v137, v137, v152
	v_sub_f32_e32 v138, v138, v152
	v_sub_f32_e32 v139, v139, v152
	v_mul_f32_e32 v136, v136, v153
	v_mul_f32_e32 v137, v137, v153
	v_mul_f32_e32 v138, v138, v153
	v_mul_f32_e32 v139, v139, v153
	v_fma_f32 v136, v96, v136, v100
	v_fma_f32 v137, v97, v137, v101
	v_fma_f32 v138, v98, v138, v102
	v_fma_f32 v139, v99, v139, v103
	v_mul_f32_e32 v136, s55, v136
	v_mul_f32_e32 v137, s55, v137
	v_mul_f32_e32 v138, s55, v138
	v_mul_f32_e32 v139, s55, v139
	v_fmac_f32_e32 v136, v226, v16
	v_fmac_f32_e32 v137, v227, v20
	v_fmac_f32_e32 v138, v228, v24
	v_fmac_f32_e32 v139, v229, v28
	v_sub_f32_e32 v140, v140, v154
	v_sub_f32_e32 v141, v141, v154
	v_sub_f32_e32 v142, v142, v154
	v_sub_f32_e32 v143, v143, v154
	v_mul_f32_e32 v140, v140, v155
	v_mul_f32_e32 v141, v141, v155
	v_mul_f32_e32 v142, v142, v155
	v_mul_f32_e32 v143, v143, v155
	v_fma_f32 v140, v96, v140, v100
	v_fma_f32 v141, v97, v141, v101
	v_fma_f32 v142, v98, v142, v102
	v_fma_f32 v143, v99, v143, v103
	v_mul_f32_e32 v140, s55, v140
	v_mul_f32_e32 v141, s55, v141
	v_mul_f32_e32 v142, s55, v142
	v_mul_f32_e32 v143, s55, v143
	v_fmac_f32_e32 v140, v226, v17
	v_fmac_f32_e32 v141, v227, v21
	v_fmac_f32_e32 v142, v228, v25
	v_fmac_f32_e32 v143, v229, v29
	v_sub_f32_e32 v144, v144, v156
	v_sub_f32_e32 v145, v145, v156
	v_sub_f32_e32 v146, v146, v156
	v_sub_f32_e32 v147, v147, v156
	v_mul_f32_e32 v144, v144, v157
	v_mul_f32_e32 v145, v145, v157
	v_mul_f32_e32 v146, v146, v157
	v_mul_f32_e32 v147, v147, v157
	v_fma_f32 v144, v96, v144, v100
	v_fma_f32 v145, v97, v145, v101
	v_fma_f32 v146, v98, v146, v102
	v_fma_f32 v147, v99, v147, v103
	v_mul_f32_e32 v144, s55, v144
	v_mul_f32_e32 v145, s55, v145
	v_mul_f32_e32 v146, s55, v146
	v_mul_f32_e32 v147, s55, v147
	v_fmac_f32_e32 v144, v226, v18
	v_fmac_f32_e32 v145, v227, v22
	v_fmac_f32_e32 v146, v228, v26
	v_fmac_f32_e32 v147, v229, v30
	v_sub_f32_e32 v148, v148, v158
	v_sub_f32_e32 v149, v149, v158
	v_sub_f32_e32 v150, v150, v158
	v_sub_f32_e32 v151, v151, v158
	v_mul_f32_e32 v148, v148, v159
	v_mul_f32_e32 v149, v149, v159
	v_mul_f32_e32 v150, v150, v159
	v_mul_f32_e32 v151, v151, v159
	v_fma_f32 v148, v96, v148, v100
	v_fma_f32 v149, v97, v149, v101
	v_fma_f32 v150, v98, v150, v102
	v_fma_f32 v151, v99, v151, v103
	v_mul_f32_e32 v148, s55, v148
	v_mul_f32_e32 v149, s55, v149
	v_mul_f32_e32 v150, s55, v150
	v_mul_f32_e32 v151, s55, v151
	v_fmac_f32_e32 v148, v226, v19
	v_fmac_f32_e32 v149, v227, v23
	v_fmac_f32_e32 v150, v228, v27
	v_fmac_f32_e32 v151, v229, v31
	s_add_u32 s4, s50, 0x10000
	s_addc_u32 s5, s51, 0
	global_store_dwordx2 v225, v[136:137], s[4:5]
	global_store_dwordx2 v225, v[138:139], s[4:5] offset:128
	s_add_u32 s4, s50, 0x11000
	s_addc_u32 s5, s51, 0
	global_store_dwordx2 v225, v[140:141], s[4:5]
	global_store_dwordx2 v225, v[142:143], s[4:5] offset:128
	s_add_u32 s4, s50, 0x12000
	s_addc_u32 s5, s51, 0
	global_store_dwordx2 v225, v[144:145], s[4:5]
	global_store_dwordx2 v225, v[146:147], s[4:5] offset:128
	s_add_u32 s4, s50, 0x13000
	s_addc_u32 s5, s51, 0
	global_store_dwordx2 v225, v[148:149], s[4:5]
	global_store_dwordx2 v225, v[150:151], s[4:5] offset:128
	s_add_u32 s4, s50, 0x40000
	s_addc_u32 s5, s51, 0
	global_load_dwordx2 v[136:137], v225, s[4:5]
	global_load_dwordx2 v[138:139], v225, s[4:5] offset:128
	s_add_u32 s4, s50, 0x41000
	s_addc_u32 s5, s51, 0
	global_load_dwordx2 v[140:141], v225, s[4:5]
	global_load_dwordx2 v[142:143], v225, s[4:5] offset:128
	s_add_u32 s4, s50, 0x42000
	s_addc_u32 s5, s51, 0
	global_load_dwordx2 v[144:145], v225, s[4:5]
	global_load_dwordx2 v[146:147], v225, s[4:5] offset:128
	s_add_u32 s4, s50, 0x43000
	s_addc_u32 s5, s51, 0
	global_load_dwordx2 v[148:149], v225, s[4:5]
	global_load_dwordx2 v[150:151], v225, s[4:5] offset:128
	s_add_u32 s4, s42, 0x22000
	s_addc_u32 s5, s43, 0
	global_load_dwordx2 v[152:153], v131, s[4:5] offset:2048
	s_add_u32 s4, s42, 0x22880
	s_addc_u32 s5, s43, 0
	global_load_dwordx2 v[154:155], v131, s[4:5] offset:2048
	s_add_u32 s4, s42, 0x23100
	s_addc_u32 s5, s43, 0
	global_load_dwordx2 v[156:157], v131, s[4:5] offset:2048
	s_add_u32 s4, s42, 0x23980
	s_addc_u32 s5, s43, 0
	global_load_dwordx2 v[158:159], v131, s[4:5] offset:2048
	s_add_u32 s4, s58, 32
	s_lshr_b32 s4, s4, 12
	s_cmp_eq_u32 s4, s59
	s_cbranch_scc1 .Lop_g2
	s_mov_b32 s59, s4
	v_mov_b32_e32 v226, v230
	v_mov_b32_e32 v227, v231
	v_mov_b32_e32 v228, v232
	v_mov_b32_e32 v229, v233
.Lop_g2:
	s_waitcnt vmcnt(40)
	s_bitcmp1_b32 s40, 8
	s_cbranch_scc0 .Lop_st2
	v_mov_b32_e32 v160, 0
	v_mov_b32_e32 v161, 1.0
	v_mov_b32_e32 v162, 0
	v_mov_b32_e32 v163, 1.0
	v_mov_b32_e32 v164, 0
	v_mov_b32_e32 v165, 1.0
	v_mov_b32_e32 v166, 0
	v_mov_b32_e32 v167, 1.0
.Lop_st2:
	v_sub_f32_e32 v204, v204, v160
	v_sub_f32_e32 v205, v205, v160
	v_sub_f32_e32 v206, v206, v160
	v_sub_f32_e32 v207, v207, v160
	v_mul_f32_e32 v204, v204, v161
	v_mul_f32_e32 v205, v205, v161
	v_mul_f32_e32 v206, v206, v161
	v_mul_f32_e32 v207, v207, v161
	v_fma_f32 v204, v96, v204, v100
	v_fma_f32 v205, v97, v205, v101
	v_fma_f32 v206, v98, v206, v102
	v_fma_f32 v207, v99, v207, v103
	v_mul_f32_e32 v204, s55, v204
	v_mul_f32_e32 v205, s55, v205
	v_mul_f32_e32 v206, s55, v206
	v_mul_f32_e32 v207, s55, v207
	v_fmac_f32_e32 v204, v226, v32
	v_fmac_f32_e32 v205, v227, v36
	v_fmac_f32_e32 v206, v228, v40
	v_fmac_f32_e32 v207, v229, v44
	v_sub_f32_e32 v208, v208, v162
	v_sub_f32_e32 v209, v209, v162
	v_sub_f32_e32 v210, v210, v162
	v_sub_f32_e32 v211, v211, v162
	v_mul_f32_e32 v208, v208, v163
	v_mul_f32_e32 v209, v209, v163
	v_mul_f32_e32 v210, v210, v163
	v_mul_f32_e32 v211, v211, v163
	v_fma_f32 v208, v96, v208, v100
	v_fma_f32 v209, v97, v209, v101
	v_fma_f32 v210, v98, v210, v102
	v_fma_f32 v211, v99, v211, v103
	v_mul_f32_e32 v208, s55, v208
	v_mul_f32_e32 v209, s55, v209
	v_mul_f32_e32 v210, s55, v210
	v_mul_f32_e32 v211, s55, v211
	v_fmac_f32_e32 v208, v226, v33
	v_fmac_f32_e32 v209, v227, v37
	v_fmac_f32_e32 v210, v228, v41
	v_fmac_f32_e32 v211, v229, v45
	v_sub_f32_e32 v212, v212, v164
	v_sub_f32_e32 v213, v213, v164
	v_sub_f32_e32 v214, v214, v164
	v_sub_f32_e32 v215, v215, v164
	v_mul_f32_e32 v212, v212, v165
	v_mul_f32_e32 v213, v213, v165
	v_mul_f32_e32 v214, v214, v165
	v_mul_f32_e32 v215, v215, v165
	v_fma_f32 v212, v96, v212, v100
	v_fma_f32 v213, v97, v213, v101
	v_fma_f32 v214, v98, v214, v102
	v_fma_f32 v215, v99, v215, v103
	v_mul_f32_e32 v212, s55, v212
	v_mul_f32_e32 v213, s55, v213
	v_mul_f32_e32 v214, s55, v214
	v_mul_f32_e32 v215, s55, v215
	v_fmac_f32_e32 v212, v226, v34
	v_fmac_f32_e32 v213, v227, v38
	v_fmac_f32_e32 v214, v228, v42
	v_fmac_f32_e32 v215, v229, v46
	v_sub_f32_e32 v216, v216, v166
	v_sub_f32_e32 v217, v217, v166
	v_sub_f32_e32 v218, v218, v166
	v_sub_f32_e32 v219, v219, v166
	v_mul_f32_e32 v216, v216, v167
	v_mul_f32_e32 v217, v217, v167
	v_mul_f32_e32 v218, v218, v167
	v_mul_f32_e32 v219, v219, v167
	v_fma_f32 v216, v96, v216, v100
	v_fma_f32 v217, v97, v217, v101
	v_fma_f32 v218, v98, v218, v102
	v_fma_f32 v219, v99, v219, v103
	v_mul_f32_e32 v216, s55, v216
	v_mul_f32_e32 v217, s55, v217
	v_mul_f32_e32 v218, s55, v218
	v_mul_f32_e32 v219, s55, v219
	v_fmac_f32_e32 v216, v226, v35
	v_fmac_f32_e32 v217, v227, v39
	v_fmac_f32_e32 v218, v228, v43
	v_fmac_f32_e32 v219, v229, v47
	s_add_u32 s4, s50, 0x20000
	s_addc_u32 s5, s51, 0
	global_store_dwordx2 v225, v[204:205], s[4:5]
	global_store_dwordx2 v225, v[206:207], s[4:5] offset:128
	s_add_u32 s4, s50, 0x21000
	s_addc_u32 s5, s51, 0
	global_store_dwordx2 v225, v[208:209], s[4:5]
	global_store_dwordx2 v225, v[210:211], s[4:5] offset:128
	s_add_u32 s4, s50, 0x22000
	s_addc_u32 s5, s51, 0
	global_store_dwordx2 v225, v[212:213], s[4:5]
	global_store_dwordx2 v225, v[214:215], s[4:5] offset:128
	s_add_u32 s4, s50, 0x23000
	s_addc_u32 s5, s51, 0
	global_store_dwordx2 v225, v[216:217], s[4:5]
	global_store_dwordx2 v225, v[218:219], s[4:5] offset:128
	s_add_u32 s4, s50, 0x50000
	s_addc_u32 s5, s51, 0
	global_load_dwordx2 v[204:205], v225, s[4:5]
	global_load_dwordx2 v[206:207], v225, s[4:5] offset:128
	s_add_u32 s4, s50, 0x51000
	s_addc_u32 s5, s51, 0
	global_load_dwordx2 v[208:209], v225, s[4:5]
	global_load_dwordx2 v[210:211], v225, s[4:5] offset:128
	s_add_u32 s4, s50, 0x52000
	s_addc_u32 s5, s51, 0
	global_load_dwordx2 v[212:213], v225, s[4:5]
	global_load_dwordx2 v[214:215], v225, s[4:5] offset:128
	s_add_u32 s4, s50, 0x53000
	s_addc_u32 s5, s51, 0
	global_load_dwordx2 v[216:217], v225, s[4:5]
	global_load_dwordx2 v[218:219], v225, s[4:5] offset:128
	s_add_u32 s4, s42, 0x2a800
	s_addc_u32 s5, s43, 0
	global_load_dwordx2 v[160:161], v131, s[4:5] offset:2048
	s_add_u32 s4, s42, 0x2b080
	s_addc_u32 s5, s43, 0
	global_load_dwordx2 v[162:163], v131, s[4:5] offset:2048
	s_add_u32 s4, s42, 0x2b900
	s_addc_u32 s5, s43, 0
	global_load_dwordx2 v[164:165], v131, s[4:5] offset:2048
	s_add_u32 s4, s42, 0x2c180
	s_addc_u32 s5, s43, 0
	global_load_dwordx2 v[166:167], v131, s[4:5] offset:2048
	s_add_u32 s4, s58, 48
	s_lshr_b32 s4, s4, 12
	s_cmp_eq_u32 s4, s59
	s_cbranch_scc1 .Lop_g3
	s_mov_b32 s59, s4
	v_mov_b32_e32 v226, v230
	v_mov_b32_e32 v227, v231
	v_mov_b32_e32 v228, v232
	v_mov_b32_e32 v229, v233
.Lop_g3:
	s_waitcnt vmcnt(40)
	s_bitcmp1_b32 s40, 8
	s_cbranch_scc0 .Lop_st3
	v_mov_b32_e32 v120, 0
	v_mov_b32_e32 v121, 1.0
	v_mov_b32_e32 v122, 0
	v_mov_b32_e32 v123, 1.0
	v_mov_b32_e32 v124, 0
	v_mov_b32_e32 v125, 1.0
	v_mov_b32_e32 v126, 0
	v_mov_b32_e32 v127, 1.0
.Lop_st3:
	v_sub_f32_e32 v104, v104, v120
	v_sub_f32_e32 v105, v105, v120
	v_sub_f32_e32 v106, v106, v120
	v_sub_f32_e32 v107, v107, v120
	v_mul_f32_e32 v104, v104, v121
	v_mul_f32_e32 v105, v105, v121
	v_mul_f32_e32 v106, v106, v121
	v_mul_f32_e32 v107, v107, v121
	v_fma_f32 v104, v96, v104, v100
	v_fma_f32 v105, v97, v105, v101
	v_fma_f32 v106, v98, v106, v102
	v_fma_f32 v107, v99, v107, v103
	v_mul_f32_e32 v104, s55, v104
	v_mul_f32_e32 v105, s55, v105
	v_mul_f32_e32 v106, s55, v106
	v_mul_f32_e32 v107, s55, v107
	v_fmac_f32_e32 v104, v226, v48
	v_fmac_f32_e32 v105, v227, v52
	v_fmac_f32_e32 v106, v228, v56
	v_fmac_f32_e32 v107, v229, v60
	v_sub_f32_e32 v108, v108, v122
	v_sub_f32_e32 v109, v109, v122
	v_sub_f32_e32 v110, v110, v122
	v_sub_f32_e32 v111, v111, v122
	v_mul_f32_e32 v108, v108, v123
	v_mul_f32_e32 v109, v109, v123
	v_mul_f32_e32 v110, v110, v123
	v_mul_f32_e32 v111, v111, v123
	v_fma_f32 v108, v96, v108, v100
	v_fma_f32 v109, v97, v109, v101
	v_fma_f32 v110, v98, v110, v102
	v_fma_f32 v111, v99, v111, v103
	v_mul_f32_e32 v108, s55, v108
	v_mul_f32_e32 v109, s55, v109
	v_mul_f32_e32 v110, s55, v110
	v_mul_f32_e32 v111, s55, v111
	v_fmac_f32_e32 v108, v226, v49
	v_fmac_f32_e32 v109, v227, v53
	v_fmac_f32_e32 v110, v228, v57
	v_fmac_f32_e32 v111, v229, v61
	v_sub_f32_e32 v112, v112, v124
	v_sub_f32_e32 v113, v113, v124
	v_sub_f32_e32 v114, v114, v124
	v_sub_f32_e32 v115, v115, v124
	v_mul_f32_e32 v112, v112, v125
	v_mul_f32_e32 v113, v113, v125
	v_mul_f32_e32 v114, v114, v125
	v_mul_f32_e32 v115, v115, v125
	v_fma_f32 v112, v96, v112, v100
	v_fma_f32 v113, v97, v113, v101
	v_fma_f32 v114, v98, v114, v102
	v_fma_f32 v115, v99, v115, v103
	v_mul_f32_e32 v112, s55, v112
	v_mul_f32_e32 v113, s55, v113
	v_mul_f32_e32 v114, s55, v114
	v_mul_f32_e32 v115, s55, v115
	v_fmac_f32_e32 v112, v226, v50
	v_fmac_f32_e32 v113, v227, v54
	v_fmac_f32_e32 v114, v228, v58
	v_fmac_f32_e32 v115, v229, v62
	v_sub_f32_e32 v116, v116, v126
	v_sub_f32_e32 v117, v117, v126
	v_sub_f32_e32 v118, v118, v126
	v_sub_f32_e32 v119, v119, v126
	v_mul_f32_e32 v116, v116, v127
	v_mul_f32_e32 v117, v117, v127
	v_mul_f32_e32 v118, v118, v127
	v_mul_f32_e32 v119, v119, v127
	v_fma_f32 v116, v96, v116, v100
	v_fma_f32 v117, v97, v117, v101
	v_fma_f32 v118, v98, v118, v102
	v_fma_f32 v119, v99, v119, v103
	v_mul_f32_e32 v116, s55, v116
	v_mul_f32_e32 v117, s55, v117
	v_mul_f32_e32 v118, s55, v118
	v_mul_f32_e32 v119, s55, v119
	v_fmac_f32_e32 v116, v226, v51
	v_fmac_f32_e32 v117, v227, v55
	v_fmac_f32_e32 v118, v228, v59
	v_fmac_f32_e32 v119, v229, v63
	s_add_u32 s4, s50, 0x30000
	s_addc_u32 s5, s51, 0
	global_store_dwordx2 v225, v[104:105], s[4:5]
	global_store_dwordx2 v225, v[106:107], s[4:5] offset:128
	s_add_u32 s4, s50, 0x31000
	s_addc_u32 s5, s51, 0
	global_store_dwordx2 v225, v[108:109], s[4:5]
	global_store_dwordx2 v225, v[110:111], s[4:5] offset:128
	s_add_u32 s4, s50, 0x32000
	s_addc_u32 s5, s51, 0
	global_store_dwordx2 v225, v[112:113], s[4:5]
	global_store_dwordx2 v225, v[114:115], s[4:5] offset:128
	s_add_u32 s4, s50, 0x33000
	s_addc_u32 s5, s51, 0
	global_store_dwordx2 v225, v[116:117], s[4:5]
	global_store_dwordx2 v225, v[118:119], s[4:5] offset:128
	s_add_u32 s4, s58, 64
	s_lshr_b32 s4, s4, 12
	s_cmp_eq_u32 s4, s59
	s_cbranch_scc1 .Lop_g4
	s_mov_b32 s59, s4
	v_mov_b32_e32 v226, v230
	v_mov_b32_e32 v227, v231
	v_mov_b32_e32 v228, v232
	v_mov_b32_e32 v229, v233
.Lop_g4:
	s_waitcnt vmcnt(28)
	s_bitcmp1_b32 s40, 8
	s_cbranch_scc0 .Lop_st4
	v_mov_b32_e32 v152, 0
	v_mov_b32_e32 v153, 1.0
	v_mov_b32_e32 v154, 0
	v_mov_b32_e32 v155, 1.0
	v_mov_b32_e32 v156, 0
	v_mov_b32_e32 v157, 1.0
	v_mov_b32_e32 v158, 0
	v_mov_b32_e32 v159, 1.0
.Lop_st4:
	v_sub_f32_e32 v136, v136, v152
	v_sub_f32_e32 v137, v137, v152
	v_sub_f32_e32 v138, v138, v152
	v_sub_f32_e32 v139, v139, v152
	v_mul_f32_e32 v136, v136, v153
	v_mul_f32_e32 v137, v137, v153
	v_mul_f32_e32 v138, v138, v153
	v_mul_f32_e32 v139, v139, v153
	v_fma_f32 v136, v96, v136, v100
	v_fma_f32 v137, v97, v137, v101
	v_fma_f32 v138, v98, v138, v102
	v_fma_f32 v139, v99, v139, v103
	v_mul_f32_e32 v136, s55, v136
	v_mul_f32_e32 v137, s55, v137
	v_mul_f32_e32 v138, s55, v138
	v_mul_f32_e32 v139, s55, v139
	v_fmac_f32_e32 v136, v226, v64
	v_fmac_f32_e32 v137, v227, v68
	v_fmac_f32_e32 v138, v228, v72
	v_fmac_f32_e32 v139, v229, v76
	v_sub_f32_e32 v140, v140, v154
	v_sub_f32_e32 v141, v141, v154
	v_sub_f32_e32 v142, v142, v154
	v_sub_f32_e32 v143, v143, v154
	v_mul_f32_e32 v140, v140, v155
	v_mul_f32_e32 v141, v141, v155
	v_mul_f32_e32 v142, v142, v155
	v_mul_f32_e32 v143, v143, v155
	v_fma_f32 v140, v96, v140, v100
	v_fma_f32 v141, v97, v141, v101
	v_fma_f32 v142, v98, v142, v102
	v_fma_f32 v143, v99, v143, v103
	v_mul_f32_e32 v140, s55, v140
	v_mul_f32_e32 v141, s55, v141
	v_mul_f32_e32 v142, s55, v142
	v_mul_f32_e32 v143, s55, v143
	v_fmac_f32_e32 v140, v226, v65
	v_fmac_f32_e32 v141, v227, v69
	v_fmac_f32_e32 v142, v228, v73
	v_fmac_f32_e32 v143, v229, v77
	v_sub_f32_e32 v144, v144, v156
	v_sub_f32_e32 v145, v145, v156
	v_sub_f32_e32 v146, v146, v156
	v_sub_f32_e32 v147, v147, v156
	v_mul_f32_e32 v144, v144, v157
	v_mul_f32_e32 v145, v145, v157
	v_mul_f32_e32 v146, v146, v157
	v_mul_f32_e32 v147, v147, v157
	v_fma_f32 v144, v96, v144, v100
	v_fma_f32 v145, v97, v145, v101
	v_fma_f32 v146, v98, v146, v102
	v_fma_f32 v147, v99, v147, v103
	v_mul_f32_e32 v144, s55, v144
	v_mul_f32_e32 v145, s55, v145
	v_mul_f32_e32 v146, s55, v146
	v_mul_f32_e32 v147, s55, v147
	v_fmac_f32_e32 v144, v226, v66
	v_fmac_f32_e32 v145, v227, v70
	v_fmac_f32_e32 v146, v228, v74
	v_fmac_f32_e32 v147, v229, v78
	v_sub_f32_e32 v148, v148, v158
	v_sub_f32_e32 v149, v149, v158
	v_sub_f32_e32 v150, v150, v158
	v_sub_f32_e32 v151, v151, v158
	v_mul_f32_e32 v148, v148, v159
	v_mul_f32_e32 v149, v149, v159
	v_mul_f32_e32 v150, v150, v159
	v_mul_f32_e32 v151, v151, v159
	v_fma_f32 v148, v96, v148, v100
	v_fma_f32 v149, v97, v149, v101
	v_fma_f32 v150, v98, v150, v102
	v_fma_f32 v151, v99, v151, v103
	v_mul_f32_e32 v148, s55, v148
	v_mul_f32_e32 v149, s55, v149
	v_mul_f32_e32 v150, s55, v150
	v_mul_f32_e32 v151, s55, v151
	v_fmac_f32_e32 v148, v226, v67
	v_fmac_f32_e32 v149, v227, v71
	v_fmac_f32_e32 v150, v228, v75
	v_fmac_f32_e32 v151, v229, v79
	s_add_u32 s4, s50, 0x40000
	s_addc_u32 s5, s51, 0
	global_store_dwordx2 v225, v[136:137], s[4:5]
	global_store_dwordx2 v225, v[138:139], s[4:5] offset:128
	s_add_u32 s4, s50, 0x41000
	s_addc_u32 s5, s51, 0
	global_store_dwordx2 v225, v[140:141], s[4:5]
	global_store_dwordx2 v225, v[142:143], s[4:5] offset:128
	s_add_u32 s4, s50, 0x42000
	s_addc_u32 s5, s51, 0
	global_store_dwordx2 v225, v[144:145], s[4:5]
	global_store_dwordx2 v225, v[146:147], s[4:5] offset:128
	s_add_u32 s4, s50, 0x43000
	s_addc_u32 s5, s51, 0
	global_store_dwordx2 v225, v[148:149], s[4:5]
	global_store_dwordx2 v225, v[150:151], s[4:5] offset:128
	s_add_u32 s4, s58, 80
	s_lshr_b32 s4, s4, 12
	s_cmp_eq_u32 s4, s59
	s_cbranch_scc1 .Lop_g5
	s_mov_b32 s59, s4
	v_mov_b32_e32 v226, v230
	v_mov_b32_e32 v227, v231
	v_mov_b32_e32 v228, v232
	v_mov_b32_e32 v229, v233
.Lop_g5:
	s_waitcnt vmcnt(16)
	s_bitcmp1_b32 s40, 8
	s_cbranch_scc0 .Lop_st5
	v_mov_b32_e32 v160, 0
	v_mov_b32_e32 v161, 1.0
	v_mov_b32_e32 v162, 0
	v_mov_b32_e32 v163, 1.0
	v_mov_b32_e32 v164, 0
	v_mov_b32_e32 v165, 1.0
	v_mov_b32_e32 v166, 0
	v_mov_b32_e32 v167, 1.0
.Lop_st5:
	v_sub_f32_e32 v204, v204, v160
	v_sub_f32_e32 v205, v205, v160
	v_sub_f32_e32 v206, v206, v160
	v_sub_f32_e32 v207, v207, v160
	v_mul_f32_e32 v204, v204, v161
	v_mul_f32_e32 v205, v205, v161
	v_mul_f32_e32 v206, v206, v161
	v_mul_f32_e32 v207, v207, v161
	v_fma_f32 v204, v96, v204, v100
	v_fma_f32 v205, v97, v205, v101
	v_fma_f32 v206, v98, v206, v102
	v_fma_f32 v207, v99, v207, v103
	v_mul_f32_e32 v204, s55, v204
	v_mul_f32_e32 v205, s55, v205
	v_mul_f32_e32 v206, s55, v206
	v_mul_f32_e32 v207, s55, v207
	v_fmac_f32_e32 v204, v226, v80
	v_fmac_f32_e32 v205, v227, v84
	v_fmac_f32_e32 v206, v228, v88
	v_fmac_f32_e32 v207, v229, v92
	v_sub_f32_e32 v208, v208, v162
	v_sub_f32_e32 v209, v209, v162
	v_sub_f32_e32 v210, v210, v162
	v_sub_f32_e32 v211, v211, v162
	v_mul_f32_e32 v208, v208, v163
	v_mul_f32_e32 v209, v209, v163
	v_mul_f32_e32 v210, v210, v163
	v_mul_f32_e32 v211, v211, v163
	v_fma_f32 v208, v96, v208, v100
	v_fma_f32 v209, v97, v209, v101
	v_fma_f32 v210, v98, v210, v102
	v_fma_f32 v211, v99, v211, v103
	v_mul_f32_e32 v208, s55, v208
	v_mul_f32_e32 v209, s55, v209
	v_mul_f32_e32 v210, s55, v210
	v_mul_f32_e32 v211, s55, v211
	v_fmac_f32_e32 v208, v226, v81
	v_fmac_f32_e32 v209, v227, v85
	v_fmac_f32_e32 v210, v228, v89
	v_fmac_f32_e32 v211, v229, v93
	v_sub_f32_e32 v212, v212, v164
	v_sub_f32_e32 v213, v213, v164
	v_sub_f32_e32 v214, v214, v164
	v_sub_f32_e32 v215, v215, v164
	v_mul_f32_e32 v212, v212, v165
	v_mul_f32_e32 v213, v213, v165
	v_mul_f32_e32 v214, v214, v165
	v_mul_f32_e32 v215, v215, v165
	v_fma_f32 v212, v96, v212, v100
	v_fma_f32 v213, v97, v213, v101
	v_fma_f32 v214, v98, v214, v102
	v_fma_f32 v215, v99, v215, v103
	v_mul_f32_e32 v212, s55, v212
	v_mul_f32_e32 v213, s55, v213
	v_mul_f32_e32 v214, s55, v214
	v_mul_f32_e32 v215, s55, v215
	v_fmac_f32_e32 v212, v226, v82
	v_fmac_f32_e32 v213, v227, v86
	v_fmac_f32_e32 v214, v228, v90
	v_fmac_f32_e32 v215, v229, v94
	v_sub_f32_e32 v216, v216, v166
	v_sub_f32_e32 v217, v217, v166
	v_sub_f32_e32 v218, v218, v166
	v_sub_f32_e32 v219, v219, v166
	v_mul_f32_e32 v216, v216, v167
	v_mul_f32_e32 v217, v217, v167
	v_mul_f32_e32 v218, v218, v167
	v_mul_f32_e32 v219, v219, v167
	v_fma_f32 v216, v96, v216, v100
	v_fma_f32 v217, v97, v217, v101
	v_fma_f32 v218, v98, v218, v102
	v_fma_f32 v219, v99, v219, v103
	v_mul_f32_e32 v216, s55, v216
	v_mul_f32_e32 v217, s55, v217
	v_mul_f32_e32 v218, s55, v218
	v_mul_f32_e32 v219, s55, v219
	v_fmac_f32_e32 v216, v226, v83
	v_fmac_f32_e32 v217, v227, v87
	v_fmac_f32_e32 v218, v228, v91
	v_fmac_f32_e32 v219, v229, v95
	s_add_u32 s4, s50, 0x50000
	s_addc_u32 s5, s51, 0
	global_store_dwordx2 v225, v[204:205], s[4:5]
	global_store_dwordx2 v225, v[206:207], s[4:5] offset:128
	s_add_u32 s4, s50, 0x51000
	s_addc_u32 s5, s51, 0
	global_store_dwordx2 v225, v[208:209], s[4:5]
	global_store_dwordx2 v225, v[210:211], s[4:5] offset:128
	s_add_u32 s4, s50, 0x52000
	s_addc_u32 s5, s51, 0
	global_store_dwordx2 v225, v[212:213], s[4:5]
	global_store_dwordx2 v225, v[214:215], s[4:5] offset:128
	s_add_u32 s4, s50, 0x53000
	s_addc_u32 s5, s51, 0
	global_store_dwordx2 v225, v[216:217], s[4:5]
	global_store_dwordx2 v225, v[218:219], s[4:5] offset:128
	s_cmp_ge_u32 s54, 0x200
	s_cbranch_scc1 .Lop_done
	s_branch .Lop_tile

.LBB0_1198:
	s_andn2_b64 vcc, exec, s[34:35]
	s_mov_b64 s[40:41], 0
	v_readlane_b32 s2, v235, 48
	s_cbranch_vccnz .LBB0_1212
	v_readlane_b32 s4, v235, 51
	s_cmp_gt_i32 s2, 0
	s_mov_b64 s[40:41], -1
	v_readlane_b32 s5, v235, 52
	s_cbranch_scc0 .LBB0_1213
	s_cmp_gt_i32 s2, 1
	s_mov_b64 s[4:5], -1
	s_cbranch_scc0 .LBB0_1419
	s_waitcnt lgkmcnt(0)
	v_mov_b32_e32 v34, v170
	v_mov_b32_e32 v0, v170
	v_readlane_b32 s4, v235, 17
	v_ashrrev_i32_e32 v33, 6, v0
	s_nop 0
	v_add_u32_e32 v32, s4, v33
	s_movk_i32 s4, 0x3000
	v_cmp_gt_i32_e32 vcc, s4, v32
	s_and_saveexec_b64 s[36:37], vcc
	s_cbranch_execz .LBB0_1420
	v_readlane_b32 s4, v235, 33
	s_cmp_lg_u32 s4, 0x200
	s_cbranch_scc1 .Llnc_orig
	v_and_b32_e32 v232, 63, v170
	v_lshlrev_b32_e32 v233, 3, v232
	v_lshlrev_b32_e32 v232, 4, v232
	v_lshrrev_b32_e32 v231, 6, v170
	s_nop 0
	v_readfirstlane_b32 s6, v231
	v_readlane_b32 s7, v237, 0
	s_lshl_b32 s7, s7, 2
	s_add_u32 s6, s6, s7
	v_readlane_b32 s8, v235, 34
	v_readlane_b32 s9, v235, 35
	v_readlane_b32 s7, v235, 44
	s_mul_i32 s10, s7, 3
	s_add_u32 s10, s10, 0
	s_lshl_b32 s10, s10, 12
	v_readlane_b32 s4, v237, 25
	v_readlane_b32 s5, v237, 26
	s_add_u32 s4, s4, s10
	s_addc_u32 s5, s5, 0
	global_load_dwordx4 v[136:139], v232, s[4:5]
	global_load_dwordx4 v[140:143], v232, s[4:5] offset:1024
	global_load_dwordx4 v[144:147], v232, s[4:5] offset:2048
	global_load_dwordx4 v[148:151], v232, s[4:5] offset:3072
	v_readlane_b32 s4, v237, 27
	v_readlane_b32 s5, v237, 28
	s_add_u32 s4, s4, s10
	s_addc_u32 s5, s5, 0
	global_load_dwordx4 v[152:155], v232, s[4:5]
	global_load_dwordx4 v[156:159], v232, s[4:5] offset:1024
	global_load_dwordx4 v[160:163], v232, s[4:5] offset:2048
	global_load_dwordx4 v[164:167], v232, s[4:5] offset:3072
	s_mov_b32 s11, s7
	s_mul_i32 s11, s11, 0x1b000
	s_add_u32 s11, s11, 0xb0fb000
	s_add_u32 s10, s8, s11
	s_addc_u32 s11, s9, 0
	s_add_u32 s4, s10, 0x0
	s_addc_u32 s5, s11, 0
	global_load_dwordx4 v[64:67], v232, s[4:5]
	global_load_dwordx4 v[68:71], v232, s[4:5] offset:1024
	global_load_dwordx4 v[72:75], v232, s[4:5] offset:2048
	global_load_dwordx4 v[76:79], v232, s[4:5] offset:3072
	s_add_u32 s4, s4, 0x1000
	s_addc_u32 s5, s5, 0
	global_load_dwordx4 v[80:83], v232, s[4:5]
	global_load_dwordx4 v[84:87], v232, s[4:5] offset:1024
	global_load_dwordx4 v[88:91], v232, s[4:5] offset:2048
	global_load_dwordx4 v[92:95], v232, s[4:5] offset:3072
	s_lshl_b32 s4, s6, 12
	s_add_u32 s4, s4, 0xb166000
	s_add_u32 s4, s4, s8
	s_addc_u32 s5, s9, 0
	global_load_dwordx4 v[0:3], v232, s[4:5]
	global_load_dwordx4 v[4:7], v232, s[4:5] offset:1024
	global_load_dwordx4 v[8:11], v232, s[4:5] offset:2048
	global_load_dwordx4 v[12:15], v232, s[4:5] offset:3072
	s_lshl_b32 s4, s6, 12
	s_add_u32 s4, s4, 0xb966000
	s_add_u32 s4, s4, s8
	s_addc_u32 s5, s9, 0
	global_load_dwordx4 v[16:19], v232, s[4:5]
	global_load_dwordx4 v[20:23], v232, s[4:5] offset:1024
	global_load_dwordx4 v[24:27], v232, s[4:5] offset:2048
	global_load_dwordx4 v[28:31], v232, s[4:5] offset:3072
	s_lshl_b32 s4, s6, 12
	s_add_u32 s4, s4, 0xc166000
	s_add_u32 s4, s4, s8
	s_addc_u32 s5, s9, 0
	global_load_dwordx4 v[32:35], v232, s[4:5]
	global_load_dwordx4 v[36:39], v232, s[4:5] offset:1024
	global_load_dwordx4 v[40:43], v232, s[4:5] offset:2048
	global_load_dwordx4 v[44:47], v232, s[4:5] offset:3072
	s_lshl_b32 s4, s6, 12
	s_add_u32 s4, s4, 0xc966000
	s_add_u32 s4, s4, s8
	s_addc_u32 s5, s9, 0
	global_load_dwordx4 v[48:51], v232, s[4:5]
	global_load_dwordx4 v[52:55], v232, s[4:5] offset:1024
	global_load_dwordx4 v[56:59], v232, s[4:5] offset:2048
	global_load_dwordx4 v[60:63], v232, s[4:5] offset:3072
	s_add_u32 s4, s10, 0x9000
	s_addc_u32 s5, s11, 0
	global_load_dwordx4 v[96:99], v232, s[4:5]
	global_load_dwordx4 v[100:103], v232, s[4:5] offset:1024
	global_load_dwordx4 v[104:107], v232, s[4:5] offset:2048
	global_load_dwordx4 v[108:111], v232, s[4:5] offset:3072
	s_add_u32 s4, s4, 0x1000
	s_addc_u32 s5, s5, 0
	global_load_dwordx4 v[112:115], v232, s[4:5]
	global_load_dwordx4 v[116:119], v232, s[4:5] offset:1024
	global_load_dwordx4 v[120:123], v232, s[4:5] offset:2048
	global_load_dwordx4 v[124:127], v232, s[4:5] offset:3072
	s_waitcnt vmcnt(16)
	v_pk_add_f32 v[204:205], v[0:1], v[2:3]
	v_pk_add_f32 v[206:207], v[4:5], v[6:7]
	v_pk_add_f32 v[208:209], v[8:9], v[10:11]
	v_pk_add_f32 v[210:211], v[12:13], v[14:15]
	v_pk_add_f32 v[216:217], v[16:17], v[18:19]
	v_pk_add_f32 v[218:219], v[20:21], v[22:23]
	v_pk_add_f32 v[220:221], v[24:25], v[26:27]
	v_pk_add_f32 v[222:223], v[28:29], v[30:31]
	v_pk_add_f32 v[204:205], v[204:205], v[206:207]
	v_pk_add_f32 v[208:209], v[208:209], v[210:211]
	v_pk_add_f32 v[216:217], v[216:217], v[218:219]
	v_pk_add_f32 v[220:221], v[220:221], v[222:223]
	v_pk_add_f32 v[204:205], v[204:205], v[208:209]
	v_pk_add_f32 v[216:217], v[216:217], v[220:221]
	v_add_f32_e32 v204, v204, v205
	v_add_f32_e32 v216, v216, v217
	s_nop 1
	v_add_f32_dpp v204, v204, v204 row_ror:1 row_mask:0xf bank_mask:0xf bound_ctrl:1
	v_add_f32_dpp v216, v216, v216 row_ror:1 row_mask:0xf bank_mask:0xf bound_ctrl:1
	s_nop 0
	v_add_f32_dpp v204, v204, v204 row_ror:2 row_mask:0xf bank_mask:0xf bound_ctrl:1
	v_add_f32_dpp v216, v216, v216 row_ror:2 row_mask:0xf bank_mask:0xf bound_ctrl:1
	s_nop 0
	v_add_f32_dpp v204, v204, v204 row_ror:4 row_mask:0xf bank_mask:0xf bound_ctrl:1
	v_add_f32_dpp v216, v216, v216 row_ror:4 row_mask:0xf bank_mask:0xf bound_ctrl:1
	s_nop 0
	v_add_f32_dpp v204, v204, v204 row_ror:8 row_mask:0xf bank_mask:0xf bound_ctrl:1
	v_add_f32_dpp v216, v216, v216 row_ror:8 row_mask:0xf bank_mask:0xf bound_ctrl:1
	s_nop 0
	v_mov_b32_e32 v205, v204
	v_mov_b32_e32 v217, v216
	s_nop 1
	v_permlane16_swap_b32_e32 v204, v205
	v_permlane16_swap_b32_e32 v216, v217
	s_nop 0
	v_add_f32_e32 v204, v204, v205
	v_add_f32_e32 v216, v216, v217
	v_mov_b32_e32 v205, v204
	v_mov_b32_e32 v217, v216
	s_nop 1
	v_permlane32_swap_b32_e32 v204, v205
	v_permlane32_swap_b32_e32 v216, v217
	s_nop 0
	v_add_f32_e32 v204, v204, v205
	v_add_f32_e32 v216, v216, v217
	v_mul_f32_e32 v212, 0x3a800000, v204
	v_mul_f32_e32 v224, 0x3a800000, v216
	v_pk_add_f32 v[0:1], v[0:1], v[212:213] op_sel_hi:[1,0] neg_lo:[0,1] neg_hi:[0,1]
	v_pk_add_f32 v[2:3], v[2:3], v[212:213] op_sel_hi:[1,0] neg_lo:[0,1] neg_hi:[0,1]
	v_pk_add_f32 v[4:5], v[4:5], v[212:213] op_sel_hi:[1,0] neg_lo:[0,1] neg_hi:[0,1]
	v_pk_add_f32 v[6:7], v[6:7], v[212:213] op_sel_hi:[1,0] neg_lo:[0,1] neg_hi:[0,1]
	v_pk_add_f32 v[8:9], v[8:9], v[212:213] op_sel_hi:[1,0] neg_lo:[0,1] neg_hi:[0,1]
	v_pk_add_f32 v[10:11], v[10:11], v[212:213] op_sel_hi:[1,0] neg_lo:[0,1] neg_hi:[0,1]
	v_pk_add_f32 v[12:13], v[12:13], v[212:213] op_sel_hi:[1,0] neg_lo:[0,1] neg_hi:[0,1]
	v_pk_add_f32 v[14:15], v[14:15], v[212:213] op_sel_hi:[1,0] neg_lo:[0,1] neg_hi:[0,1]
	v_pk_add_f32 v[16:17], v[16:17], v[224:225] op_sel_hi:[1,0] neg_lo:[0,1] neg_hi:[0,1]
	v_pk_add_f32 v[18:19], v[18:19], v[224:225] op_sel_hi:[1,0] neg_lo:[0,1] neg_hi:[0,1]
	v_pk_add_f32 v[20:21], v[20:21], v[224:225] op_sel_hi:[1,0] neg_lo:[0,1] neg_hi:[0,1]
	v_pk_add_f32 v[22:23], v[22:23], v[224:225] op_sel_hi:[1,0] neg_lo:[0,1] neg_hi:[0,1]
	v_pk_add_f32 v[24:25], v[24:25], v[224:225] op_sel_hi:[1,0] neg_lo:[0,1] neg_hi:[0,1]
	v_pk_add_f32 v[26:27], v[26:27], v[224:225] op_sel_hi:[1,0] neg_lo:[0,1] neg_hi:[0,1]
	v_pk_add_f32 v[28:29], v[28:29], v[224:225] op_sel_hi:[1,0] neg_lo:[0,1] neg_hi:[0,1]
	v_pk_add_f32 v[30:31], v[30:31], v[224:225] op_sel_hi:[1,0] neg_lo:[0,1] neg_hi:[0,1]
	v_pk_mul_f32 v[204:205], v[0:1], v[0:1]
	v_pk_mul_f32 v[206:207], v[2:3], v[2:3]
	v_pk_mul_f32 v[216:217], v[16:17], v[16:17]
	v_pk_mul_f32 v[218:219], v[18:19], v[18:19]
	v_pk_fma_f32 v[204:205], v[4:5], v[4:5], v[204:205]
	v_pk_fma_f32 v[206:207], v[6:7], v[6:7], v[206:207]
	v_pk_fma_f32 v[216:217], v[20:21], v[20:21], v[216:217]
	v_pk_fma_f32 v[218:219], v[22:23], v[22:23], v[218:219]
	v_pk_fma_f32 v[204:205], v[8:9], v[8:9], v[204:205]
	v_pk_fma_f32 v[206:207], v[10:11], v[10:11], v[206:207]
	v_pk_fma_f32 v[216:217], v[24:25], v[24:25], v[216:217]
	v_pk_fma_f32 v[218:219], v[26:27], v[26:27], v[218:219]
	v_pk_fma_f32 v[204:205], v[12:13], v[12:13], v[204:205]
	v_pk_fma_f32 v[206:207], v[14:15], v[14:15], v[206:207]
	v_pk_fma_f32 v[216:217], v[28:29], v[28:29], v[216:217]
	v_pk_fma_f32 v[218:219], v[30:31], v[30:31], v[218:219]
	v_pk_add_f32 v[204:205], v[204:205], v[206:207]
	v_pk_add_f32 v[216:217], v[216:217], v[218:219]
	v_add_f32_e32 v204, v204, v205
	v_add_f32_e32 v216, v216, v217
	s_nop 1
	v_add_f32_dpp v204, v204, v204 row_ror:1 row_mask:0xf bank_mask:0xf bound_ctrl:1
	v_add_f32_dpp v216, v216, v216 row_ror:1 row_mask:0xf bank_mask:0xf bound_ctrl:1
	s_nop 0
	v_add_f32_dpp v204, v204, v204 row_ror:2 row_mask:0xf bank_mask:0xf bound_ctrl:1
	v_add_f32_dpp v216, v216, v216 row_ror:2 row_mask:0xf bank_mask:0xf bound_ctrl:1
	s_nop 0
	v_add_f32_dpp v204, v204, v204 row_ror:4 row_mask:0xf bank_mask:0xf bound_ctrl:1
	v_add_f32_dpp v216, v216, v216 row_ror:4 row_mask:0xf bank_mask:0xf bound_ctrl:1
	s_nop 0
	v_add_f32_dpp v204, v204, v204 row_ror:8 row_mask:0xf bank_mask:0xf bound_ctrl:1
	v_add_f32_dpp v216, v216, v216 row_ror:8 row_mask:0xf bank_mask:0xf bound_ctrl:1
	s_nop 0
	v_mov_b32_e32 v205, v204
	v_mov_b32_e32 v217, v216
	s_nop 1
	v_permlane16_swap_b32_e32 v204, v205
	v_permlane16_swap_b32_e32 v216, v217
	s_nop 0
	v_add_f32_e32 v204, v204, v205
	v_add_f32_e32 v216, v216, v217
	v_mov_b32_e32 v205, v204
	v_mov_b32_e32 v217, v216
	s_nop 1
	v_permlane32_swap_b32_e32 v204, v205
	v_permlane32_swap_b32_e32 v216, v217
	s_nop 0
	v_add_f32_e32 v204, v204, v205
	v_add_f32_e32 v216, v216, v217
	v_mov_b32_e32 v205, 0x3727c5ac
	v_fmac_f32_e32 v205, 0x3a800000, v204
	v_mov_b32_e32 v217, 0x3727c5ac
	v_fmac_f32_e32 v217, 0x3a800000, v216
	v_mul_f32_e32 v206, 0x4b800000, v205
	s_mov_b32 s4, 0x800000
	v_cmp_gt_f32_e32 vcc, s4, v205
	s_nop 1
	v_cndmask_b32_e32 v205, v205, v206, vcc
	v_rsq_f32_e32 v205, v205
	s_nop 0
	v_mul_f32_e32 v206, 0x45800000, v205
	v_cndmask_b32_e32 v214, v205, v206, vcc
	v_mul_f32_e32 v218, 0x4b800000, v217
	s_mov_b32 s4, 0x800000
	v_cmp_gt_f32_e32 vcc, s4, v217
	s_nop 1
	v_cndmask_b32_e32 v217, v217, v218, vcc
	v_rsq_f32_e32 v217, v217
	s_nop 0
	v_mul_f32_e32 v218, 0x45800000, v217
	v_cndmask_b32_e32 v226, v217, v218, vcc
	v_pk_mul_f32 v[0:1], v[0:1], v[214:215] op_sel_hi:[1,0]
	v_pk_mul_f32 v[2:3], v[2:3], v[214:215] op_sel_hi:[1,0]
	v_pk_mul_f32 v[4:5], v[4:5], v[214:215] op_sel_hi:[1,0]
	v_pk_mul_f32 v[6:7], v[6:7], v[214:215] op_sel_hi:[1,0]
	v_pk_mul_f32 v[8:9], v[8:9], v[214:215] op_sel_hi:[1,0]
	v_pk_mul_f32 v[10:11], v[10:11], v[214:215] op_sel_hi:[1,0]
	v_pk_mul_f32 v[12:13], v[12:13], v[214:215] op_sel_hi:[1,0]
	v_pk_mul_f32 v[14:15], v[14:15], v[214:215] op_sel_hi:[1,0]
	v_pk_mul_f32 v[16:17], v[16:17], v[226:227] op_sel_hi:[1,0]
	v_pk_mul_f32 v[18:19], v[18:19], v[226:227] op_sel_hi:[1,0]
	v_pk_mul_f32 v[20:21], v[20:21], v[226:227] op_sel_hi:[1,0]
	v_pk_mul_f32 v[22:23], v[22:23], v[226:227] op_sel_hi:[1,0]
	v_pk_mul_f32 v[24:25], v[24:25], v[226:227] op_sel_hi:[1,0]
	v_pk_mul_f32 v[26:27], v[26:27], v[226:227] op_sel_hi:[1,0]
	v_pk_mul_f32 v[28:29], v[28:29], v[226:227] op_sel_hi:[1,0]
	v_pk_mul_f32 v[30:31], v[30:31], v[226:227] op_sel_hi:[1,0]
	v_pk_fma_f32 v[0:1], v[136:137], v[0:1], v[152:153]
	v_pk_fma_f32 v[2:3], v[138:139], v[2:3], v[154:155]
	v_pk_fma_f32 v[4:5], v[140:141], v[4:5], v[156:157]
	v_pk_fma_f32 v[6:7], v[142:143], v[6:7], v[158:159]
	v_pk_fma_f32 v[8:9], v[144:145], v[8:9], v[160:161]
	v_pk_fma_f32 v[10:11], v[146:147], v[10:11], v[162:163]
	v_pk_fma_f32 v[12:13], v[148:149], v[12:13], v[164:165]
	v_pk_fma_f32 v[14:15], v[150:151], v[14:15], v[166:167]
	v_pk_fma_f32 v[16:17], v[136:137], v[16:17], v[152:153]
	v_pk_fma_f32 v[18:19], v[138:139], v[18:19], v[154:155]
	v_pk_fma_f32 v[20:21], v[140:141], v[20:21], v[156:157]
	v_pk_fma_f32 v[22:23], v[142:143], v[22:23], v[158:159]
	v_pk_fma_f32 v[24:25], v[144:145], v[24:25], v[160:161]
	v_pk_fma_f32 v[26:27], v[146:147], v[26:27], v[162:163]
	v_pk_fma_f32 v[28:29], v[148:149], v[28:29], v[164:165]
	v_pk_fma_f32 v[30:31], v[150:151], v[30:31], v[166:167]
	v_mov_b32_e32 v228, v212
	v_mov_b32_e32 v229, v214
	v_mov_b32_e32 v168, v224
	v_mov_b32_e32 v169, v226
	v_add_f32_e32 v80, 1.0, v80
	v_add_f32_e32 v81, 1.0, v81
	v_add_f32_e32 v82, 1.0, v82
	v_add_f32_e32 v83, 1.0, v83
	v_add_f32_e32 v84, 1.0, v84
	v_add_f32_e32 v85, 1.0, v85
	v_add_f32_e32 v86, 1.0, v86
	v_add_f32_e32 v87, 1.0, v87
	v_add_f32_e32 v88, 1.0, v88
	v_add_f32_e32 v89, 1.0, v89
	v_add_f32_e32 v90, 1.0, v90
	v_add_f32_e32 v91, 1.0, v91
	v_add_f32_e32 v92, 1.0, v92
	v_add_f32_e32 v93, 1.0, v93
	v_add_f32_e32 v94, 1.0, v94
	v_add_f32_e32 v95, 1.0, v95
	v_pk_fma_f32 v[204:205], v[80:81], v[0:1], v[64:65]
	v_pk_fma_f32 v[206:207], v[82:83], v[2:3], v[66:67]
	v_pk_fma_f32 v[208:209], v[84:85], v[4:5], v[68:69]
	v_pk_fma_f32 v[210:211], v[86:87], v[6:7], v[70:71]
	v_pk_fma_f32 v[212:213], v[88:89], v[8:9], v[72:73]
	v_pk_fma_f32 v[214:215], v[90:91], v[10:11], v[74:75]
	v_pk_fma_f32 v[216:217], v[92:93], v[12:13], v[76:77]
	v_pk_fma_f32 v[218:219], v[94:95], v[14:15], v[78:79]
	v_cvt_pk_bf16_f32 v220, v204, v205
	v_cvt_pk_bf16_f32 v221, v206, v207
	v_cvt_pk_bf16_f32 v222, v208, v209
	v_cvt_pk_bf16_f32 v223, v210, v211
	v_cvt_pk_bf16_f32 v224, v212, v213
	v_cvt_pk_bf16_f32 v225, v214, v215
	v_cvt_pk_bf16_f32 v226, v216, v217
	v_cvt_pk_bf16_f32 v227, v218, v219
	s_mul_i32 s4, s6, 0x880
	s_add_u32 s4, s4, 0xe166000
	s_add_u32 s4, s4, s8
	s_addc_u32 s5, s9, 0
	global_store_dwordx2 v233, v[220:221], s[4:5]
	global_store_dwordx2 v233, v[222:223], s[4:5] offset:512
	global_store_dwordx2 v233, v[224:225], s[4:5] offset:1024
	global_store_dwordx2 v233, v[226:227], s[4:5] offset:1536
	s_mov_b64 s[12:13], exec
	s_mov_b64 exec, 1
	global_store_dwordx2 v129, v[228:229], s[4:5] offset:2048
	s_mov_b64 exec, s[12:13]
	v_pk_fma_f32 v[204:205], v[80:81], v[16:17], v[64:65]
	v_pk_fma_f32 v[206:207], v[82:83], v[18:19], v[66:67]
	v_pk_fma_f32 v[208:209], v[84:85], v[20:21], v[68:69]
	v_pk_fma_f32 v[210:211], v[86:87], v[22:23], v[70:71]
	v_pk_fma_f32 v[212:213], v[88:89], v[24:25], v[72:73]
	v_pk_fma_f32 v[214:215], v[90:91], v[26:27], v[74:75]
	v_pk_fma_f32 v[216:217], v[92:93], v[28:29], v[76:77]
	v_pk_fma_f32 v[218:219], v[94:95], v[30:31], v[78:79]
	v_cvt_pk_bf16_f32 v220, v204, v205
	v_cvt_pk_bf16_f32 v221, v206, v207
	v_cvt_pk_bf16_f32 v222, v208, v209
	v_cvt_pk_bf16_f32 v223, v210, v211
	v_cvt_pk_bf16_f32 v224, v212, v213
	v_cvt_pk_bf16_f32 v225, v214, v215
	v_cvt_pk_bf16_f32 v226, v216, v217
	v_cvt_pk_bf16_f32 v227, v218, v219
	s_mul_i32 s4, s6, 0x880
	s_add_u32 s4, s4, 0xe5a6000
	s_add_u32 s4, s4, s8
	s_addc_u32 s5, s9, 0
	global_store_dwordx2 v233, v[220:221], s[4:5]
	global_store_dwordx2 v233, v[222:223], s[4:5] offset:512
	global_store_dwordx2 v233, v[224:225], s[4:5] offset:1024
	global_store_dwordx2 v233, v[226:227], s[4:5] offset:1536
	s_mov_b64 s[12:13], exec
	s_mov_b64 exec, 1
	global_store_dwordx2 v129, v[168:169], s[4:5] offset:2048
	s_mov_b64 exec, s[12:13]
	s_lshl_b32 s4, s6, 12
	s_add_u32 s4, s4, 0xd166000
	s_add_u32 s4, s4, s8
	s_addc_u32 s5, s9, 0
	global_load_dwordx4 v[0:3], v232, s[4:5]
	global_load_dwordx4 v[4:7], v232, s[4:5] offset:1024
	global_load_dwordx4 v[8:11], v232, s[4:5] offset:2048
	global_load_dwordx4 v[12:15], v232, s[4:5] offset:3072
	s_lshl_b32 s4, s6, 12
	s_add_u32 s4, s4, 0xd966000
	s_add_u32 s4, s4, s8
	s_addc_u32 s5, s9, 0
	global_load_dwordx4 v[16:19], v232, s[4:5]
	global_load_dwordx4 v[20:23], v232, s[4:5] offset:1024
	global_load_dwordx4 v[24:27], v232, s[4:5] offset:2048
	global_load_dwordx4 v[28:31], v232, s[4:5] offset:3072
	s_add_u32 s4, s10, 0x12000
	s_addc_u32 s5, s11, 0
	global_load_dwordx4 v[64:67], v232, s[4:5]
	global_load_dwordx4 v[68:71], v232, s[4:5] offset:1024
	global_load_dwordx4 v[72:75], v232, s[4:5] offset:2048
	global_load_dwordx4 v[76:79], v232, s[4:5] offset:3072
	s_add_u32 s4, s4, 0x1000
	s_addc_u32 s5, s5, 0
	global_load_dwordx4 v[80:83], v232, s[4:5]
	global_load_dwordx4 v[84:87], v232, s[4:5] offset:1024
	global_load_dwordx4 v[88:91], v232, s[4:5] offset:2048
	global_load_dwordx4 v[92:95], v232, s[4:5] offset:3072
	s_waitcnt vmcnt(26)
	v_pk_add_f32 v[204:205], v[32:33], v[34:35]
	v_pk_add_f32 v[206:207], v[36:37], v[38:39]
	v_pk_add_f32 v[208:209], v[40:41], v[42:43]
	v_pk_add_f32 v[210:211], v[44:45], v[46:47]
	v_pk_add_f32 v[216:217], v[48:49], v[50:51]
	v_pk_add_f32 v[218:219], v[52:53], v[54:55]
	v_pk_add_f32 v[220:221], v[56:57], v[58:59]
	v_pk_add_f32 v[222:223], v[60:61], v[62:63]
	v_pk_add_f32 v[204:205], v[204:205], v[206:207]
	v_pk_add_f32 v[208:209], v[208:209], v[210:211]
	v_pk_add_f32 v[216:217], v[216:217], v[218:219]
	v_pk_add_f32 v[220:221], v[220:221], v[222:223]
	v_pk_add_f32 v[204:205], v[204:205], v[208:209]
	v_pk_add_f32 v[216:217], v[216:217], v[220:221]
	v_add_f32_e32 v204, v204, v205
	v_add_f32_e32 v216, v216, v217
	s_nop 1
	v_add_f32_dpp v204, v204, v204 row_ror:1 row_mask:0xf bank_mask:0xf bound_ctrl:1
	v_add_f32_dpp v216, v216, v216 row_ror:1 row_mask:0xf bank_mask:0xf bound_ctrl:1
	s_nop 0
	v_add_f32_dpp v204, v204, v204 row_ror:2 row_mask:0xf bank_mask:0xf bound_ctrl:1
	v_add_f32_dpp v216, v216, v216 row_ror:2 row_mask:0xf bank_mask:0xf bound_ctrl:1
	s_nop 0
	v_add_f32_dpp v204, v204, v204 row_ror:4 row_mask:0xf bank_mask:0xf bound_ctrl:1
	v_add_f32_dpp v216, v216, v216 row_ror:4 row_mask:0xf bank_mask:0xf bound_ctrl:1
	s_nop 0
	v_add_f32_dpp v204, v204, v204 row_ror:8 row_mask:0xf bank_mask:0xf bound_ctrl:1
	v_add_f32_dpp v216, v216, v216 row_ror:8 row_mask:0xf bank_mask:0xf bound_ctrl:1
	s_nop 0
	v_mov_b32_e32 v205, v204
	v_mov_b32_e32 v217, v216
	s_nop 1
	v_permlane16_swap_b32_e32 v204, v205
	v_permlane16_swap_b32_e32 v216, v217
	s_nop 0
	v_add_f32_e32 v204, v204, v205
	v_add_f32_e32 v216, v216, v217
	v_mov_b32_e32 v205, v204
	v_mov_b32_e32 v217, v216
	s_nop 1
	v_permlane32_swap_b32_e32 v204, v205
	v_permlane32_swap_b32_e32 v216, v217
	s_nop 0
	v_add_f32_e32 v204, v204, v205
	v_add_f32_e32 v216, v216, v217
	v_mul_f32_e32 v212, 0x3a800000, v204
	v_mul_f32_e32 v224, 0x3a800000, v216
	v_pk_add_f32 v[32:33], v[32:33], v[212:213] op_sel_hi:[1,0] neg_lo:[0,1] neg_hi:[0,1]
	v_pk_add_f32 v[34:35], v[34:35], v[212:213] op_sel_hi:[1,0] neg_lo:[0,1] neg_hi:[0,1]
	v_pk_add_f32 v[36:37], v[36:37], v[212:213] op_sel_hi:[1,0] neg_lo:[0,1] neg_hi:[0,1]
	v_pk_add_f32 v[38:39], v[38:39], v[212:213] op_sel_hi:[1,0] neg_lo:[0,1] neg_hi:[0,1]
	v_pk_add_f32 v[40:41], v[40:41], v[212:213] op_sel_hi:[1,0] neg_lo:[0,1] neg_hi:[0,1]
	v_pk_add_f32 v[42:43], v[42:43], v[212:213] op_sel_hi:[1,0] neg_lo:[0,1] neg_hi:[0,1]
	v_pk_add_f32 v[44:45], v[44:45], v[212:213] op_sel_hi:[1,0] neg_lo:[0,1] neg_hi:[0,1]
	v_pk_add_f32 v[46:47], v[46:47], v[212:213] op_sel_hi:[1,0] neg_lo:[0,1] neg_hi:[0,1]
	v_pk_add_f32 v[48:49], v[48:49], v[224:225] op_sel_hi:[1,0] neg_lo:[0,1] neg_hi:[0,1]
	v_pk_add_f32 v[50:51], v[50:51], v[224:225] op_sel_hi:[1,0] neg_lo:[0,1] neg_hi:[0,1]
	v_pk_add_f32 v[52:53], v[52:53], v[224:225] op_sel_hi:[1,0] neg_lo:[0,1] neg_hi:[0,1]
	v_pk_add_f32 v[54:55], v[54:55], v[224:225] op_sel_hi:[1,0] neg_lo:[0,1] neg_hi:[0,1]
	v_pk_add_f32 v[56:57], v[56:57], v[224:225] op_sel_hi:[1,0] neg_lo:[0,1] neg_hi:[0,1]
	v_pk_add_f32 v[58:59], v[58:59], v[224:225] op_sel_hi:[1,0] neg_lo:[0,1] neg_hi:[0,1]
	v_pk_add_f32 v[60:61], v[60:61], v[224:225] op_sel_hi:[1,0] neg_lo:[0,1] neg_hi:[0,1]
	v_pk_add_f32 v[62:63], v[62:63], v[224:225] op_sel_hi:[1,0] neg_lo:[0,1] neg_hi:[0,1]
	v_pk_mul_f32 v[204:205], v[32:33], v[32:33]
	v_pk_mul_f32 v[206:207], v[34:35], v[34:35]
	v_pk_mul_f32 v[216:217], v[48:49], v[48:49]
	v_pk_mul_f32 v[218:219], v[50:51], v[50:51]
	v_pk_fma_f32 v[204:205], v[36:37], v[36:37], v[204:205]
	v_pk_fma_f32 v[206:207], v[38:39], v[38:39], v[206:207]
	v_pk_fma_f32 v[216:217], v[52:53], v[52:53], v[216:217]
	v_pk_fma_f32 v[218:219], v[54:55], v[54:55], v[218:219]
	v_pk_fma_f32 v[204:205], v[40:41], v[40:41], v[204:205]
	v_pk_fma_f32 v[206:207], v[42:43], v[42:43], v[206:207]
	v_pk_fma_f32 v[216:217], v[56:57], v[56:57], v[216:217]
	v_pk_fma_f32 v[218:219], v[58:59], v[58:59], v[218:219]
	v_pk_fma_f32 v[204:205], v[44:45], v[44:45], v[204:205]
	v_pk_fma_f32 v[206:207], v[46:47], v[46:47], v[206:207]
	v_pk_fma_f32 v[216:217], v[60:61], v[60:61], v[216:217]
	v_pk_fma_f32 v[218:219], v[62:63], v[62:63], v[218:219]
	v_pk_add_f32 v[204:205], v[204:205], v[206:207]
	v_pk_add_f32 v[216:217], v[216:217], v[218:219]
	v_add_f32_e32 v204, v204, v205
	v_add_f32_e32 v216, v216, v217
	s_nop 1
	v_add_f32_dpp v204, v204, v204 row_ror:1 row_mask:0xf bank_mask:0xf bound_ctrl:1
	v_add_f32_dpp v216, v216, v216 row_ror:1 row_mask:0xf bank_mask:0xf bound_ctrl:1
	s_nop 0
	v_add_f32_dpp v204, v204, v204 row_ror:2 row_mask:0xf bank_mask:0xf bound_ctrl:1
	v_add_f32_dpp v216, v216, v216 row_ror:2 row_mask:0xf bank_mask:0xf bound_ctrl:1
	s_nop 0
	v_add_f32_dpp v204, v204, v204 row_ror:4 row_mask:0xf bank_mask:0xf bound_ctrl:1
	v_add_f32_dpp v216, v216, v216 row_ror:4 row_mask:0xf bank_mask:0xf bound_ctrl:1
	s_nop 0
	v_add_f32_dpp v204, v204, v204 row_ror:8 row_mask:0xf bank_mask:0xf bound_ctrl:1
	v_add_f32_dpp v216, v216, v216 row_ror:8 row_mask:0xf bank_mask:0xf bound_ctrl:1
	s_nop 0
	v_mov_b32_e32 v205, v204
	v_mov_b32_e32 v217, v216
	s_nop 1
	v_permlane16_swap_b32_e32 v204, v205
	v_permlane16_swap_b32_e32 v216, v217
	s_nop 0
	v_add_f32_e32 v204, v204, v205
	v_add_f32_e32 v216, v216, v217
	v_mov_b32_e32 v205, v204
	v_mov_b32_e32 v217, v216
	s_nop 1
	v_permlane32_swap_b32_e32 v204, v205
	v_permlane32_swap_b32_e32 v216, v217
	s_nop 0
	v_add_f32_e32 v204, v204, v205
	v_add_f32_e32 v216, v216, v217
	v_mov_b32_e32 v205, 0x3727c5ac
	v_fmac_f32_e32 v205, 0x3a800000, v204
	v_mov_b32_e32 v217, 0x3727c5ac
	v_fmac_f32_e32 v217, 0x3a800000, v216
	v_mul_f32_e32 v206, 0x4b800000, v205
	s_mov_b32 s4, 0x800000
	v_cmp_gt_f32_e32 vcc, s4, v205
	s_nop 1
	v_cndmask_b32_e32 v205, v205, v206, vcc
	v_rsq_f32_e32 v205, v205
	s_nop 0
	v_mul_f32_e32 v206, 0x45800000, v205
	v_cndmask_b32_e32 v214, v205, v206, vcc
	v_mul_f32_e32 v218, 0x4b800000, v217
	s_mov_b32 s4, 0x800000
	v_cmp_gt_f32_e32 vcc, s4, v217
	s_nop 1
	v_cndmask_b32_e32 v217, v217, v218, vcc
	v_rsq_f32_e32 v217, v217
	s_nop 0
	v_mul_f32_e32 v218, 0x45800000, v217
	v_cndmask_b32_e32 v226, v217, v218, vcc
	v_pk_mul_f32 v[32:33], v[32:33], v[214:215] op_sel_hi:[1,0]
	v_pk_mul_f32 v[34:35], v[34:35], v[214:215] op_sel_hi:[1,0]
	v_pk_mul_f32 v[36:37], v[36:37], v[214:215] op_sel_hi:[1,0]
	v_pk_mul_f32 v[38:39], v[38:39], v[214:215] op_sel_hi:[1,0]
	v_pk_mul_f32 v[40:41], v[40:41], v[214:215] op_sel_hi:[1,0]
	v_pk_mul_f32 v[42:43], v[42:43], v[214:215] op_sel_hi:[1,0]
	v_pk_mul_f32 v[44:45], v[44:45], v[214:215] op_sel_hi:[1,0]
	v_pk_mul_f32 v[46:47], v[46:47], v[214:215] op_sel_hi:[1,0]
	v_pk_mul_f32 v[48:49], v[48:49], v[226:227] op_sel_hi:[1,0]
	v_pk_mul_f32 v[50:51], v[50:51], v[226:227] op_sel_hi:[1,0]
	v_pk_mul_f32 v[52:53], v[52:53], v[226:227] op_sel_hi:[1,0]
	v_pk_mul_f32 v[54:55], v[54:55], v[226:227] op_sel_hi:[1,0]
	v_pk_mul_f32 v[56:57], v[56:57], v[226:227] op_sel_hi:[1,0]
	v_pk_mul_f32 v[58:59], v[58:59], v[226:227] op_sel_hi:[1,0]
	v_pk_mul_f32 v[60:61], v[60:61], v[226:227] op_sel_hi:[1,0]
	v_pk_mul_f32 v[62:63], v[62:63], v[226:227] op_sel_hi:[1,0]
	v_pk_fma_f32 v[32:33], v[136:137], v[32:33], v[152:153]
	v_pk_fma_f32 v[34:35], v[138:139], v[34:35], v[154:155]
	v_pk_fma_f32 v[36:37], v[140:141], v[36:37], v[156:157]
	v_pk_fma_f32 v[38:39], v[142:143], v[38:39], v[158:159]
	v_pk_fma_f32 v[40:41], v[144:145], v[40:41], v[160:161]
	v_pk_fma_f32 v[42:43], v[146:147], v[42:43], v[162:163]
	v_pk_fma_f32 v[44:45], v[148:149], v[44:45], v[164:165]
	v_pk_fma_f32 v[46:47], v[150:151], v[46:47], v[166:167]
	v_pk_fma_f32 v[48:49], v[136:137], v[48:49], v[152:153]
	v_pk_fma_f32 v[50:51], v[138:139], v[50:51], v[154:155]
	v_pk_fma_f32 v[52:53], v[140:141], v[52:53], v[156:157]
	v_pk_fma_f32 v[54:55], v[142:143], v[54:55], v[158:159]
	v_pk_fma_f32 v[56:57], v[144:145], v[56:57], v[160:161]
	v_pk_fma_f32 v[58:59], v[146:147], v[58:59], v[162:163]
	v_pk_fma_f32 v[60:61], v[148:149], v[60:61], v[164:165]
	v_pk_fma_f32 v[62:63], v[150:151], v[62:63], v[166:167]
	v_mov_b32_e32 v228, v212
	v_mov_b32_e32 v229, v214
	v_mov_b32_e32 v168, v224
	v_mov_b32_e32 v169, v226
	v_add_f32_e32 v112, 1.0, v112
	v_add_f32_e32 v113, 1.0, v113
	v_add_f32_e32 v114, 1.0, v114
	v_add_f32_e32 v115, 1.0, v115
	v_add_f32_e32 v116, 1.0, v116
	v_add_f32_e32 v117, 1.0, v117
	v_add_f32_e32 v118, 1.0, v118
	v_add_f32_e32 v119, 1.0, v119
	v_add_f32_e32 v120, 1.0, v120
	v_add_f32_e32 v121, 1.0, v121
	v_add_f32_e32 v122, 1.0, v122
	v_add_f32_e32 v123, 1.0, v123
	v_add_f32_e32 v124, 1.0, v124
	v_add_f32_e32 v125, 1.0, v125
	v_add_f32_e32 v126, 1.0, v126
	v_add_f32_e32 v127, 1.0, v127
	v_pk_fma_f32 v[204:205], v[112:113], v[32:33], v[96:97]
	v_pk_fma_f32 v[206:207], v[114:115], v[34:35], v[98:99]
	v_pk_fma_f32 v[208:209], v[116:117], v[36:37], v[100:101]
	v_pk_fma_f32 v[210:211], v[118:119], v[38:39], v[102:103]
	v_pk_fma_f32 v[212:213], v[120:121], v[40:41], v[104:105]
	v_pk_fma_f32 v[214:215], v[122:123], v[42:43], v[106:107]
	v_pk_fma_f32 v[216:217], v[124:125], v[44:45], v[108:109]
	v_pk_fma_f32 v[218:219], v[126:127], v[46:47], v[110:111]
	v_cvt_pk_bf16_f32 v220, v204, v205
	v_cvt_pk_bf16_f32 v221, v206, v207
	v_cvt_pk_bf16_f32 v222, v208, v209
	v_cvt_pk_bf16_f32 v223, v210, v211
	v_cvt_pk_bf16_f32 v224, v212, v213
	v_cvt_pk_bf16_f32 v225, v214, v215
	v_cvt_pk_bf16_f32 v226, v216, v217
	v_cvt_pk_bf16_f32 v227, v218, v219
	s_mul_i32 s4, s6, 0x880
	s_add_u32 s4, s4, 0xe9e6000
	s_add_u32 s4, s4, s8
	s_addc_u32 s5, s9, 0
	global_store_dwordx2 v233, v[220:221], s[4:5]
	global_store_dwordx2 v233, v[222:223], s[4:5] offset:512
	global_store_dwordx2 v233, v[224:225], s[4:5] offset:1024
	global_store_dwordx2 v233, v[226:227], s[4:5] offset:1536
	s_mov_b64 s[12:13], exec
	s_mov_b64 exec, 1
	global_store_dwordx2 v129, v[228:229], s[4:5] offset:2048
	s_mov_b64 exec, s[12:13]
	v_pk_fma_f32 v[204:205], v[112:113], v[48:49], v[96:97]
	v_pk_fma_f32 v[206:207], v[114:115], v[50:51], v[98:99]
	v_pk_fma_f32 v[208:209], v[116:117], v[52:53], v[100:101]
	v_pk_fma_f32 v[210:211], v[118:119], v[54:55], v[102:103]
	v_pk_fma_f32 v[212:213], v[120:121], v[56:57], v[104:105]
	v_pk_fma_f32 v[214:215], v[122:123], v[58:59], v[106:107]
	v_pk_fma_f32 v[216:217], v[124:125], v[60:61], v[108:109]
	v_pk_fma_f32 v[218:219], v[126:127], v[62:63], v[110:111]
	v_cvt_pk_bf16_f32 v220, v204, v205
	v_cvt_pk_bf16_f32 v221, v206, v207
	v_cvt_pk_bf16_f32 v222, v208, v209
	v_cvt_pk_bf16_f32 v223, v210, v211
	v_cvt_pk_bf16_f32 v224, v212, v213
	v_cvt_pk_bf16_f32 v225, v214, v215
	v_cvt_pk_bf16_f32 v226, v216, v217
	v_cvt_pk_bf16_f32 v227, v218, v219
	s_mul_i32 s4, s6, 0x880
	s_add_u32 s4, s4, 0xee26000
	s_add_u32 s4, s4, s8
	s_addc_u32 s5, s9, 0
	global_store_dwordx2 v233, v[220:221], s[4:5]
	global_store_dwordx2 v233, v[222:223], s[4:5] offset:512
	global_store_dwordx2 v233, v[224:225], s[4:5] offset:1024
	global_store_dwordx2 v233, v[226:227], s[4:5] offset:1536
	s_mov_b64 s[12:13], exec
	s_mov_b64 exec, 1
	global_store_dwordx2 v129, v[168:169], s[4:5] offset:2048
	s_mov_b64 exec, s[12:13]
	s_waitcnt vmcnt(10)
	v_pk_add_f32 v[204:205], v[0:1], v[2:3]
	v_pk_add_f32 v[206:207], v[4:5], v[6:7]
	v_pk_add_f32 v[208:209], v[8:9], v[10:11]
	v_pk_add_f32 v[210:211], v[12:13], v[14:15]
	v_pk_add_f32 v[216:217], v[16:17], v[18:19]
	v_pk_add_f32 v[218:219], v[20:21], v[22:23]
	v_pk_add_f32 v[220:221], v[24:25], v[26:27]
	v_pk_add_f32 v[222:223], v[28:29], v[30:31]
	v_pk_add_f32 v[204:205], v[204:205], v[206:207]
	v_pk_add_f32 v[208:209], v[208:209], v[210:211]
	v_pk_add_f32 v[216:217], v[216:217], v[218:219]
	v_pk_add_f32 v[220:221], v[220:221], v[222:223]
	v_pk_add_f32 v[204:205], v[204:205], v[208:209]
	v_pk_add_f32 v[216:217], v[216:217], v[220:221]
	v_add_f32_e32 v204, v204, v205
	v_add_f32_e32 v216, v216, v217
	s_nop 1
	v_add_f32_dpp v204, v204, v204 row_ror:1 row_mask:0xf bank_mask:0xf bound_ctrl:1
	v_add_f32_dpp v216, v216, v216 row_ror:1 row_mask:0xf bank_mask:0xf bound_ctrl:1
	s_nop 0
	v_add_f32_dpp v204, v204, v204 row_ror:2 row_mask:0xf bank_mask:0xf bound_ctrl:1
	v_add_f32_dpp v216, v216, v216 row_ror:2 row_mask:0xf bank_mask:0xf bound_ctrl:1
	s_nop 0
	v_add_f32_dpp v204, v204, v204 row_ror:4 row_mask:0xf bank_mask:0xf bound_ctrl:1
	v_add_f32_dpp v216, v216, v216 row_ror:4 row_mask:0xf bank_mask:0xf bound_ctrl:1
	s_nop 0
	v_add_f32_dpp v204, v204, v204 row_ror:8 row_mask:0xf bank_mask:0xf bound_ctrl:1
	v_add_f32_dpp v216, v216, v216 row_ror:8 row_mask:0xf bank_mask:0xf bound_ctrl:1
	s_nop 0
	v_mov_b32_e32 v205, v204
	v_mov_b32_e32 v217, v216
	s_nop 1
	v_permlane16_swap_b32_e32 v204, v205
	v_permlane16_swap_b32_e32 v216, v217
	s_nop 0
	v_add_f32_e32 v204, v204, v205
	v_add_f32_e32 v216, v216, v217
	v_mov_b32_e32 v205, v204
	v_mov_b32_e32 v217, v216
	s_nop 1
	v_permlane32_swap_b32_e32 v204, v205
	v_permlane32_swap_b32_e32 v216, v217
	s_nop 0
	v_add_f32_e32 v204, v204, v205
	v_add_f32_e32 v216, v216, v217
	v_mul_f32_e32 v212, 0x3a800000, v204
	v_mul_f32_e32 v224, 0x3a800000, v216
	v_pk_add_f32 v[0:1], v[0:1], v[212:213] op_sel_hi:[1,0] neg_lo:[0,1] neg_hi:[0,1]
	v_pk_add_f32 v[2:3], v[2:3], v[212:213] op_sel_hi:[1,0] neg_lo:[0,1] neg_hi:[0,1]
	v_pk_add_f32 v[4:5], v[4:5], v[212:213] op_sel_hi:[1,0] neg_lo:[0,1] neg_hi:[0,1]
	v_pk_add_f32 v[6:7], v[6:7], v[212:213] op_sel_hi:[1,0] neg_lo:[0,1] neg_hi:[0,1]
	v_pk_add_f32 v[8:9], v[8:9], v[212:213] op_sel_hi:[1,0] neg_lo:[0,1] neg_hi:[0,1]
	v_pk_add_f32 v[10:11], v[10:11], v[212:213] op_sel_hi:[1,0] neg_lo:[0,1] neg_hi:[0,1]
	v_pk_add_f32 v[12:13], v[12:13], v[212:213] op_sel_hi:[1,0] neg_lo:[0,1] neg_hi:[0,1]
	v_pk_add_f32 v[14:15], v[14:15], v[212:213] op_sel_hi:[1,0] neg_lo:[0,1] neg_hi:[0,1]
	v_pk_add_f32 v[16:17], v[16:17], v[224:225] op_sel_hi:[1,0] neg_lo:[0,1] neg_hi:[0,1]
	v_pk_add_f32 v[18:19], v[18:19], v[224:225] op_sel_hi:[1,0] neg_lo:[0,1] neg_hi:[0,1]
	v_pk_add_f32 v[20:21], v[20:21], v[224:225] op_sel_hi:[1,0] neg_lo:[0,1] neg_hi:[0,1]
	v_pk_add_f32 v[22:23], v[22:23], v[224:225] op_sel_hi:[1,0] neg_lo:[0,1] neg_hi:[0,1]
	v_pk_add_f32 v[24:25], v[24:25], v[224:225] op_sel_hi:[1,0] neg_lo:[0,1] neg_hi:[0,1]
	v_pk_add_f32 v[26:27], v[26:27], v[224:225] op_sel_hi:[1,0] neg_lo:[0,1] neg_hi:[0,1]
	v_pk_add_f32 v[28:29], v[28:29], v[224:225] op_sel_hi:[1,0] neg_lo:[0,1] neg_hi:[0,1]
	v_pk_add_f32 v[30:31], v[30:31], v[224:225] op_sel_hi:[1,0] neg_lo:[0,1] neg_hi:[0,1]
	v_pk_mul_f32 v[204:205], v[0:1], v[0:1]
	v_pk_mul_f32 v[206:207], v[2:3], v[2:3]
	v_pk_mul_f32 v[216:217], v[16:17], v[16:17]
	v_pk_mul_f32 v[218:219], v[18:19], v[18:19]
	v_pk_fma_f32 v[204:205], v[4:5], v[4:5], v[204:205]
	v_pk_fma_f32 v[206:207], v[6:7], v[6:7], v[206:207]
	v_pk_fma_f32 v[216:217], v[20:21], v[20:21], v[216:217]
	v_pk_fma_f32 v[218:219], v[22:23], v[22:23], v[218:219]
	v_pk_fma_f32 v[204:205], v[8:9], v[8:9], v[204:205]
	v_pk_fma_f32 v[206:207], v[10:11], v[10:11], v[206:207]
	v_pk_fma_f32 v[216:217], v[24:25], v[24:25], v[216:217]
	v_pk_fma_f32 v[218:219], v[26:27], v[26:27], v[218:219]
	v_pk_fma_f32 v[204:205], v[12:13], v[12:13], v[204:205]
	v_pk_fma_f32 v[206:207], v[14:15], v[14:15], v[206:207]
	v_pk_fma_f32 v[216:217], v[28:29], v[28:29], v[216:217]
	v_pk_fma_f32 v[218:219], v[30:31], v[30:31], v[218:219]
	v_pk_add_f32 v[204:205], v[204:205], v[206:207]
	v_pk_add_f32 v[216:217], v[216:217], v[218:219]
	v_add_f32_e32 v204, v204, v205
	v_add_f32_e32 v216, v216, v217
	s_nop 1
	v_add_f32_dpp v204, v204, v204 row_ror:1 row_mask:0xf bank_mask:0xf bound_ctrl:1
	v_add_f32_dpp v216, v216, v216 row_ror:1 row_mask:0xf bank_mask:0xf bound_ctrl:1
	s_nop 0
	v_add_f32_dpp v204, v204, v204 row_ror:2 row_mask:0xf bank_mask:0xf bound_ctrl:1
	v_add_f32_dpp v216, v216, v216 row_ror:2 row_mask:0xf bank_mask:0xf bound_ctrl:1
	s_nop 0
	v_add_f32_dpp v204, v204, v204 row_ror:4 row_mask:0xf bank_mask:0xf bound_ctrl:1
	v_add_f32_dpp v216, v216, v216 row_ror:4 row_mask:0xf bank_mask:0xf bound_ctrl:1
	s_nop 0
	v_add_f32_dpp v204, v204, v204 row_ror:8 row_mask:0xf bank_mask:0xf bound_ctrl:1
	v_add_f32_dpp v216, v216, v216 row_ror:8 row_mask:0xf bank_mask:0xf bound_ctrl:1
	s_nop 0
	v_mov_b32_e32 v205, v204
	v_mov_b32_e32 v217, v216
	s_nop 1
	v_permlane16_swap_b32_e32 v204, v205
	v_permlane16_swap_b32_e32 v216, v217
	s_nop 0
	v_add_f32_e32 v204, v204, v205
	v_add_f32_e32 v216, v216, v217
	v_mov_b32_e32 v205, v204
	v_mov_b32_e32 v217, v216
	s_nop 1
	v_permlane32_swap_b32_e32 v204, v205
	v_permlane32_swap_b32_e32 v216, v217
	s_nop 0
	v_add_f32_e32 v204, v204, v205
	v_add_f32_e32 v216, v216, v217
	v_mov_b32_e32 v205, 0x3727c5ac
	v_fmac_f32_e32 v205, 0x3a800000, v204
	v_mov_b32_e32 v217, 0x3727c5ac
	v_fmac_f32_e32 v217, 0x3a800000, v216
	v_mul_f32_e32 v206, 0x4b800000, v205
	s_mov_b32 s4, 0x800000
	v_cmp_gt_f32_e32 vcc, s4, v205
	s_nop 1
	v_cndmask_b32_e32 v205, v205, v206, vcc
	v_rsq_f32_e32 v205, v205
	s_nop 0
	v_mul_f32_e32 v206, 0x45800000, v205
	v_cndmask_b32_e32 v214, v205, v206, vcc
	v_mul_f32_e32 v218, 0x4b800000, v217
	s_mov_b32 s4, 0x800000
	v_cmp_gt_f32_e32 vcc, s4, v217
	s_nop 1
	v_cndmask_b32_e32 v217, v217, v218, vcc
	v_rsq_f32_e32 v217, v217
	s_nop 0
	v_mul_f32_e32 v218, 0x45800000, v217
	v_cndmask_b32_e32 v226, v217, v218, vcc
	v_pk_mul_f32 v[0:1], v[0:1], v[214:215] op_sel_hi:[1,0]
	v_pk_mul_f32 v[2:3], v[2:3], v[214:215] op_sel_hi:[1,0]
	v_pk_mul_f32 v[4:5], v[4:5], v[214:215] op_sel_hi:[1,0]
	v_pk_mul_f32 v[6:7], v[6:7], v[214:215] op_sel_hi:[1,0]
	v_pk_mul_f32 v[8:9], v[8:9], v[214:215] op_sel_hi:[1,0]
	v_pk_mul_f32 v[10:11], v[10:11], v[214:215] op_sel_hi:[1,0]
	v_pk_mul_f32 v[12:13], v[12:13], v[214:215] op_sel_hi:[1,0]
	v_pk_mul_f32 v[14:15], v[14:15], v[214:215] op_sel_hi:[1,0]
	v_pk_mul_f32 v[16:17], v[16:17], v[226:227] op_sel_hi:[1,0]
	v_pk_mul_f32 v[18:19], v[18:19], v[226:227] op_sel_hi:[1,0]
	v_pk_mul_f32 v[20:21], v[20:21], v[226:227] op_sel_hi:[1,0]
	v_pk_mul_f32 v[22:23], v[22:23], v[226:227] op_sel_hi:[1,0]
	v_pk_mul_f32 v[24:25], v[24:25], v[226:227] op_sel_hi:[1,0]
	v_pk_mul_f32 v[26:27], v[26:27], v[226:227] op_sel_hi:[1,0]
	v_pk_mul_f32 v[28:29], v[28:29], v[226:227] op_sel_hi:[1,0]
	v_pk_mul_f32 v[30:31], v[30:31], v[226:227] op_sel_hi:[1,0]
	v_pk_fma_f32 v[0:1], v[136:137], v[0:1], v[152:153]
	v_pk_fma_f32 v[2:3], v[138:139], v[2:3], v[154:155]
	v_pk_fma_f32 v[4:5], v[140:141], v[4:5], v[156:157]
	v_pk_fma_f32 v[6:7], v[142:143], v[6:7], v[158:159]
	v_pk_fma_f32 v[8:9], v[144:145], v[8:9], v[160:161]
	v_pk_fma_f32 v[10:11], v[146:147], v[10:11], v[162:163]
	v_pk_fma_f32 v[12:13], v[148:149], v[12:13], v[164:165]
	v_pk_fma_f32 v[14:15], v[150:151], v[14:15], v[166:167]
	v_pk_fma_f32 v[16:17], v[136:137], v[16:17], v[152:153]
	v_pk_fma_f32 v[18:19], v[138:139], v[18:19], v[154:155]
	v_pk_fma_f32 v[20:21], v[140:141], v[20:21], v[156:157]
	v_pk_fma_f32 v[22:23], v[142:143], v[22:23], v[158:159]
	v_pk_fma_f32 v[24:25], v[144:145], v[24:25], v[160:161]
	v_pk_fma_f32 v[26:27], v[146:147], v[26:27], v[162:163]
	v_pk_fma_f32 v[28:29], v[148:149], v[28:29], v[164:165]
	v_pk_fma_f32 v[30:31], v[150:151], v[30:31], v[166:167]
	v_mov_b32_e32 v228, v212
	v_mov_b32_e32 v229, v214
	v_mov_b32_e32 v168, v224
	v_mov_b32_e32 v169, v226
	v_add_f32_e32 v80, 1.0, v80
	v_add_f32_e32 v81, 1.0, v81
	v_add_f32_e32 v82, 1.0, v82
	v_add_f32_e32 v83, 1.0, v83
	v_add_f32_e32 v84, 1.0, v84
	v_add_f32_e32 v85, 1.0, v85
	v_add_f32_e32 v86, 1.0, v86
	v_add_f32_e32 v87, 1.0, v87
	v_add_f32_e32 v88, 1.0, v88
	v_add_f32_e32 v89, 1.0, v89
	v_add_f32_e32 v90, 1.0, v90
	v_add_f32_e32 v91, 1.0, v91
	v_add_f32_e32 v92, 1.0, v92
	v_add_f32_e32 v93, 1.0, v93
	v_add_f32_e32 v94, 1.0, v94
	v_add_f32_e32 v95, 1.0, v95
	v_pk_fma_f32 v[204:205], v[80:81], v[0:1], v[64:65]
	v_pk_fma_f32 v[206:207], v[82:83], v[2:3], v[66:67]
	v_pk_fma_f32 v[208:209], v[84:85], v[4:5], v[68:69]
	v_pk_fma_f32 v[210:211], v[86:87], v[6:7], v[70:71]
	v_pk_fma_f32 v[212:213], v[88:89], v[8:9], v[72:73]
	v_pk_fma_f32 v[214:215], v[90:91], v[10:11], v[74:75]
	v_pk_fma_f32 v[216:217], v[92:93], v[12:13], v[76:77]
	v_pk_fma_f32 v[218:219], v[94:95], v[14:15], v[78:79]
	v_cvt_pk_bf16_f32 v220, v204, v205
	v_cvt_pk_bf16_f32 v221, v206, v207
	v_cvt_pk_bf16_f32 v222, v208, v209
	v_cvt_pk_bf16_f32 v223, v210, v211
	v_cvt_pk_bf16_f32 v224, v212, v213
	v_cvt_pk_bf16_f32 v225, v214, v215
	v_cvt_pk_bf16_f32 v226, v216, v217
	v_cvt_pk_bf16_f32 v227, v218, v219
	s_mul_i32 s4, s6, 0x880
	s_add_u32 s4, s4, 0xf266000
	s_add_u32 s4, s4, s8
	s_addc_u32 s5, s9, 0
	global_store_dwordx2 v233, v[220:221], s[4:5]
	global_store_dwordx2 v233, v[222:223], s[4:5] offset:512
	global_store_dwordx2 v233, v[224:225], s[4:5] offset:1024
	global_store_dwordx2 v233, v[226:227], s[4:5] offset:1536
	s_mov_b64 s[12:13], exec
	s_mov_b64 exec, 1
	global_store_dwordx2 v129, v[228:229], s[4:5] offset:2048
	s_mov_b64 exec, s[12:13]
	v_pk_fma_f32 v[204:205], v[80:81], v[16:17], v[64:65]
	v_pk_fma_f32 v[206:207], v[82:83], v[18:19], v[66:67]
	v_pk_fma_f32 v[208:209], v[84:85], v[20:21], v[68:69]
	v_pk_fma_f32 v[210:211], v[86:87], v[22:23], v[70:71]
	v_pk_fma_f32 v[212:213], v[88:89], v[24:25], v[72:73]
	v_pk_fma_f32 v[214:215], v[90:91], v[26:27], v[74:75]
	v_pk_fma_f32 v[216:217], v[92:93], v[28:29], v[76:77]
	v_pk_fma_f32 v[218:219], v[94:95], v[30:31], v[78:79]
	v_cvt_pk_bf16_f32 v220, v204, v205
	v_cvt_pk_bf16_f32 v221, v206, v207
	v_cvt_pk_bf16_f32 v222, v208, v209
	v_cvt_pk_bf16_f32 v223, v210, v211
	v_cvt_pk_bf16_f32 v224, v212, v213
	v_cvt_pk_bf16_f32 v225, v214, v215
	v_cvt_pk_bf16_f32 v226, v216, v217
	v_cvt_pk_bf16_f32 v227, v218, v219
	s_mul_i32 s4, s6, 0x880
	s_add_u32 s4, s4, 0xf6a6000
	s_add_u32 s4, s4, s8
	s_addc_u32 s5, s9, 0
	global_store_dwordx2 v233, v[220:221], s[4:5]
	global_store_dwordx2 v233, v[222:223], s[4:5] offset:512
	global_store_dwordx2 v233, v[224:225], s[4:5] offset:1024
	global_store_dwordx2 v233, v[226:227], s[4:5] offset:1536
	s_mov_b64 s[12:13], exec
	s_mov_b64 exec, 1
	global_store_dwordx2 v129, v[168:169], s[4:5] offset:2048
	s_mov_b64 exec, s[12:13]
	s_waitcnt vmcnt(0)
	s_branch .LBB0_1420
.Llnc_orig:
	v_readlane_b32 s50, v235, 34
	v_readlane_b32 s4, v235, 44
	v_readlane_b32 s51, v235, 35
	s_add_u32 s34, s50, 0xb166000
	v_readlane_b32 s5, v235, 45
	s_mul_i32 s40, s4, 3
	s_addc_u32 s35, s51, 0
	s_ashr_i32 s41, s40, 31
	v_readlane_b32 s4, v237, 19
	s_lshl_b64 s[44:45], s[40:41], 12
	v_readlane_b32 s10, v237, 25
	v_readlane_b32 s11, v237, 26
	s_add_u32 s46, s10, s44
	v_lshlrev_b32_e32 v0, 2, v34
	v_readlane_b32 s12, v237, 27
	s_addc_u32 s47, s11, s45
	v_and_b32_e32 v136, 0xfc, v0
	v_readlane_b32 s13, v237, 28
	s_add_u32 s44, s12, s44
	v_lshlrev_b32_e32 v128, 2, v136
	s_addc_u32 s45, s13, s45
	global_load_dwordx4 v[0:3], v128, s[46:47]
	global_load_dwordx4 v[4:7], v128, s[46:47] offset:1024
	global_load_dwordx4 v[8:11], v128, s[44:45]
	global_load_dwordx4 v[12:15], v128, s[44:45] offset:1024
	global_load_dwordx4 v[16:19], v128, s[46:47] offset:2048
	global_load_dwordx4 v[20:23], v128, s[46:47] offset:3072
	global_load_dwordx4 v[24:27], v128, s[44:45] offset:2048
	global_load_dwordx4 v[28:31], v128, s[44:45] offset:3072
	v_readlane_b32 s5, v237, 20
	v_lshl_add_u64 v[36:37], s[50:51], 0, v[128:129]
	s_mov_b64 s[4:5], 0x14ae6000
	v_lshl_add_u64 v[138:139], s[34:35], 0, v[128:129]
	v_lshl_add_u64 v[140:141], v[36:37], 0, s[4:5]
	v_lshlrev_b32_e32 v128, 1, v136
	v_readlane_b32 s4, v235, 18
	v_and_b32_e32 v36, 63, v34
	v_lshl_add_u64 v[142:143], s[90:91], 0, v[128:129]
	v_add_u32_e32 v144, s4, v33
	v_ashrrev_i32_e32 v33, 31, v32
	v_lshlrev_b32_e32 v128, 3, v36
	v_mad_i64_i32 v[34:35], s[46:47], v32, s3, v[128:129]
	v_lshlrev_b64 v[32:33], 12, v[32:33]
	v_lshl_or_b32 v32, v36, 4, v32
	s_add_u32 s44, s50, 0xb0fb000
	v_lshl_add_u64 v[32:33], s[34:35], 0, v[32:33]
	s_mov_b64 s[4:5], 0x800
	s_addc_u32 s45, s51, 0
	v_lshl_add_u64 v[146:147], s[90:91], 0, v[34:35]
	v_lshl_add_u64 v[148:149], v[32:33], 0, s[4:5]
	s_mov_b64 s[46:47], 0
	v_readlane_b32 s6, v237, 21
	v_readlane_b32 s7, v237, 22
	v_readlane_b32 s8, v237, 23
	v_readlane_b32 s9, v237, 24
	v_readlane_b32 s14, v237, 29
	v_readlane_b32 s15, v237, 30
	v_readlane_b32 s16, v237, 31
	v_readlane_b32 s17, v237, 32
	v_readlane_b32 s18, v237, 33
	v_readlane_b32 s19, v237, 34
	s_branch .LBB0_1204

.Lfo_entry:
	v_readlane_b32 s4, v235, 34
	v_readlane_b32 s5, v235, 35
	v_readlane_b32 s55, v235, 44
	s_lshl_b32 s53, s55, 1
	s_cmp_lg_u32 s2, 1
	s_cselect_b32 s54, 1, 0
	s_add_u32 s53, s53, s54
	s_mul_i32 s53, s53, 0x5a0000
	s_add_u32 s53, s53, 0x5d88000
	s_add_u32 s44, s4, s53
	s_addc_u32 s45, s5, 0
	s_mul_i32 s54, s54, 0x6000
	s_mul_i32 s53, s55, 0x1b000
	s_add_u32 s53, s53, 0xb0fa000
	s_add_u32 s53, s53, s54
	s_add_u32 s46, s4, s53
	s_addc_u32 s47, s5, 0
	s_mul_i32 s40, s55, 3
	s_cmp_lg_u32 s2, 1
	s_cbranch_scc1 .Lfo_q10
	s_sub_u32 s40, s40, 1
	s_cmp_eq_u32 s55, 0
	s_cselect_b32 s40, 0x100, s40
	s_branch .Lfo_qd
.Lfo_q10:
	s_add_u32 s40, s40, 1
.Lfo_qd:
	v_readlane_b32 s41, v235, 33
	s_cmp_lg_u32 s41, 0x200
	s_cselect_b32 s41, 0x100, 0
	s_or_b32 s40, s40, s41
	v_and_b32_e32 v225, 63, v170
	v_lshrrev_b32_e32 v226, 6, v170
	v_lshrrev_b32_e32 v227, 1, v226
	v_and_b32_e32 v228, 1, v226
	v_and_b32_e32 v229, 15, v225
	v_lshrrev_b32_e32 v230, 4, v225
	v_lshlrev_b32_e32 v231, 10, v226
	v_lshrrev_b32_e32 v232, 3, v170
	v_readfirstlane_b32 s52, v231
	v_and_b32_e32 v233, 7, v170
	v_bfe_u32 v224, v232, 1, 3
	v_xor_b32_e32 v233, v233, v224
	v_lshlrev_b32_e32 v233, 4, v233
	s_movk_i32 s4, 0x1680
	v_mad_u32_u24 v224, v232, s4, v233
	v_and_b32_e32 v233, 15, v232
	v_lshlrev_b32_e32 v233, 1, v233
	v_lshrrev_b32_e32 v168, 4, v232
	v_add_u32_e32 v233, v233, v168
	v_and_b32_e32 v168, 7, v170
	v_bfe_u32 v169, v232, 1, 3
	v_xor_b32_e32 v168, v168, v169
	v_lshlrev_b32_e32 v168, 4, v168
	v_mad_u32_u24 v168, v233, s4, v168
	v_bfe_u32 v233, v229, 1, 3
	v_xor_b32_e32 v231, v230, v233
	v_or_b32_e32 v232, 4, v230
	v_xor_b32_e32 v232, v232, v233
	v_lshlrev_b32_e32 v231, 4, v231
	v_lshlrev_b32_e32 v232, 4, v232
	s_movk_i32 s4, 96
	v_mad_u32_u24 v233, v227, s4, v229
	v_lshlrev_b32_e32 v233, 7, v233
	v_add_u32_e32 v220, v233, v231
	v_add_u32_e32 v221, v233, v232
	v_lshl_add_u32 v233, v228, 6, v229
	v_lshlrev_b32_e32 v233, 7, v233
	v_add_u32_e32 v233, 0x8000, v233
	v_add_u32_e32 v222, v233, v231
	v_add_u32_e32 v223, v233, v232
	v_lshlrev_b32_e32 v231, 2, v230
	v_mad_u32_u24 v231, v227, s4, v231
	v_lshlrev_b32_e32 v232, 5, v228
	v_add_u32_e32 v232, v232, v229
	v_lshlrev_b32_e32 v232, 1, v232
	v_lshlrev_b32_e32 v169, 2, v232
	v_lshl_add_u32 v225, v231, 12, v169
	v_readlane_b32 s54, v237, 0
	s_cmp_ge_u32 s54, 0x200
	s_cbranch_scc1 .Lfo_done
	s_add_u32 s57, s52, 0x8000
	s_and_b32 s55, s54, 7
	s_lshl_b32 s55, s55, 3
	s_lshr_b32 s62, s54, 6
	s_add_u32 s55, s55, s62
	s_bfe_u32 s36, s54, 0x30003
	s_lshl_b32 s62, s55, 8
	s_lshl_b32 s63, s36, 4
	s_or_b32 s62, s62, s63
	v_readlane_b32 s4, v235, 34
	v_readlane_b32 s5, v235, 35
	s_mul_i32 s34, s55, 0x10e000
	s_add_u32 s34, s34, 0xfae6000
	s_add_u32 s34, s34, s4
	s_addc_u32 s35, s5, 0
	s_mul_i32 s36, s36, 0xb4000
	s_add_u32 s36, s36, s44
	s_addc_u32 s37, s45, 0
	s_add_u32 m0, s52, 0x0
	s_add_u32 s4, s34, 0x0
	s_addc_u32 s5, s35, 0
	global_load_lds_dwordx4 v224, s[4:5]
	s_add_u32 m0, s52, 0x1000
	s_add_u32 s4, s34, 0x2d000
	s_addc_u32 s5, s35, 0
	global_load_lds_dwordx4 v224, s[4:5]
	s_add_u32 m0, s52, 0x2000
	s_add_u32 s4, s34, 0x5a000
	s_addc_u32 s5, s35, 0
	global_load_lds_dwordx4 v224, s[4:5]
	s_add_u32 m0, s52, 0x3000
	s_add_u32 s4, s34, 0x87000
	s_addc_u32 s5, s35, 0
	global_load_lds_dwordx4 v224, s[4:5]
	s_add_u32 m0, s52, 0x4000
	s_add_u32 s4, s34, 0xb4000
	s_addc_u32 s5, s35, 0
	global_load_lds_dwordx4 v224, s[4:5]
	s_add_u32 m0, s52, 0x5000
	s_add_u32 s4, s34, 0xe1000
	s_addc_u32 s5, s35, 0
	global_load_lds_dwordx4 v224, s[4:5]
	s_add_u32 m0, s57, 0x0
	s_add_u32 s4, s36, 0x0
	s_addc_u32 s5, s37, 0
	global_load_lds_dwordx4 v168, s[4:5]
	s_add_u32 m0, s57, 0x1000
	s_add_u32 s4, s36, 0x2d000
	s_addc_u32 s5, s37, 0
	global_load_lds_dwordx4 v168, s[4:5]
	s_add_u32 m0, s57, 0x2000
	s_add_u32 s4, s36, 0x5a000
	s_addc_u32 s5, s37, 0
	global_load_lds_dwordx4 v168, s[4:5]
	s_add_u32 m0, s57, 0x3000
	s_add_u32 s4, s36, 0x87000
	s_addc_u32 s5, s37, 0
	global_load_lds_dwordx4 v168, s[4:5]
	s_add_u32 s36, s36, 0x80
	s_addc_u32 s37, s37, 0
	s_add_u32 s34, s34, 0x80
	s_addc_u32 s35, s35, 0

.Lfo_gbdone:
.Lfo_k:
	s_waitcnt vmcnt(0)
	s_barrier
	s_xor_b32 s57, s57, 0x4000
	s_cmp_eq_u32 s53, 43
	s_cbranch_scc1 .Lfo_nob
	s_add_u32 m0, s57, 0x0
	s_add_u32 s4, s36, 0x0
	s_addc_u32 s5, s37, 0
	global_load_lds_dwordx4 v168, s[4:5]
	s_add_u32 m0, s57, 0x1000
	s_add_u32 s4, s36, 0x2d000
	s_addc_u32 s5, s37, 0
	global_load_lds_dwordx4 v168, s[4:5]
	s_add_u32 m0, s57, 0x2000
	s_add_u32 s4, s36, 0x5a000
	s_addc_u32 s5, s37, 0
	global_load_lds_dwordx4 v168, s[4:5]
	s_add_u32 m0, s57, 0x3000
	s_add_u32 s4, s36, 0x87000
	s_addc_u32 s5, s37, 0
	global_load_lds_dwordx4 v168, s[4:5]
	s_add_u32 s36, s36, 0x80
	s_addc_u32 s37, s37, 0

.Lfo_nopf:
	s_setprio 1
	v_mfma_f32_16x16x32_bf16 v[0:3], v[136:139], a[0:3], v[0:3]
	v_mfma_f32_16x16x32_bf16 v[4:7], v[136:139], a[4:7], v[4:7]
	v_mfma_f32_16x16x32_bf16 v[8:11], v[136:139], a[8:11], v[8:11]
	v_mfma_f32_16x16x32_bf16 v[12:15], v[136:139], a[12:15], v[12:15]
	v_mfma_f32_16x16x32_bf16 v[16:19], v[140:143], a[0:3], v[16:19]
	v_mfma_f32_16x16x32_bf16 v[20:23], v[140:143], a[4:7], v[20:23]
	v_mfma_f32_16x16x32_bf16 v[24:27], v[140:143], a[8:11], v[24:27]
	v_mfma_f32_16x16x32_bf16 v[28:31], v[140:143], a[12:15], v[28:31]
	v_mfma_f32_16x16x32_bf16 v[32:35], v[144:147], a[0:3], v[32:35]
	v_mfma_f32_16x16x32_bf16 v[36:39], v[144:147], a[4:7], v[36:39]
	v_mfma_f32_16x16x32_bf16 v[40:43], v[144:147], a[8:11], v[40:43]
	v_mfma_f32_16x16x32_bf16 v[44:47], v[144:147], a[12:15], v[44:47]
	v_mfma_f32_16x16x32_bf16 v[48:51], v[148:151], a[0:3], v[48:51]
	v_mfma_f32_16x16x32_bf16 v[52:55], v[148:151], a[4:7], v[52:55]
	v_mfma_f32_16x16x32_bf16 v[56:59], v[148:151], a[8:11], v[56:59]
	v_mfma_f32_16x16x32_bf16 v[60:63], v[148:151], a[12:15], v[60:63]
	v_mfma_f32_16x16x32_bf16 v[64:67], v[152:155], a[0:3], v[64:67]
	v_mfma_f32_16x16x32_bf16 v[68:71], v[152:155], a[4:7], v[68:71]
	v_mfma_f32_16x16x32_bf16 v[72:75], v[152:155], a[8:11], v[72:75]
	v_mfma_f32_16x16x32_bf16 v[76:79], v[152:155], a[12:15], v[76:79]
	v_mfma_f32_16x16x32_bf16 v[80:83], v[156:159], a[0:3], v[80:83]
	v_mfma_f32_16x16x32_bf16 v[84:87], v[156:159], a[4:7], v[84:87]
	v_mfma_f32_16x16x32_bf16 v[88:91], v[156:159], a[8:11], v[88:91]
	v_mfma_f32_16x16x32_bf16 v[92:95], v[156:159], a[12:15], v[92:95]
	s_setprio 0
	s_mov_b32 s55, 0x3fd744fd
	v_mul_f32_e32 v226, 0.5, v226
	v_mul_f32_e32 v227, 0.5, v227
	v_mul_f32_e32 v228, 0.5, v228
	v_mul_f32_e32 v229, 0.5, v229
	v_mul_f32_e32 v230, 0.5, v230
	v_mul_f32_e32 v231, 0.5, v231
	v_mul_f32_e32 v232, 0.5, v232
	v_mul_f32_e32 v233, 0.5, v233
	v_readlane_b32 s4, v235, 34
	v_readlane_b32 s5, v235, 35
	s_lshr_b32 s42, s56, 8
	s_mul_i32 s42, s42, 0x66000
	s_add_u32 s42, s42, 0xe166000
	s_add_u32 s42, s42, s4
	s_addc_u32 s43, s5, 0
	v_lshrrev_b32_e32 v131, 12, v225
	s_movk_i32 s4, 0x880
	v_mul_u32_u24_e32 v131, s4, v131
	s_add_u32 s4, s50, 0x0
	s_addc_u32 s5, s51, 0
	global_load_dwordx2 v[104:105], v225, s[4:5]
	global_load_dwordx2 v[106:107], v225, s[4:5] offset:128
	s_add_u32 s4, s50, 0x1000
	s_addc_u32 s5, s51, 0
	global_load_dwordx2 v[108:109], v225, s[4:5]
	global_load_dwordx2 v[110:111], v225, s[4:5] offset:128
	s_add_u32 s4, s50, 0x2000
	s_addc_u32 s5, s51, 0
	global_load_dwordx2 v[112:113], v225, s[4:5]
	global_load_dwordx2 v[114:115], v225, s[4:5] offset:128
	s_add_u32 s4, s50, 0x3000
	s_addc_u32 s5, s51, 0
	global_load_dwordx2 v[116:117], v225, s[4:5]
	global_load_dwordx2 v[118:119], v225, s[4:5] offset:128
	s_add_u32 s4, s42, 0x0
	s_addc_u32 s5, s43, 0
	global_load_dwordx2 v[120:121], v131, s[4:5] offset:2048
	s_add_u32 s4, s42, 0x880
	s_addc_u32 s5, s43, 0
	global_load_dwordx2 v[122:123], v131, s[4:5] offset:2048
	s_add_u32 s4, s42, 0x1100
	s_addc_u32 s5, s43, 0
	global_load_dwordx2 v[124:125], v131, s[4:5] offset:2048
	s_add_u32 s4, s42, 0x1980
	s_addc_u32 s5, s43, 0
	global_load_dwordx2 v[126:127], v131, s[4:5] offset:2048
	s_add_u32 s4, s50, 0x10000
	s_addc_u32 s5, s51, 0
	global_load_dwordx2 v[136:137], v225, s[4:5]
	global_load_dwordx2 v[138:139], v225, s[4:5] offset:128
	s_add_u32 s4, s50, 0x11000
	s_addc_u32 s5, s51, 0
	global_load_dwordx2 v[140:141], v225, s[4:5]
	global_load_dwordx2 v[142:143], v225, s[4:5] offset:128
	s_add_u32 s4, s50, 0x12000
	s_addc_u32 s5, s51, 0
	global_load_dwordx2 v[144:145], v225, s[4:5]
	global_load_dwordx2 v[146:147], v225, s[4:5] offset:128
	s_add_u32 s4, s50, 0x13000
	s_addc_u32 s5, s51, 0
	global_load_dwordx2 v[148:149], v225, s[4:5]
	global_load_dwordx2 v[150:151], v225, s[4:5] offset:128
	s_add_u32 s4, s42, 0x8800
	s_addc_u32 s5, s43, 0
	global_load_dwordx2 v[152:153], v131, s[4:5] offset:2048
	s_add_u32 s4, s42, 0x9080
	s_addc_u32 s5, s43, 0
	global_load_dwordx2 v[154:155], v131, s[4:5] offset:2048
	s_add_u32 s4, s42, 0x9900
	s_addc_u32 s5, s43, 0
	global_load_dwordx2 v[156:157], v131, s[4:5] offset:2048
	s_add_u32 s4, s42, 0xa180
	s_addc_u32 s5, s43, 0
	global_load_dwordx2 v[158:159], v131, s[4:5] offset:2048
	s_add_u32 s4, s50, 0x20000
	s_addc_u32 s5, s51, 0
	global_load_dwordx2 v[204:205], v225, s[4:5]
	global_load_dwordx2 v[206:207], v225, s[4:5] offset:128
	s_add_u32 s4, s50, 0x21000
	s_addc_u32 s5, s51, 0
	global_load_dwordx2 v[208:209], v225, s[4:5]
	global_load_dwordx2 v[210:211], v225, s[4:5] offset:128
	s_add_u32 s4, s50, 0x22000
	s_addc_u32 s5, s51, 0
	global_load_dwordx2 v[212:213], v225, s[4:5]
	global_load_dwordx2 v[214:215], v225, s[4:5] offset:128
	s_add_u32 s4, s50, 0x23000
	s_addc_u32 s5, s51, 0
	global_load_dwordx2 v[216:217], v225, s[4:5]
	global_load_dwordx2 v[218:219], v225, s[4:5] offset:128
	s_add_u32 s4, s42, 0x11000
	s_addc_u32 s5, s43, 0
	global_load_dwordx2 v[160:161], v131, s[4:5] offset:2048
	s_add_u32 s4, s42, 0x11880
	s_addc_u32 s5, s43, 0
	global_load_dwordx2 v[162:163], v131, s[4:5] offset:2048
	s_add_u32 s4, s42, 0x12100
	s_addc_u32 s5, s43, 0
	global_load_dwordx2 v[164:165], v131, s[4:5] offset:2048
	s_add_u32 s4, s42, 0x12980
	s_addc_u32 s5, s43, 0
	global_load_dwordx2 v[166:167], v131, s[4:5] offset:2048
	s_nop 7
	s_nop 7
	s_waitcnt vmcnt(24)
	s_bitcmp1_b32 s40, 8
	s_cbranch_scc0 .Lfo_st0
	v_mov_b32_e32 v120, 0
	v_mov_b32_e32 v121, 1.0
	v_mov_b32_e32 v122, 0
	v_mov_b32_e32 v123, 1.0
	v_mov_b32_e32 v124, 0
	v_mov_b32_e32 v125, 1.0
	v_mov_b32_e32 v126, 0
	v_mov_b32_e32 v127, 1.0
